# p3a: S2 loads hoisted, S3 record copies pipelined, S4 triangular solve rewritten with DPP row_newbcast (bit-identical); EpiResid loads batched
# speedup vs baseline: 1.0174x; 1.0144x over previous
.LBB0_653:
	v_readlane_b32 s1, v249, 49
	v_readlane_b32 s0, v248, 20
	v_readlane_b32 s4, v248, 2
	v_readlane_b32 s5, v248, 17
	s_lshl_b32 s0, s0, 3
	s_add_i32 s0, s0, s1
	s_add_i32 s72, s72, s0
	s_lshr_b32 s1, s72, 4
	s_mov_b32 s3, 0x24300000
	s_cmp_eq_u32 s1, 2
	s_cselect_b32 s2, s3, 0x26000000
	s_cmp_lg_u32 s1, 1
	s_cselect_b32 s1, s2, 0x1d000000
	s_cmp_gt_u32 s72, 15
	s_cselect_b32 s1, s1, 0x1ed00000
	s_add_u32 s1, s70, s1
	s_addc_u32 s2, s71, 0
	s_lshl_b32 s0, s0, 6
	s_and_b32 s0, s0, 0x3c0
	s_add_i32 s0, s0, s85
	s_mul_hi_i32 s3, s0, 0x7400
	s_mulk_i32 s0, 0x7400
	s_add_u32 s6, s1, s0
	s_addc_u32 s7, s2, s3
	v_and_b32_e32 v2, 15, v1
	v_lshl_add_u32 v138, v2, 2, s4
	ds_read_b32 v148, v138 offset:8432
	v_cmp_eq_u32_e32 vcc, 63, v1
	s_nop 1
	v_cndmask_b32_e64 v134, 0, 1.0, vcc
	v_mov_b32_e32 v135, v18
	v_mov_b32_e32 v136, v18
	v_mov_b32_e32 v137, v18
	ds_read_b32 v144, v138 offset:8416
	s_waitcnt lgkmcnt(2)
	v_cmp_eq_u32_e32 vcc, 62, v1
	s_nop 1
	v_cndmask_b32_e64 v130, 0, 1.0, vcc
	v_mov_b32_e32 v131, v18
	v_mov_b32_e32 v132, v18
	v_mov_b32_e32 v133, v18
	v_add_f32_e32 v2, v134, v135
	v_add_f32_e32 v3, v136, v137
	v_add_f32_e32 v129, v2, v3
	ds_read_b32 v140, v138 offset:8400
	s_waitcnt lgkmcnt(2)
	v_cmp_eq_u32_e32 vcc, 61, v1
	v_fmac_f32_dpp v133, -v148, v129 row_newbcast:3 row_mask:0xf bank_mask:0xf
	s_nop 0
	v_cndmask_b32_e64 v134, 0, 1.0, vcc
	v_mov_b32_e32 v135, v18
	v_mov_b32_e32 v136, v18
	v_mov_b32_e32 v137, v18
	v_add_f32_e32 v2, v130, v131
	v_add_f32_e32 v3, v132, v133
	v_add_f32_e32 v128, v2, v3
	ds_read_b32 v148, v138 offset:8384
	s_waitcnt lgkmcnt(2)
	v_cmp_eq_u32_e32 vcc, 60, v1
	v_fmac_f32_dpp v137, -v144, v129 row_newbcast:3 row_mask:0xf bank_mask:0xf
	v_fmac_f32_dpp v136, -v144, v128 row_newbcast:2 row_mask:0xf bank_mask:0xf
	v_cndmask_b32_e64 v130, 0, 1.0, vcc
	v_mov_b32_e32 v131, v18
	v_mov_b32_e32 v132, v18
	v_mov_b32_e32 v133, v18
	v_add_f32_e32 v2, v134, v135
	v_add_f32_e32 v3, v136, v137
	v_add_f32_e32 v127, v2, v3
	ds_read_b32 v144, v138 offset:8352
	s_waitcnt lgkmcnt(2)
	v_cmp_eq_u32_e32 vcc, 59, v1
	v_fmac_f32_dpp v132, -v140, v128 row_newbcast:2 row_mask:0xf bank_mask:0xf
	v_fmac_f32_dpp v133, -v140, v129 row_newbcast:3 row_mask:0xf bank_mask:0xf
	v_fmac_f32_dpp v131, -v140, v127 row_newbcast:1 row_mask:0xf bank_mask:0xf
	v_cndmask_b32_e64 v134, 0, 1.0, vcc
	v_mov_b32_e32 v135, v18
	v_mov_b32_e32 v136, v18
	v_mov_b32_e32 v137, v18
	v_add_f32_e32 v2, v130, v131
	v_add_f32_e32 v3, v132, v133
	v_add_f32_e32 v126, v2, v3
	ds_read_b32 v140, v138 offset:8320
	s_waitcnt lgkmcnt(2)
	v_cmp_eq_u32_e32 vcc, 58, v1
	v_fmac_f32_dpp v135, -v148, v127 row_newbcast:1 row_mask:0xf bank_mask:0xf
	v_fmac_f32_dpp v136, -v148, v128 row_newbcast:2 row_mask:0xf bank_mask:0xf
	v_fmac_f32_dpp v137, -v148, v129 row_newbcast:3 row_mask:0xf bank_mask:0xf
	v_fmac_f32_dpp v134, -v148, v126 row_newbcast:0 row_mask:0xf bank_mask:0xf
	v_cndmask_b32_e64 v130, 0, 1.0, vcc
	v_mov_b32_e32 v131, v18
	v_mov_b32_e32 v132, v18
	v_mov_b32_e32 v133, v18
	v_add_f32_e32 v2, v134, v135
	v_add_f32_e32 v3, v136, v137
	v_add_f32_e32 v125, v2, v3
	ds_read_b32 v148, v138 offset:8288
	s_waitcnt lgkmcnt(2)
	v_cmp_eq_u32_e32 vcc, 57, v1
	v_fmac_f32_dpp v130, -v144, v126 row_newbcast:4 row_mask:0xf bank_mask:0xf
	v_fmac_f32_dpp v131, -v144, v127 row_newbcast:5 row_mask:0xf bank_mask:0xf
	v_fmac_f32_dpp v132, -v144, v128 row_newbcast:6 row_mask:0xf bank_mask:0xf
	v_fmac_f32_dpp v133, -v144, v125 row_newbcast:3 row_mask:0xf bank_mask:0xf
	s_nop 1
	v_fmac_f32_dpp v133, -v144, v129 row_newbcast:7 row_mask:0xf bank_mask:0xf
	v_cndmask_b32_e64 v134, 0, 1.0, vcc
	v_mov_b32_e32 v135, v18
	v_mov_b32_e32 v136, v18
	v_mov_b32_e32 v137, v18
	v_add_f32_e32 v2, v130, v131
	v_add_f32_e32 v3, v132, v133
	v_add_f32_e32 v124, v2, v3
	ds_read_b32 v144, v138 offset:8256
	s_waitcnt lgkmcnt(2)
	v_cmp_eq_u32_e32 vcc, 56, v1
	v_fmac_f32_dpp v137, -v140, v125 row_newbcast:3 row_mask:0xf bank_mask:0xf
	v_fmac_f32_dpp v134, -v140, v126 row_newbcast:4 row_mask:0xf bank_mask:0xf
	v_fmac_f32_dpp v135, -v140, v127 row_newbcast:5 row_mask:0xf bank_mask:0xf
	v_fmac_f32_dpp v136, -v140, v124 row_newbcast:2 row_mask:0xf bank_mask:0xf
	v_fmac_f32_dpp v137, -v140, v129 row_newbcast:7 row_mask:0xf bank_mask:0xf
	s_nop 0
	v_fmac_f32_dpp v136, -v140, v128 row_newbcast:6 row_mask:0xf bank_mask:0xf
	v_cndmask_b32_e64 v130, 0, 1.0, vcc
	v_mov_b32_e32 v131, v18
	v_mov_b32_e32 v132, v18
	v_mov_b32_e32 v133, v18
	v_add_f32_e32 v2, v134, v135
	v_add_f32_e32 v3, v136, v137
	v_add_f32_e32 v123, v2, v3
	ds_read_b32 v140, v138 offset:8208
	s_waitcnt lgkmcnt(2)
	v_cmp_eq_u32_e32 vcc, 55, v1
	v_fmac_f32_dpp v132, -v148, v124 row_newbcast:2 row_mask:0xf bank_mask:0xf
	v_fmac_f32_dpp v133, -v148, v125 row_newbcast:3 row_mask:0xf bank_mask:0xf
	v_fmac_f32_dpp v130, -v148, v126 row_newbcast:4 row_mask:0xf bank_mask:0xf
	v_fmac_f32_dpp v131, -v148, v123 row_newbcast:1 row_mask:0xf bank_mask:0xf
	v_fmac_f32_dpp v132, -v148, v128 row_newbcast:6 row_mask:0xf bank_mask:0xf
	v_fmac_f32_dpp v133, -v148, v129 row_newbcast:7 row_mask:0xf bank_mask:0xf
	v_fmac_f32_dpp v131, -v148, v127 row_newbcast:5 row_mask:0xf bank_mask:0xf
	v_cndmask_b32_e64 v134, 0, 1.0, vcc
	v_mov_b32_e32 v135, v18
	v_mov_b32_e32 v136, v18
	v_mov_b32_e32 v137, v18
	v_add_f32_e32 v2, v130, v131
	v_add_f32_e32 v3, v132, v133
	v_add_f32_e32 v122, v2, v3
	ds_read_b32 v148, v138 offset:8160
	s_waitcnt lgkmcnt(2)
	v_cmp_eq_u32_e32 vcc, 54, v1
	v_fmac_f32_dpp v135, -v144, v123 row_newbcast:1 row_mask:0xf bank_mask:0xf
	v_fmac_f32_dpp v136, -v144, v124 row_newbcast:2 row_mask:0xf bank_mask:0xf
	v_fmac_f32_dpp v137, -v144, v125 row_newbcast:3 row_mask:0xf bank_mask:0xf
	v_fmac_f32_dpp v134, -v144, v122 row_newbcast:0 row_mask:0xf bank_mask:0xf
	v_fmac_f32_dpp v135, -v144, v127 row_newbcast:5 row_mask:0xf bank_mask:0xf
	v_fmac_f32_dpp v136, -v144, v128 row_newbcast:6 row_mask:0xf bank_mask:0xf
	v_fmac_f32_dpp v137, -v144, v129 row_newbcast:7 row_mask:0xf bank_mask:0xf
	v_fmac_f32_dpp v134, -v144, v126 row_newbcast:4 row_mask:0xf bank_mask:0xf
	v_cndmask_b32_e64 v130, 0, 1.0, vcc
	v_mov_b32_e32 v131, v18
	v_mov_b32_e32 v132, v18
	v_mov_b32_e32 v133, v18
	v_add_f32_e32 v2, v134, v135
	v_add_f32_e32 v3, v136, v137
	v_add_f32_e32 v121, v2, v3
	ds_read_b32 v144, v138 offset:8112
	s_waitcnt lgkmcnt(2)
	v_cmp_eq_u32_e32 vcc, 53, v1
	v_fmac_f32_dpp v130, -v140, v122 row_newbcast:4 row_mask:0xf bank_mask:0xf
	v_fmac_f32_dpp v131, -v140, v123 row_newbcast:5 row_mask:0xf bank_mask:0xf
	v_fmac_f32_dpp v132, -v140, v124 row_newbcast:6 row_mask:0xf bank_mask:0xf
	v_fmac_f32_dpp v133, -v140, v121 row_newbcast:3 row_mask:0xf bank_mask:0xf
	v_fmac_f32_dpp v130, -v140, v126 row_newbcast:8 row_mask:0xf bank_mask:0xf
	v_fmac_f32_dpp v131, -v140, v127 row_newbcast:9 row_mask:0xf bank_mask:0xf
	v_fmac_f32_dpp v132, -v140, v128 row_newbcast:10 row_mask:0xf bank_mask:0xf
	v_fmac_f32_dpp v133, -v140, v125 row_newbcast:7 row_mask:0xf bank_mask:0xf
	s_nop 1
	v_fmac_f32_dpp v133, -v140, v129 row_newbcast:11 row_mask:0xf bank_mask:0xf
	v_cndmask_b32_e64 v134, 0, 1.0, vcc
	v_mov_b32_e32 v135, v18
	v_mov_b32_e32 v136, v18
	v_mov_b32_e32 v137, v18
	v_add_f32_e32 v2, v130, v131
	v_add_f32_e32 v3, v132, v133
	v_add_f32_e32 v120, v2, v3
	ds_read_b32 v140, v138 offset:8064
	s_waitcnt lgkmcnt(2)
	v_cmp_eq_u32_e32 vcc, 52, v1
	v_fmac_f32_dpp v137, -v148, v121 row_newbcast:3 row_mask:0xf bank_mask:0xf
	v_fmac_f32_dpp v134, -v148, v122 row_newbcast:4 row_mask:0xf bank_mask:0xf
	v_fmac_f32_dpp v135, -v148, v123 row_newbcast:5 row_mask:0xf bank_mask:0xf
	v_fmac_f32_dpp v136, -v148, v120 row_newbcast:2 row_mask:0xf bank_mask:0xf
	v_fmac_f32_dpp v137, -v148, v125 row_newbcast:7 row_mask:0xf bank_mask:0xf
	v_fmac_f32_dpp v134, -v148, v126 row_newbcast:8 row_mask:0xf bank_mask:0xf
	v_fmac_f32_dpp v135, -v148, v127 row_newbcast:9 row_mask:0xf bank_mask:0xf
	v_fmac_f32_dpp v136, -v148, v124 row_newbcast:6 row_mask:0xf bank_mask:0xf
	v_fmac_f32_dpp v137, -v148, v129 row_newbcast:11 row_mask:0xf bank_mask:0xf
	s_nop 0
	v_fmac_f32_dpp v136, -v148, v128 row_newbcast:10 row_mask:0xf bank_mask:0xf
	v_cndmask_b32_e64 v130, 0, 1.0, vcc
	v_mov_b32_e32 v131, v18
	v_mov_b32_e32 v132, v18
	v_mov_b32_e32 v133, v18
	v_add_f32_e32 v2, v134, v135
	v_add_f32_e32 v3, v136, v137
	v_add_f32_e32 v119, v2, v3
	ds_read_b32 v148, v138 offset:8000
	s_waitcnt lgkmcnt(2)
	v_cmp_eq_u32_e32 vcc, 51, v1
	v_fmac_f32_dpp v132, -v144, v120 row_newbcast:2 row_mask:0xf bank_mask:0xf
	v_fmac_f32_dpp v133, -v144, v121 row_newbcast:3 row_mask:0xf bank_mask:0xf
	v_fmac_f32_dpp v130, -v144, v122 row_newbcast:4 row_mask:0xf bank_mask:0xf
	v_fmac_f32_dpp v131, -v144, v119 row_newbcast:1 row_mask:0xf bank_mask:0xf
	v_fmac_f32_dpp v132, -v144, v124 row_newbcast:6 row_mask:0xf bank_mask:0xf
	v_fmac_f32_dpp v133, -v144, v125 row_newbcast:7 row_mask:0xf bank_mask:0xf
	v_fmac_f32_dpp v130, -v144, v126 row_newbcast:8 row_mask:0xf bank_mask:0xf
	v_fmac_f32_dpp v131, -v144, v123 row_newbcast:5 row_mask:0xf bank_mask:0xf
	v_fmac_f32_dpp v132, -v144, v128 row_newbcast:10 row_mask:0xf bank_mask:0xf
	v_fmac_f32_dpp v133, -v144, v129 row_newbcast:11 row_mask:0xf bank_mask:0xf
	v_fmac_f32_dpp v131, -v144, v127 row_newbcast:9 row_mask:0xf bank_mask:0xf
	v_cndmask_b32_e64 v134, 0, 1.0, vcc
	v_mov_b32_e32 v135, v18
	v_mov_b32_e32 v136, v18
	v_mov_b32_e32 v137, v18
	v_add_f32_e32 v2, v130, v131
	v_add_f32_e32 v3, v132, v133
	v_add_f32_e32 v118, v2, v3
	ds_read_b32 v144, v138 offset:7936
	s_waitcnt lgkmcnt(2)
	v_cmp_eq_u32_e32 vcc, 50, v1
	v_fmac_f32_dpp v135, -v140, v119 row_newbcast:1 row_mask:0xf bank_mask:0xf
	v_fmac_f32_dpp v136, -v140, v120 row_newbcast:2 row_mask:0xf bank_mask:0xf
	v_fmac_f32_dpp v137, -v140, v121 row_newbcast:3 row_mask:0xf bank_mask:0xf
	v_fmac_f32_dpp v134, -v140, v118 row_newbcast:0 row_mask:0xf bank_mask:0xf
	v_fmac_f32_dpp v135, -v140, v123 row_newbcast:5 row_mask:0xf bank_mask:0xf
	v_fmac_f32_dpp v136, -v140, v124 row_newbcast:6 row_mask:0xf bank_mask:0xf
	v_fmac_f32_dpp v137, -v140, v125 row_newbcast:7 row_mask:0xf bank_mask:0xf
	v_fmac_f32_dpp v134, -v140, v122 row_newbcast:4 row_mask:0xf bank_mask:0xf
	v_fmac_f32_dpp v135, -v140, v127 row_newbcast:9 row_mask:0xf bank_mask:0xf
	v_fmac_f32_dpp v136, -v140, v128 row_newbcast:10 row_mask:0xf bank_mask:0xf
	v_fmac_f32_dpp v137, -v140, v129 row_newbcast:11 row_mask:0xf bank_mask:0xf
	v_fmac_f32_dpp v134, -v140, v126 row_newbcast:8 row_mask:0xf bank_mask:0xf
	v_cndmask_b32_e64 v130, 0, 1.0, vcc
	v_mov_b32_e32 v131, v18
	v_mov_b32_e32 v132, v18
	v_mov_b32_e32 v133, v18
	v_add_f32_e32 v2, v134, v135
	v_add_f32_e32 v3, v136, v137
	v_add_f32_e32 v117, v2, v3
	ds_read_b32 v140, v138 offset:7872
	s_waitcnt lgkmcnt(2)
	v_cmp_eq_u32_e32 vcc, 49, v1
	v_fmac_f32_dpp v130, -v148, v118 row_newbcast:4 row_mask:0xf bank_mask:0xf
	v_fmac_f32_dpp v131, -v148, v119 row_newbcast:5 row_mask:0xf bank_mask:0xf
	v_fmac_f32_dpp v132, -v148, v120 row_newbcast:6 row_mask:0xf bank_mask:0xf
	v_fmac_f32_dpp v133, -v148, v117 row_newbcast:3 row_mask:0xf bank_mask:0xf
	v_fmac_f32_dpp v130, -v148, v122 row_newbcast:8 row_mask:0xf bank_mask:0xf
	v_fmac_f32_dpp v131, -v148, v123 row_newbcast:9 row_mask:0xf bank_mask:0xf
	v_fmac_f32_dpp v132, -v148, v124 row_newbcast:10 row_mask:0xf bank_mask:0xf
	v_fmac_f32_dpp v133, -v148, v121 row_newbcast:7 row_mask:0xf bank_mask:0xf
	v_fmac_f32_dpp v130, -v148, v126 row_newbcast:12 row_mask:0xf bank_mask:0xf
	v_fmac_f32_dpp v131, -v148, v127 row_newbcast:13 row_mask:0xf bank_mask:0xf
	v_fmac_f32_dpp v132, -v148, v128 row_newbcast:14 row_mask:0xf bank_mask:0xf
	v_fmac_f32_dpp v133, -v148, v125 row_newbcast:11 row_mask:0xf bank_mask:0xf
	s_nop 1
	v_fmac_f32_dpp v133, -v148, v129 row_newbcast:15 row_mask:0xf bank_mask:0xf
	v_cndmask_b32_e64 v134, 0, 1.0, vcc
	v_mov_b32_e32 v135, v18
	v_mov_b32_e32 v136, v18
	v_mov_b32_e32 v137, v18
	v_add_f32_e32 v2, v130, v131
	v_add_f32_e32 v3, v132, v133
	v_add_f32_e32 v116, v2, v3
	ds_read_b32 v148, v138 offset:7808
	s_waitcnt lgkmcnt(2)
	v_cmp_eq_u32_e32 vcc, 48, v1
	v_fmac_f32_dpp v137, -v144, v117 row_newbcast:3 row_mask:0xf bank_mask:0xf
	v_fmac_f32_dpp v134, -v144, v118 row_newbcast:4 row_mask:0xf bank_mask:0xf
	v_fmac_f32_dpp v135, -v144, v119 row_newbcast:5 row_mask:0xf bank_mask:0xf
	v_fmac_f32_dpp v136, -v144, v116 row_newbcast:2 row_mask:0xf bank_mask:0xf
	v_fmac_f32_dpp v137, -v144, v121 row_newbcast:7 row_mask:0xf bank_mask:0xf
	v_fmac_f32_dpp v134, -v144, v122 row_newbcast:8 row_mask:0xf bank_mask:0xf
	v_fmac_f32_dpp v135, -v144, v123 row_newbcast:9 row_mask:0xf bank_mask:0xf
	v_fmac_f32_dpp v136, -v144, v120 row_newbcast:6 row_mask:0xf bank_mask:0xf
	v_fmac_f32_dpp v137, -v144, v125 row_newbcast:11 row_mask:0xf bank_mask:0xf
	v_fmac_f32_dpp v134, -v144, v126 row_newbcast:12 row_mask:0xf bank_mask:0xf
	v_fmac_f32_dpp v135, -v144, v127 row_newbcast:13 row_mask:0xf bank_mask:0xf
	v_fmac_f32_dpp v136, -v144, v124 row_newbcast:10 row_mask:0xf bank_mask:0xf
	v_fmac_f32_dpp v137, -v144, v129 row_newbcast:15 row_mask:0xf bank_mask:0xf
	s_nop 0
	v_fmac_f32_dpp v136, -v144, v128 row_newbcast:14 row_mask:0xf bank_mask:0xf
	v_cndmask_b32_e64 v130, 0, 1.0, vcc
	v_mov_b32_e32 v131, v18
	v_mov_b32_e32 v132, v18
	v_mov_b32_e32 v133, v18
	v_add_f32_e32 v2, v134, v135
	v_add_f32_e32 v3, v136, v137
	v_add_f32_e32 v115, v2, v3
	ds_read_b32 v144, v138 offset:7728
	ds_read_b32 v145, v138 offset:7792
	s_waitcnt lgkmcnt(3)
	v_cmp_eq_u32_e32 vcc, 47, v1
	v_fmac_f32_dpp v132, -v140, v116 row_newbcast:2 row_mask:0xf bank_mask:0xf
	v_fmac_f32_dpp v133, -v140, v117 row_newbcast:3 row_mask:0xf bank_mask:0xf
	v_fmac_f32_dpp v130, -v140, v118 row_newbcast:4 row_mask:0xf bank_mask:0xf
	v_fmac_f32_dpp v131, -v140, v115 row_newbcast:1 row_mask:0xf bank_mask:0xf
	v_fmac_f32_dpp v132, -v140, v120 row_newbcast:6 row_mask:0xf bank_mask:0xf
	v_fmac_f32_dpp v133, -v140, v121 row_newbcast:7 row_mask:0xf bank_mask:0xf
	v_fmac_f32_dpp v130, -v140, v122 row_newbcast:8 row_mask:0xf bank_mask:0xf
	v_fmac_f32_dpp v131, -v140, v119 row_newbcast:5 row_mask:0xf bank_mask:0xf
	v_fmac_f32_dpp v132, -v140, v124 row_newbcast:10 row_mask:0xf bank_mask:0xf
	v_fmac_f32_dpp v133, -v140, v125 row_newbcast:11 row_mask:0xf bank_mask:0xf
	v_fmac_f32_dpp v130, -v140, v126 row_newbcast:12 row_mask:0xf bank_mask:0xf
	v_fmac_f32_dpp v131, -v140, v123 row_newbcast:9 row_mask:0xf bank_mask:0xf
	v_fmac_f32_dpp v132, -v140, v128 row_newbcast:14 row_mask:0xf bank_mask:0xf
	v_fmac_f32_dpp v133, -v140, v129 row_newbcast:15 row_mask:0xf bank_mask:0xf
	v_fmac_f32_dpp v131, -v140, v127 row_newbcast:13 row_mask:0xf bank_mask:0xf
	v_cndmask_b32_e64 v134, 0, 1.0, vcc
	v_mov_b32_e32 v135, v18
	v_mov_b32_e32 v136, v18
	v_mov_b32_e32 v137, v18
	v_add_f32_e32 v2, v130, v131
	v_add_f32_e32 v3, v132, v133
	v_add_f32_e32 v114, v2, v3
	ds_read_b32 v140, v138 offset:7648
	ds_read_b32 v141, v138 offset:7712
	s_waitcnt lgkmcnt(4)
	v_cmp_eq_u32_e32 vcc, 46, v1
	v_fmac_f32_dpp v135, -v148, v115 row_newbcast:1 row_mask:0xf bank_mask:0xf
	v_fmac_f32_dpp v136, -v148, v116 row_newbcast:2 row_mask:0xf bank_mask:0xf
	v_fmac_f32_dpp v137, -v148, v117 row_newbcast:3 row_mask:0xf bank_mask:0xf
	v_fmac_f32_dpp v134, -v148, v114 row_newbcast:0 row_mask:0xf bank_mask:0xf
	v_fmac_f32_dpp v135, -v148, v119 row_newbcast:5 row_mask:0xf bank_mask:0xf
	v_fmac_f32_dpp v136, -v148, v120 row_newbcast:6 row_mask:0xf bank_mask:0xf
	v_fmac_f32_dpp v137, -v148, v121 row_newbcast:7 row_mask:0xf bank_mask:0xf
	v_fmac_f32_dpp v134, -v148, v118 row_newbcast:4 row_mask:0xf bank_mask:0xf
	v_fmac_f32_dpp v135, -v148, v123 row_newbcast:9 row_mask:0xf bank_mask:0xf
	v_fmac_f32_dpp v136, -v148, v124 row_newbcast:10 row_mask:0xf bank_mask:0xf
	v_fmac_f32_dpp v137, -v148, v125 row_newbcast:11 row_mask:0xf bank_mask:0xf
	v_fmac_f32_dpp v134, -v148, v122 row_newbcast:8 row_mask:0xf bank_mask:0xf
	v_fmac_f32_dpp v135, -v148, v127 row_newbcast:13 row_mask:0xf bank_mask:0xf
	v_fmac_f32_dpp v136, -v148, v128 row_newbcast:14 row_mask:0xf bank_mask:0xf
	v_fmac_f32_dpp v137, -v148, v129 row_newbcast:15 row_mask:0xf bank_mask:0xf
	v_fmac_f32_dpp v134, -v148, v126 row_newbcast:12 row_mask:0xf bank_mask:0xf
	v_cndmask_b32_e64 v130, 0, 1.0, vcc
	v_mov_b32_e32 v131, v18
	v_mov_b32_e32 v132, v18
	v_mov_b32_e32 v133, v18
	v_add_f32_e32 v2, v134, v135
	v_add_f32_e32 v3, v136, v137
	v_add_f32_e32 v113, v2, v3
	ds_read_b32 v148, v138 offset:7568
	ds_read_b32 v149, v138 offset:7632
	s_waitcnt lgkmcnt(4)
	v_cmp_eq_u32_e32 vcc, 45, v1
	v_fmac_f32_dpp v130, -v144, v114 row_newbcast:4 row_mask:0xf bank_mask:0xf
	v_fmac_f32_dpp v131, -v144, v115 row_newbcast:5 row_mask:0xf bank_mask:0xf
	v_fmac_f32_dpp v132, -v144, v116 row_newbcast:6 row_mask:0xf bank_mask:0xf
	v_fmac_f32_dpp v133, -v144, v113 row_newbcast:3 row_mask:0xf bank_mask:0xf
	v_fmac_f32_dpp v130, -v144, v118 row_newbcast:8 row_mask:0xf bank_mask:0xf
	v_fmac_f32_dpp v131, -v144, v119 row_newbcast:9 row_mask:0xf bank_mask:0xf
	v_fmac_f32_dpp v132, -v144, v120 row_newbcast:10 row_mask:0xf bank_mask:0xf
	v_fmac_f32_dpp v133, -v144, v117 row_newbcast:7 row_mask:0xf bank_mask:0xf
	v_fmac_f32_dpp v130, -v144, v122 row_newbcast:12 row_mask:0xf bank_mask:0xf
	v_fmac_f32_dpp v131, -v144, v123 row_newbcast:13 row_mask:0xf bank_mask:0xf
	v_fmac_f32_dpp v132, -v144, v124 row_newbcast:14 row_mask:0xf bank_mask:0xf
	v_fmac_f32_dpp v133, -v144, v121 row_newbcast:11 row_mask:0xf bank_mask:0xf
	v_fmac_f32_dpp v130, -v145, v126 row_newbcast:0 row_mask:0xf bank_mask:0xf
	v_fmac_f32_dpp v131, -v145, v127 row_newbcast:1 row_mask:0xf bank_mask:0xf
	v_fmac_f32_dpp v132, -v145, v128 row_newbcast:2 row_mask:0xf bank_mask:0xf
	v_fmac_f32_dpp v133, -v144, v125 row_newbcast:15 row_mask:0xf bank_mask:0xf
	s_nop 1
	v_fmac_f32_dpp v133, -v145, v129 row_newbcast:3 row_mask:0xf bank_mask:0xf
	v_cndmask_b32_e64 v134, 0, 1.0, vcc
	v_mov_b32_e32 v135, v18
	v_mov_b32_e32 v136, v18
	v_mov_b32_e32 v137, v18
	v_add_f32_e32 v2, v130, v131
	v_add_f32_e32 v3, v132, v133
	v_add_f32_e32 v112, v2, v3
	ds_read_b32 v144, v138 offset:7488
	ds_read_b32 v145, v138 offset:7552
	s_waitcnt lgkmcnt(4)
	v_cmp_eq_u32_e32 vcc, 44, v1
	v_fmac_f32_dpp v137, -v140, v113 row_newbcast:3 row_mask:0xf bank_mask:0xf
	v_fmac_f32_dpp v134, -v140, v114 row_newbcast:4 row_mask:0xf bank_mask:0xf
	v_fmac_f32_dpp v135, -v140, v115 row_newbcast:5 row_mask:0xf bank_mask:0xf
	v_fmac_f32_dpp v136, -v140, v112 row_newbcast:2 row_mask:0xf bank_mask:0xf
	v_fmac_f32_dpp v137, -v140, v117 row_newbcast:7 row_mask:0xf bank_mask:0xf
	v_fmac_f32_dpp v134, -v140, v118 row_newbcast:8 row_mask:0xf bank_mask:0xf
	v_fmac_f32_dpp v135, -v140, v119 row_newbcast:9 row_mask:0xf bank_mask:0xf
	v_fmac_f32_dpp v136, -v140, v116 row_newbcast:6 row_mask:0xf bank_mask:0xf
	v_fmac_f32_dpp v137, -v140, v121 row_newbcast:11 row_mask:0xf bank_mask:0xf
	v_fmac_f32_dpp v134, -v140, v122 row_newbcast:12 row_mask:0xf bank_mask:0xf
	v_fmac_f32_dpp v135, -v140, v123 row_newbcast:13 row_mask:0xf bank_mask:0xf
	v_fmac_f32_dpp v136, -v140, v120 row_newbcast:10 row_mask:0xf bank_mask:0xf
	v_fmac_f32_dpp v137, -v140, v125 row_newbcast:15 row_mask:0xf bank_mask:0xf
	v_fmac_f32_dpp v134, -v141, v126 row_newbcast:0 row_mask:0xf bank_mask:0xf
	v_fmac_f32_dpp v135, -v141, v127 row_newbcast:1 row_mask:0xf bank_mask:0xf
	v_fmac_f32_dpp v136, -v140, v124 row_newbcast:14 row_mask:0xf bank_mask:0xf
	v_fmac_f32_dpp v137, -v141, v129 row_newbcast:3 row_mask:0xf bank_mask:0xf
	s_nop 0
	v_fmac_f32_dpp v136, -v141, v128 row_newbcast:2 row_mask:0xf bank_mask:0xf
	v_cndmask_b32_e64 v130, 0, 1.0, vcc
	v_mov_b32_e32 v131, v18
	v_mov_b32_e32 v132, v18
	v_mov_b32_e32 v133, v18
	v_add_f32_e32 v2, v134, v135
	v_add_f32_e32 v3, v136, v137
	v_add_f32_e32 v111, v2, v3
	ds_read_b32 v140, v138 offset:7392
	ds_read_b32 v141, v138 offset:7456
	s_waitcnt lgkmcnt(4)
	v_cmp_eq_u32_e32 vcc, 43, v1
	v_fmac_f32_dpp v132, -v148, v112 row_newbcast:2 row_mask:0xf bank_mask:0xf
	v_fmac_f32_dpp v133, -v148, v113 row_newbcast:3 row_mask:0xf bank_mask:0xf
	v_fmac_f32_dpp v130, -v148, v114 row_newbcast:4 row_mask:0xf bank_mask:0xf
	v_fmac_f32_dpp v131, -v148, v111 row_newbcast:1 row_mask:0xf bank_mask:0xf
	v_fmac_f32_dpp v132, -v148, v116 row_newbcast:6 row_mask:0xf bank_mask:0xf
	v_fmac_f32_dpp v133, -v148, v117 row_newbcast:7 row_mask:0xf bank_mask:0xf
	v_fmac_f32_dpp v130, -v148, v118 row_newbcast:8 row_mask:0xf bank_mask:0xf
	v_fmac_f32_dpp v131, -v148, v115 row_newbcast:5 row_mask:0xf bank_mask:0xf
	v_fmac_f32_dpp v132, -v148, v120 row_newbcast:10 row_mask:0xf bank_mask:0xf
	v_fmac_f32_dpp v133, -v148, v121 row_newbcast:11 row_mask:0xf bank_mask:0xf
	v_fmac_f32_dpp v130, -v148, v122 row_newbcast:12 row_mask:0xf bank_mask:0xf
	v_fmac_f32_dpp v131, -v148, v119 row_newbcast:9 row_mask:0xf bank_mask:0xf
	v_fmac_f32_dpp v132, -v148, v124 row_newbcast:14 row_mask:0xf bank_mask:0xf
	v_fmac_f32_dpp v133, -v148, v125 row_newbcast:15 row_mask:0xf bank_mask:0xf
	v_fmac_f32_dpp v130, -v149, v126 row_newbcast:0 row_mask:0xf bank_mask:0xf
	v_fmac_f32_dpp v131, -v148, v123 row_newbcast:13 row_mask:0xf bank_mask:0xf
	v_fmac_f32_dpp v132, -v149, v128 row_newbcast:2 row_mask:0xf bank_mask:0xf
	v_fmac_f32_dpp v133, -v149, v129 row_newbcast:3 row_mask:0xf bank_mask:0xf
	v_fmac_f32_dpp v131, -v149, v127 row_newbcast:1 row_mask:0xf bank_mask:0xf
	v_cndmask_b32_e64 v134, 0, 1.0, vcc
	v_mov_b32_e32 v135, v18
	v_mov_b32_e32 v136, v18
	v_mov_b32_e32 v137, v18
	v_add_f32_e32 v2, v130, v131
	v_add_f32_e32 v3, v132, v133
	v_add_f32_e32 v110, v2, v3
	ds_read_b32 v148, v138 offset:7296
	ds_read_b32 v149, v138 offset:7360
	s_waitcnt lgkmcnt(4)
	v_cmp_eq_u32_e32 vcc, 42, v1
	v_fmac_f32_dpp v135, -v144, v111 row_newbcast:1 row_mask:0xf bank_mask:0xf
	v_fmac_f32_dpp v136, -v144, v112 row_newbcast:2 row_mask:0xf bank_mask:0xf
	v_fmac_f32_dpp v137, -v144, v113 row_newbcast:3 row_mask:0xf bank_mask:0xf
	v_fmac_f32_dpp v134, -v144, v110 row_newbcast:0 row_mask:0xf bank_mask:0xf
	v_fmac_f32_dpp v135, -v144, v115 row_newbcast:5 row_mask:0xf bank_mask:0xf
	v_fmac_f32_dpp v136, -v144, v116 row_newbcast:6 row_mask:0xf bank_mask:0xf
	v_fmac_f32_dpp v137, -v144, v117 row_newbcast:7 row_mask:0xf bank_mask:0xf
	v_fmac_f32_dpp v134, -v144, v114 row_newbcast:4 row_mask:0xf bank_mask:0xf
	v_fmac_f32_dpp v135, -v144, v119 row_newbcast:9 row_mask:0xf bank_mask:0xf
	v_fmac_f32_dpp v136, -v144, v120 row_newbcast:10 row_mask:0xf bank_mask:0xf
	v_fmac_f32_dpp v137, -v144, v121 row_newbcast:11 row_mask:0xf bank_mask:0xf
	v_fmac_f32_dpp v134, -v144, v118 row_newbcast:8 row_mask:0xf bank_mask:0xf
	v_fmac_f32_dpp v135, -v144, v123 row_newbcast:13 row_mask:0xf bank_mask:0xf
	v_fmac_f32_dpp v136, -v144, v124 row_newbcast:14 row_mask:0xf bank_mask:0xf
	v_fmac_f32_dpp v137, -v144, v125 row_newbcast:15 row_mask:0xf bank_mask:0xf
	v_fmac_f32_dpp v134, -v144, v122 row_newbcast:12 row_mask:0xf bank_mask:0xf
	v_fmac_f32_dpp v135, -v145, v127 row_newbcast:1 row_mask:0xf bank_mask:0xf
	v_fmac_f32_dpp v136, -v145, v128 row_newbcast:2 row_mask:0xf bank_mask:0xf
	v_fmac_f32_dpp v137, -v145, v129 row_newbcast:3 row_mask:0xf bank_mask:0xf
	v_fmac_f32_dpp v134, -v145, v126 row_newbcast:0 row_mask:0xf bank_mask:0xf
	v_cndmask_b32_e64 v130, 0, 1.0, vcc
	v_mov_b32_e32 v131, v18
	v_mov_b32_e32 v132, v18
	v_mov_b32_e32 v133, v18
	v_add_f32_e32 v2, v134, v135
	v_add_f32_e32 v3, v136, v137
	v_add_f32_e32 v109, v2, v3
	ds_read_b32 v144, v138 offset:7200
	ds_read_b32 v145, v138 offset:7264
	s_waitcnt lgkmcnt(4)
	v_cmp_eq_u32_e32 vcc, 41, v1
	v_fmac_f32_dpp v130, -v140, v110 row_newbcast:4 row_mask:0xf bank_mask:0xf
	v_fmac_f32_dpp v131, -v140, v111 row_newbcast:5 row_mask:0xf bank_mask:0xf
	v_fmac_f32_dpp v132, -v140, v112 row_newbcast:6 row_mask:0xf bank_mask:0xf
	v_fmac_f32_dpp v133, -v140, v109 row_newbcast:3 row_mask:0xf bank_mask:0xf
	v_fmac_f32_dpp v130, -v140, v114 row_newbcast:8 row_mask:0xf bank_mask:0xf
	v_fmac_f32_dpp v131, -v140, v115 row_newbcast:9 row_mask:0xf bank_mask:0xf
	v_fmac_f32_dpp v132, -v140, v116 row_newbcast:10 row_mask:0xf bank_mask:0xf
	v_fmac_f32_dpp v133, -v140, v113 row_newbcast:7 row_mask:0xf bank_mask:0xf
	v_fmac_f32_dpp v130, -v140, v118 row_newbcast:12 row_mask:0xf bank_mask:0xf
	v_fmac_f32_dpp v131, -v140, v119 row_newbcast:13 row_mask:0xf bank_mask:0xf
	v_fmac_f32_dpp v132, -v140, v120 row_newbcast:14 row_mask:0xf bank_mask:0xf
	v_fmac_f32_dpp v133, -v140, v117 row_newbcast:11 row_mask:0xf bank_mask:0xf
	v_fmac_f32_dpp v130, -v141, v122 row_newbcast:0 row_mask:0xf bank_mask:0xf
	v_fmac_f32_dpp v131, -v141, v123 row_newbcast:1 row_mask:0xf bank_mask:0xf
	v_fmac_f32_dpp v132, -v141, v124 row_newbcast:2 row_mask:0xf bank_mask:0xf
	v_fmac_f32_dpp v133, -v140, v121 row_newbcast:15 row_mask:0xf bank_mask:0xf
	v_fmac_f32_dpp v130, -v141, v126 row_newbcast:4 row_mask:0xf bank_mask:0xf
	v_fmac_f32_dpp v131, -v141, v127 row_newbcast:5 row_mask:0xf bank_mask:0xf
	v_fmac_f32_dpp v132, -v141, v128 row_newbcast:6 row_mask:0xf bank_mask:0xf
	v_fmac_f32_dpp v133, -v141, v125 row_newbcast:3 row_mask:0xf bank_mask:0xf
	s_nop 1
	v_fmac_f32_dpp v133, -v141, v129 row_newbcast:7 row_mask:0xf bank_mask:0xf
	v_cndmask_b32_e64 v134, 0, 1.0, vcc
	v_mov_b32_e32 v135, v18
	v_mov_b32_e32 v136, v18
	v_mov_b32_e32 v137, v18
	v_add_f32_e32 v2, v130, v131
	v_add_f32_e32 v3, v132, v133
	v_add_f32_e32 v108, v2, v3
	ds_read_b32 v140, v138 offset:7104
	ds_read_b32 v141, v138 offset:7168
	s_waitcnt lgkmcnt(4)
	v_cmp_eq_u32_e32 vcc, 40, v1
	v_fmac_f32_dpp v137, -v148, v109 row_newbcast:3 row_mask:0xf bank_mask:0xf
	v_fmac_f32_dpp v134, -v148, v110 row_newbcast:4 row_mask:0xf bank_mask:0xf
	v_fmac_f32_dpp v135, -v148, v111 row_newbcast:5 row_mask:0xf bank_mask:0xf
	v_fmac_f32_dpp v136, -v148, v108 row_newbcast:2 row_mask:0xf bank_mask:0xf
	v_fmac_f32_dpp v137, -v148, v113 row_newbcast:7 row_mask:0xf bank_mask:0xf
	v_fmac_f32_dpp v134, -v148, v114 row_newbcast:8 row_mask:0xf bank_mask:0xf
	v_fmac_f32_dpp v135, -v148, v115 row_newbcast:9 row_mask:0xf bank_mask:0xf
	v_fmac_f32_dpp v136, -v148, v112 row_newbcast:6 row_mask:0xf bank_mask:0xf
	v_fmac_f32_dpp v137, -v148, v117 row_newbcast:11 row_mask:0xf bank_mask:0xf
	v_fmac_f32_dpp v134, -v148, v118 row_newbcast:12 row_mask:0xf bank_mask:0xf
	v_fmac_f32_dpp v135, -v148, v119 row_newbcast:13 row_mask:0xf bank_mask:0xf
	v_fmac_f32_dpp v136, -v148, v116 row_newbcast:10 row_mask:0xf bank_mask:0xf
	v_fmac_f32_dpp v137, -v148, v121 row_newbcast:15 row_mask:0xf bank_mask:0xf
	v_fmac_f32_dpp v134, -v149, v122 row_newbcast:0 row_mask:0xf bank_mask:0xf
	v_fmac_f32_dpp v135, -v149, v123 row_newbcast:1 row_mask:0xf bank_mask:0xf
	v_fmac_f32_dpp v136, -v148, v120 row_newbcast:14 row_mask:0xf bank_mask:0xf
	v_fmac_f32_dpp v137, -v149, v125 row_newbcast:3 row_mask:0xf bank_mask:0xf
	v_fmac_f32_dpp v134, -v149, v126 row_newbcast:4 row_mask:0xf bank_mask:0xf
	v_fmac_f32_dpp v135, -v149, v127 row_newbcast:5 row_mask:0xf bank_mask:0xf
	v_fmac_f32_dpp v136, -v149, v124 row_newbcast:2 row_mask:0xf bank_mask:0xf
	v_fmac_f32_dpp v137, -v149, v129 row_newbcast:7 row_mask:0xf bank_mask:0xf
	s_nop 0
	v_fmac_f32_dpp v136, -v149, v128 row_newbcast:6 row_mask:0xf bank_mask:0xf
	v_cndmask_b32_e64 v130, 0, 1.0, vcc
	v_mov_b32_e32 v131, v18
	v_mov_b32_e32 v132, v18
	v_mov_b32_e32 v133, v18
	v_add_f32_e32 v2, v134, v135
	v_add_f32_e32 v3, v136, v137
	v_add_f32_e32 v107, v2, v3
	ds_read_b32 v148, v138 offset:6992
	ds_read_b32 v149, v138 offset:7056
	s_waitcnt lgkmcnt(4)
	v_cmp_eq_u32_e32 vcc, 39, v1
	v_fmac_f32_dpp v132, -v144, v108 row_newbcast:2 row_mask:0xf bank_mask:0xf
	v_fmac_f32_dpp v133, -v144, v109 row_newbcast:3 row_mask:0xf bank_mask:0xf
	v_fmac_f32_dpp v130, -v144, v110 row_newbcast:4 row_mask:0xf bank_mask:0xf
	v_fmac_f32_dpp v131, -v144, v107 row_newbcast:1 row_mask:0xf bank_mask:0xf
	v_fmac_f32_dpp v132, -v144, v112 row_newbcast:6 row_mask:0xf bank_mask:0xf
	v_fmac_f32_dpp v133, -v144, v113 row_newbcast:7 row_mask:0xf bank_mask:0xf
	v_fmac_f32_dpp v130, -v144, v114 row_newbcast:8 row_mask:0xf bank_mask:0xf
	v_fmac_f32_dpp v131, -v144, v111 row_newbcast:5 row_mask:0xf bank_mask:0xf
	v_fmac_f32_dpp v132, -v144, v116 row_newbcast:10 row_mask:0xf bank_mask:0xf
	v_fmac_f32_dpp v133, -v144, v117 row_newbcast:11 row_mask:0xf bank_mask:0xf
	v_fmac_f32_dpp v130, -v144, v118 row_newbcast:12 row_mask:0xf bank_mask:0xf
	v_fmac_f32_dpp v131, -v144, v115 row_newbcast:9 row_mask:0xf bank_mask:0xf
	v_fmac_f32_dpp v132, -v144, v120 row_newbcast:14 row_mask:0xf bank_mask:0xf
	v_fmac_f32_dpp v133, -v144, v121 row_newbcast:15 row_mask:0xf bank_mask:0xf
	v_fmac_f32_dpp v130, -v145, v122 row_newbcast:0 row_mask:0xf bank_mask:0xf
	v_fmac_f32_dpp v131, -v144, v119 row_newbcast:13 row_mask:0xf bank_mask:0xf
	v_fmac_f32_dpp v132, -v145, v124 row_newbcast:2 row_mask:0xf bank_mask:0xf
	v_fmac_f32_dpp v133, -v145, v125 row_newbcast:3 row_mask:0xf bank_mask:0xf
	v_fmac_f32_dpp v130, -v145, v126 row_newbcast:4 row_mask:0xf bank_mask:0xf
	v_fmac_f32_dpp v131, -v145, v123 row_newbcast:1 row_mask:0xf bank_mask:0xf
	v_fmac_f32_dpp v132, -v145, v128 row_newbcast:6 row_mask:0xf bank_mask:0xf
	v_fmac_f32_dpp v133, -v145, v129 row_newbcast:7 row_mask:0xf bank_mask:0xf
	v_fmac_f32_dpp v131, -v145, v127 row_newbcast:5 row_mask:0xf bank_mask:0xf
	v_cndmask_b32_e64 v134, 0, 1.0, vcc
	v_mov_b32_e32 v135, v18
	v_mov_b32_e32 v136, v18
	v_mov_b32_e32 v137, v18
	v_add_f32_e32 v2, v130, v131
	v_add_f32_e32 v3, v132, v133
	v_add_f32_e32 v106, v2, v3
	ds_read_b32 v144, v138 offset:6880
	ds_read_b32 v145, v138 offset:6944
	s_waitcnt lgkmcnt(4)
	v_cmp_eq_u32_e32 vcc, 38, v1
	v_fmac_f32_dpp v135, -v140, v107 row_newbcast:1 row_mask:0xf bank_mask:0xf
	v_fmac_f32_dpp v136, -v140, v108 row_newbcast:2 row_mask:0xf bank_mask:0xf
	v_fmac_f32_dpp v137, -v140, v109 row_newbcast:3 row_mask:0xf bank_mask:0xf
	v_fmac_f32_dpp v134, -v140, v106 row_newbcast:0 row_mask:0xf bank_mask:0xf
	v_fmac_f32_dpp v135, -v140, v111 row_newbcast:5 row_mask:0xf bank_mask:0xf
	v_fmac_f32_dpp v136, -v140, v112 row_newbcast:6 row_mask:0xf bank_mask:0xf
	v_fmac_f32_dpp v137, -v140, v113 row_newbcast:7 row_mask:0xf bank_mask:0xf
	v_fmac_f32_dpp v134, -v140, v110 row_newbcast:4 row_mask:0xf bank_mask:0xf
	v_fmac_f32_dpp v135, -v140, v115 row_newbcast:9 row_mask:0xf bank_mask:0xf
	v_fmac_f32_dpp v136, -v140, v116 row_newbcast:10 row_mask:0xf bank_mask:0xf
	v_fmac_f32_dpp v137, -v140, v117 row_newbcast:11 row_mask:0xf bank_mask:0xf
	v_fmac_f32_dpp v134, -v140, v114 row_newbcast:8 row_mask:0xf bank_mask:0xf
	v_fmac_f32_dpp v135, -v140, v119 row_newbcast:13 row_mask:0xf bank_mask:0xf
	v_fmac_f32_dpp v136, -v140, v120 row_newbcast:14 row_mask:0xf bank_mask:0xf
	v_fmac_f32_dpp v137, -v140, v121 row_newbcast:15 row_mask:0xf bank_mask:0xf
	v_fmac_f32_dpp v134, -v140, v118 row_newbcast:12 row_mask:0xf bank_mask:0xf
	v_fmac_f32_dpp v135, -v141, v123 row_newbcast:1 row_mask:0xf bank_mask:0xf
	v_fmac_f32_dpp v136, -v141, v124 row_newbcast:2 row_mask:0xf bank_mask:0xf
	v_fmac_f32_dpp v137, -v141, v125 row_newbcast:3 row_mask:0xf bank_mask:0xf
	v_fmac_f32_dpp v134, -v141, v122 row_newbcast:0 row_mask:0xf bank_mask:0xf
	v_fmac_f32_dpp v135, -v141, v127 row_newbcast:5 row_mask:0xf bank_mask:0xf
	v_fmac_f32_dpp v136, -v141, v128 row_newbcast:6 row_mask:0xf bank_mask:0xf
	v_fmac_f32_dpp v137, -v141, v129 row_newbcast:7 row_mask:0xf bank_mask:0xf
	v_fmac_f32_dpp v134, -v141, v126 row_newbcast:4 row_mask:0xf bank_mask:0xf
	v_cndmask_b32_e64 v130, 0, 1.0, vcc
	v_mov_b32_e32 v131, v18
	v_mov_b32_e32 v132, v18
	v_mov_b32_e32 v133, v18
	v_add_f32_e32 v2, v134, v135
	v_add_f32_e32 v3, v136, v137
	v_add_f32_e32 v105, v2, v3
	ds_read_b32 v140, v138 offset:6768
	ds_read_b32 v141, v138 offset:6832
	s_waitcnt lgkmcnt(4)
	v_cmp_eq_u32_e32 vcc, 37, v1
	v_fmac_f32_dpp v130, -v148, v106 row_newbcast:4 row_mask:0xf bank_mask:0xf
	v_fmac_f32_dpp v131, -v148, v107 row_newbcast:5 row_mask:0xf bank_mask:0xf
	v_fmac_f32_dpp v132, -v148, v108 row_newbcast:6 row_mask:0xf bank_mask:0xf
	v_fmac_f32_dpp v133, -v148, v105 row_newbcast:3 row_mask:0xf bank_mask:0xf
	v_fmac_f32_dpp v130, -v148, v110 row_newbcast:8 row_mask:0xf bank_mask:0xf
	v_fmac_f32_dpp v131, -v148, v111 row_newbcast:9 row_mask:0xf bank_mask:0xf
	v_fmac_f32_dpp v132, -v148, v112 row_newbcast:10 row_mask:0xf bank_mask:0xf
	v_fmac_f32_dpp v133, -v148, v109 row_newbcast:7 row_mask:0xf bank_mask:0xf
	v_fmac_f32_dpp v130, -v148, v114 row_newbcast:12 row_mask:0xf bank_mask:0xf
	v_fmac_f32_dpp v131, -v148, v115 row_newbcast:13 row_mask:0xf bank_mask:0xf
	v_fmac_f32_dpp v132, -v148, v116 row_newbcast:14 row_mask:0xf bank_mask:0xf
	v_fmac_f32_dpp v133, -v148, v113 row_newbcast:11 row_mask:0xf bank_mask:0xf
	v_fmac_f32_dpp v130, -v149, v118 row_newbcast:0 row_mask:0xf bank_mask:0xf
	v_fmac_f32_dpp v131, -v149, v119 row_newbcast:1 row_mask:0xf bank_mask:0xf
	v_fmac_f32_dpp v132, -v149, v120 row_newbcast:2 row_mask:0xf bank_mask:0xf
	v_fmac_f32_dpp v133, -v148, v117 row_newbcast:15 row_mask:0xf bank_mask:0xf
	v_fmac_f32_dpp v130, -v149, v122 row_newbcast:4 row_mask:0xf bank_mask:0xf
	v_fmac_f32_dpp v131, -v149, v123 row_newbcast:5 row_mask:0xf bank_mask:0xf
	v_fmac_f32_dpp v132, -v149, v124 row_newbcast:6 row_mask:0xf bank_mask:0xf
	v_fmac_f32_dpp v133, -v149, v121 row_newbcast:3 row_mask:0xf bank_mask:0xf
	v_fmac_f32_dpp v130, -v149, v126 row_newbcast:8 row_mask:0xf bank_mask:0xf
	v_fmac_f32_dpp v131, -v149, v127 row_newbcast:9 row_mask:0xf bank_mask:0xf
	v_fmac_f32_dpp v132, -v149, v128 row_newbcast:10 row_mask:0xf bank_mask:0xf
	v_fmac_f32_dpp v133, -v149, v125 row_newbcast:7 row_mask:0xf bank_mask:0xf
	s_nop 1
	v_fmac_f32_dpp v133, -v149, v129 row_newbcast:11 row_mask:0xf bank_mask:0xf
	v_cndmask_b32_e64 v134, 0, 1.0, vcc
	v_mov_b32_e32 v135, v18
	v_mov_b32_e32 v136, v18
	v_mov_b32_e32 v137, v18
	v_add_f32_e32 v2, v130, v131
	v_add_f32_e32 v3, v132, v133
	v_add_f32_e32 v104, v2, v3
	ds_read_b32 v148, v138 offset:6656
	ds_read_b32 v149, v138 offset:6720
	s_waitcnt lgkmcnt(4)
	v_cmp_eq_u32_e32 vcc, 36, v1
	v_fmac_f32_dpp v137, -v144, v105 row_newbcast:3 row_mask:0xf bank_mask:0xf
	v_fmac_f32_dpp v134, -v144, v106 row_newbcast:4 row_mask:0xf bank_mask:0xf
	v_fmac_f32_dpp v135, -v144, v107 row_newbcast:5 row_mask:0xf bank_mask:0xf
	v_fmac_f32_dpp v136, -v144, v104 row_newbcast:2 row_mask:0xf bank_mask:0xf
	v_fmac_f32_dpp v137, -v144, v109 row_newbcast:7 row_mask:0xf bank_mask:0xf
	v_fmac_f32_dpp v134, -v144, v110 row_newbcast:8 row_mask:0xf bank_mask:0xf
	v_fmac_f32_dpp v135, -v144, v111 row_newbcast:9 row_mask:0xf bank_mask:0xf
	v_fmac_f32_dpp v136, -v144, v108 row_newbcast:6 row_mask:0xf bank_mask:0xf
	v_fmac_f32_dpp v137, -v144, v113 row_newbcast:11 row_mask:0xf bank_mask:0xf
	v_fmac_f32_dpp v134, -v144, v114 row_newbcast:12 row_mask:0xf bank_mask:0xf
	v_fmac_f32_dpp v135, -v144, v115 row_newbcast:13 row_mask:0xf bank_mask:0xf
	v_fmac_f32_dpp v136, -v144, v112 row_newbcast:10 row_mask:0xf bank_mask:0xf
	v_fmac_f32_dpp v137, -v144, v117 row_newbcast:15 row_mask:0xf bank_mask:0xf
	v_fmac_f32_dpp v134, -v145, v118 row_newbcast:0 row_mask:0xf bank_mask:0xf
	v_fmac_f32_dpp v135, -v145, v119 row_newbcast:1 row_mask:0xf bank_mask:0xf
	v_fmac_f32_dpp v136, -v144, v116 row_newbcast:14 row_mask:0xf bank_mask:0xf
	v_fmac_f32_dpp v137, -v145, v121 row_newbcast:3 row_mask:0xf bank_mask:0xf
	v_fmac_f32_dpp v134, -v145, v122 row_newbcast:4 row_mask:0xf bank_mask:0xf
	v_fmac_f32_dpp v135, -v145, v123 row_newbcast:5 row_mask:0xf bank_mask:0xf
	v_fmac_f32_dpp v136, -v145, v120 row_newbcast:2 row_mask:0xf bank_mask:0xf
	v_fmac_f32_dpp v137, -v145, v125 row_newbcast:7 row_mask:0xf bank_mask:0xf
	v_fmac_f32_dpp v134, -v145, v126 row_newbcast:8 row_mask:0xf bank_mask:0xf
	v_fmac_f32_dpp v135, -v145, v127 row_newbcast:9 row_mask:0xf bank_mask:0xf
	v_fmac_f32_dpp v136, -v145, v124 row_newbcast:6 row_mask:0xf bank_mask:0xf
	v_fmac_f32_dpp v137, -v145, v129 row_newbcast:11 row_mask:0xf bank_mask:0xf
	s_nop 0
	v_fmac_f32_dpp v136, -v145, v128 row_newbcast:10 row_mask:0xf bank_mask:0xf
	v_cndmask_b32_e64 v130, 0, 1.0, vcc
	v_mov_b32_e32 v131, v18
	v_mov_b32_e32 v132, v18
	v_mov_b32_e32 v133, v18
	v_add_f32_e32 v2, v134, v135
	v_add_f32_e32 v3, v136, v137
	v_add_f32_e32 v103, v2, v3
	ds_read_b32 v144, v138 offset:6528
	ds_read_b32 v145, v138 offset:6592
	s_waitcnt lgkmcnt(4)
	v_cmp_eq_u32_e32 vcc, 35, v1
	v_fmac_f32_dpp v132, -v140, v104 row_newbcast:2 row_mask:0xf bank_mask:0xf
	v_fmac_f32_dpp v133, -v140, v105 row_newbcast:3 row_mask:0xf bank_mask:0xf
	v_fmac_f32_dpp v130, -v140, v106 row_newbcast:4 row_mask:0xf bank_mask:0xf
	v_fmac_f32_dpp v131, -v140, v103 row_newbcast:1 row_mask:0xf bank_mask:0xf
	v_fmac_f32_dpp v132, -v140, v108 row_newbcast:6 row_mask:0xf bank_mask:0xf
	v_fmac_f32_dpp v133, -v140, v109 row_newbcast:7 row_mask:0xf bank_mask:0xf
	v_fmac_f32_dpp v130, -v140, v110 row_newbcast:8 row_mask:0xf bank_mask:0xf
	v_fmac_f32_dpp v131, -v140, v107 row_newbcast:5 row_mask:0xf bank_mask:0xf
	v_fmac_f32_dpp v132, -v140, v112 row_newbcast:10 row_mask:0xf bank_mask:0xf
	v_fmac_f32_dpp v133, -v140, v113 row_newbcast:11 row_mask:0xf bank_mask:0xf
	v_fmac_f32_dpp v130, -v140, v114 row_newbcast:12 row_mask:0xf bank_mask:0xf
	v_fmac_f32_dpp v131, -v140, v111 row_newbcast:9 row_mask:0xf bank_mask:0xf
	v_fmac_f32_dpp v132, -v140, v116 row_newbcast:14 row_mask:0xf bank_mask:0xf
	v_fmac_f32_dpp v133, -v140, v117 row_newbcast:15 row_mask:0xf bank_mask:0xf
	v_fmac_f32_dpp v130, -v141, v118 row_newbcast:0 row_mask:0xf bank_mask:0xf
	v_fmac_f32_dpp v131, -v140, v115 row_newbcast:13 row_mask:0xf bank_mask:0xf
	v_fmac_f32_dpp v132, -v141, v120 row_newbcast:2 row_mask:0xf bank_mask:0xf
	v_fmac_f32_dpp v133, -v141, v121 row_newbcast:3 row_mask:0xf bank_mask:0xf
	v_fmac_f32_dpp v130, -v141, v122 row_newbcast:4 row_mask:0xf bank_mask:0xf
	v_fmac_f32_dpp v131, -v141, v119 row_newbcast:1 row_mask:0xf bank_mask:0xf
	v_fmac_f32_dpp v132, -v141, v124 row_newbcast:6 row_mask:0xf bank_mask:0xf
	v_fmac_f32_dpp v133, -v141, v125 row_newbcast:7 row_mask:0xf bank_mask:0xf
	v_fmac_f32_dpp v130, -v141, v126 row_newbcast:8 row_mask:0xf bank_mask:0xf
	v_fmac_f32_dpp v131, -v141, v123 row_newbcast:5 row_mask:0xf bank_mask:0xf
	v_fmac_f32_dpp v132, -v141, v128 row_newbcast:10 row_mask:0xf bank_mask:0xf
	v_fmac_f32_dpp v133, -v141, v129 row_newbcast:11 row_mask:0xf bank_mask:0xf
	v_fmac_f32_dpp v131, -v141, v127 row_newbcast:9 row_mask:0xf bank_mask:0xf
	v_cndmask_b32_e64 v134, 0, 1.0, vcc
	v_mov_b32_e32 v135, v18
	v_mov_b32_e32 v136, v18
	v_mov_b32_e32 v137, v18
	v_add_f32_e32 v2, v130, v131
	v_add_f32_e32 v3, v132, v133
	v_add_f32_e32 v102, v2, v3
	ds_read_b32 v140, v138 offset:6400
	ds_read_b32 v141, v138 offset:6464
	s_waitcnt lgkmcnt(4)
	v_cmp_eq_u32_e32 vcc, 34, v1
	v_fmac_f32_dpp v135, -v148, v103 row_newbcast:1 row_mask:0xf bank_mask:0xf
	v_fmac_f32_dpp v136, -v148, v104 row_newbcast:2 row_mask:0xf bank_mask:0xf
	v_fmac_f32_dpp v137, -v148, v105 row_newbcast:3 row_mask:0xf bank_mask:0xf
	v_fmac_f32_dpp v134, -v148, v102 row_newbcast:0 row_mask:0xf bank_mask:0xf
	v_fmac_f32_dpp v135, -v148, v107 row_newbcast:5 row_mask:0xf bank_mask:0xf
	v_fmac_f32_dpp v136, -v148, v108 row_newbcast:6 row_mask:0xf bank_mask:0xf
	v_fmac_f32_dpp v137, -v148, v109 row_newbcast:7 row_mask:0xf bank_mask:0xf
	v_fmac_f32_dpp v134, -v148, v106 row_newbcast:4 row_mask:0xf bank_mask:0xf
	v_fmac_f32_dpp v135, -v148, v111 row_newbcast:9 row_mask:0xf bank_mask:0xf
	v_fmac_f32_dpp v136, -v148, v112 row_newbcast:10 row_mask:0xf bank_mask:0xf
	v_fmac_f32_dpp v137, -v148, v113 row_newbcast:11 row_mask:0xf bank_mask:0xf
	v_fmac_f32_dpp v134, -v148, v110 row_newbcast:8 row_mask:0xf bank_mask:0xf
	v_fmac_f32_dpp v135, -v148, v115 row_newbcast:13 row_mask:0xf bank_mask:0xf
	v_fmac_f32_dpp v136, -v148, v116 row_newbcast:14 row_mask:0xf bank_mask:0xf
	v_fmac_f32_dpp v137, -v148, v117 row_newbcast:15 row_mask:0xf bank_mask:0xf
	v_fmac_f32_dpp v134, -v148, v114 row_newbcast:12 row_mask:0xf bank_mask:0xf
	v_fmac_f32_dpp v135, -v149, v119 row_newbcast:1 row_mask:0xf bank_mask:0xf
	v_fmac_f32_dpp v136, -v149, v120 row_newbcast:2 row_mask:0xf bank_mask:0xf
	v_fmac_f32_dpp v137, -v149, v121 row_newbcast:3 row_mask:0xf bank_mask:0xf
	v_fmac_f32_dpp v134, -v149, v118 row_newbcast:0 row_mask:0xf bank_mask:0xf
	v_fmac_f32_dpp v135, -v149, v123 row_newbcast:5 row_mask:0xf bank_mask:0xf
	v_fmac_f32_dpp v136, -v149, v124 row_newbcast:6 row_mask:0xf bank_mask:0xf
	v_fmac_f32_dpp v137, -v149, v125 row_newbcast:7 row_mask:0xf bank_mask:0xf
	v_fmac_f32_dpp v134, -v149, v122 row_newbcast:4 row_mask:0xf bank_mask:0xf
	v_fmac_f32_dpp v135, -v149, v127 row_newbcast:9 row_mask:0xf bank_mask:0xf
	v_fmac_f32_dpp v136, -v149, v128 row_newbcast:10 row_mask:0xf bank_mask:0xf
	v_fmac_f32_dpp v137, -v149, v129 row_newbcast:11 row_mask:0xf bank_mask:0xf
	v_fmac_f32_dpp v134, -v149, v126 row_newbcast:8 row_mask:0xf bank_mask:0xf
	v_cndmask_b32_e64 v130, 0, 1.0, vcc
	v_mov_b32_e32 v131, v18
	v_mov_b32_e32 v132, v18
	v_mov_b32_e32 v133, v18
	v_add_f32_e32 v2, v134, v135
	v_add_f32_e32 v3, v136, v137
	v_add_f32_e32 v101, v2, v3
	ds_read_b32 v148, v138 offset:6272
	ds_read_b32 v149, v138 offset:6336
	s_waitcnt lgkmcnt(4)
	v_cmp_eq_u32_e32 vcc, 33, v1
	v_fmac_f32_dpp v130, -v144, v102 row_newbcast:4 row_mask:0xf bank_mask:0xf
	v_fmac_f32_dpp v131, -v144, v103 row_newbcast:5 row_mask:0xf bank_mask:0xf
	v_fmac_f32_dpp v132, -v144, v104 row_newbcast:6 row_mask:0xf bank_mask:0xf
	v_fmac_f32_dpp v133, -v144, v101 row_newbcast:3 row_mask:0xf bank_mask:0xf
	v_fmac_f32_dpp v130, -v144, v106 row_newbcast:8 row_mask:0xf bank_mask:0xf
	v_fmac_f32_dpp v131, -v144, v107 row_newbcast:9 row_mask:0xf bank_mask:0xf
	v_fmac_f32_dpp v132, -v144, v108 row_newbcast:10 row_mask:0xf bank_mask:0xf
	v_fmac_f32_dpp v133, -v144, v105 row_newbcast:7 row_mask:0xf bank_mask:0xf
	v_fmac_f32_dpp v130, -v144, v110 row_newbcast:12 row_mask:0xf bank_mask:0xf
	v_fmac_f32_dpp v131, -v144, v111 row_newbcast:13 row_mask:0xf bank_mask:0xf
	v_fmac_f32_dpp v132, -v144, v112 row_newbcast:14 row_mask:0xf bank_mask:0xf
	v_fmac_f32_dpp v133, -v144, v109 row_newbcast:11 row_mask:0xf bank_mask:0xf
	v_fmac_f32_dpp v130, -v145, v114 row_newbcast:0 row_mask:0xf bank_mask:0xf
	v_fmac_f32_dpp v131, -v145, v115 row_newbcast:1 row_mask:0xf bank_mask:0xf
	v_fmac_f32_dpp v132, -v145, v116 row_newbcast:2 row_mask:0xf bank_mask:0xf
	v_fmac_f32_dpp v133, -v144, v113 row_newbcast:15 row_mask:0xf bank_mask:0xf
	v_fmac_f32_dpp v130, -v145, v118 row_newbcast:4 row_mask:0xf bank_mask:0xf
	v_fmac_f32_dpp v131, -v145, v119 row_newbcast:5 row_mask:0xf bank_mask:0xf
	v_fmac_f32_dpp v132, -v145, v120 row_newbcast:6 row_mask:0xf bank_mask:0xf
	v_fmac_f32_dpp v133, -v145, v117 row_newbcast:3 row_mask:0xf bank_mask:0xf
	v_fmac_f32_dpp v130, -v145, v122 row_newbcast:8 row_mask:0xf bank_mask:0xf
	v_fmac_f32_dpp v131, -v145, v123 row_newbcast:9 row_mask:0xf bank_mask:0xf
	v_fmac_f32_dpp v132, -v145, v124 row_newbcast:10 row_mask:0xf bank_mask:0xf
	v_fmac_f32_dpp v133, -v145, v121 row_newbcast:7 row_mask:0xf bank_mask:0xf
	v_fmac_f32_dpp v130, -v145, v126 row_newbcast:12 row_mask:0xf bank_mask:0xf
	v_fmac_f32_dpp v131, -v145, v127 row_newbcast:13 row_mask:0xf bank_mask:0xf
	v_fmac_f32_dpp v132, -v145, v128 row_newbcast:14 row_mask:0xf bank_mask:0xf
	v_fmac_f32_dpp v133, -v145, v125 row_newbcast:11 row_mask:0xf bank_mask:0xf
	s_nop 1
	v_fmac_f32_dpp v133, -v145, v129 row_newbcast:15 row_mask:0xf bank_mask:0xf
	v_cndmask_b32_e64 v134, 0, 1.0, vcc
	v_mov_b32_e32 v135, v18
	v_mov_b32_e32 v136, v18
	v_mov_b32_e32 v137, v18
	v_add_f32_e32 v2, v130, v131
	v_add_f32_e32 v3, v132, v133
	v_add_f32_e32 v100, v2, v3
	ds_read_b32 v144, v138 offset:6144
	ds_read_b32 v145, v138 offset:6208
	s_waitcnt lgkmcnt(4)
	v_cmp_eq_u32_e32 vcc, 32, v1
	v_fmac_f32_dpp v137, -v140, v101 row_newbcast:3 row_mask:0xf bank_mask:0xf
	v_fmac_f32_dpp v134, -v140, v102 row_newbcast:4 row_mask:0xf bank_mask:0xf
	v_fmac_f32_dpp v135, -v140, v103 row_newbcast:5 row_mask:0xf bank_mask:0xf
	v_fmac_f32_dpp v136, -v140, v100 row_newbcast:2 row_mask:0xf bank_mask:0xf
	v_fmac_f32_dpp v137, -v140, v105 row_newbcast:7 row_mask:0xf bank_mask:0xf
	v_fmac_f32_dpp v134, -v140, v106 row_newbcast:8 row_mask:0xf bank_mask:0xf
	v_fmac_f32_dpp v135, -v140, v107 row_newbcast:9 row_mask:0xf bank_mask:0xf
	v_fmac_f32_dpp v136, -v140, v104 row_newbcast:6 row_mask:0xf bank_mask:0xf
	v_fmac_f32_dpp v137, -v140, v109 row_newbcast:11 row_mask:0xf bank_mask:0xf
	v_fmac_f32_dpp v134, -v140, v110 row_newbcast:12 row_mask:0xf bank_mask:0xf
	v_fmac_f32_dpp v135, -v140, v111 row_newbcast:13 row_mask:0xf bank_mask:0xf
	v_fmac_f32_dpp v136, -v140, v108 row_newbcast:10 row_mask:0xf bank_mask:0xf
	v_fmac_f32_dpp v137, -v140, v113 row_newbcast:15 row_mask:0xf bank_mask:0xf
	v_fmac_f32_dpp v134, -v141, v114 row_newbcast:0 row_mask:0xf bank_mask:0xf
	v_fmac_f32_dpp v135, -v141, v115 row_newbcast:1 row_mask:0xf bank_mask:0xf
	v_fmac_f32_dpp v136, -v140, v112 row_newbcast:14 row_mask:0xf bank_mask:0xf
	v_fmac_f32_dpp v137, -v141, v117 row_newbcast:3 row_mask:0xf bank_mask:0xf
	v_fmac_f32_dpp v134, -v141, v118 row_newbcast:4 row_mask:0xf bank_mask:0xf
	v_fmac_f32_dpp v135, -v141, v119 row_newbcast:5 row_mask:0xf bank_mask:0xf
	v_fmac_f32_dpp v136, -v141, v116 row_newbcast:2 row_mask:0xf bank_mask:0xf
	v_fmac_f32_dpp v137, -v141, v121 row_newbcast:7 row_mask:0xf bank_mask:0xf
	v_fmac_f32_dpp v134, -v141, v122 row_newbcast:8 row_mask:0xf bank_mask:0xf
	v_fmac_f32_dpp v135, -v141, v123 row_newbcast:9 row_mask:0xf bank_mask:0xf
	v_fmac_f32_dpp v136, -v141, v120 row_newbcast:6 row_mask:0xf bank_mask:0xf
	v_fmac_f32_dpp v137, -v141, v125 row_newbcast:11 row_mask:0xf bank_mask:0xf
	v_fmac_f32_dpp v134, -v141, v126 row_newbcast:12 row_mask:0xf bank_mask:0xf
	v_fmac_f32_dpp v135, -v141, v127 row_newbcast:13 row_mask:0xf bank_mask:0xf
	v_fmac_f32_dpp v136, -v141, v124 row_newbcast:10 row_mask:0xf bank_mask:0xf
	v_fmac_f32_dpp v137, -v141, v129 row_newbcast:15 row_mask:0xf bank_mask:0xf
	s_nop 0
	v_fmac_f32_dpp v136, -v141, v128 row_newbcast:14 row_mask:0xf bank_mask:0xf
	v_cndmask_b32_e64 v130, 0, 1.0, vcc
	v_mov_b32_e32 v131, v18
	v_mov_b32_e32 v132, v18
	v_mov_b32_e32 v133, v18
	v_add_f32_e32 v2, v134, v135
	v_add_f32_e32 v3, v136, v137
	v_add_f32_e32 v99, v2, v3
	ds_read_b32 v140, v138 offset:6000
	ds_read_b32 v141, v138 offset:6064
	ds_read_b32 v142, v138 offset:6128
	s_waitcnt lgkmcnt(5)
	v_cmp_eq_u32_e32 vcc, 31, v1
	v_fmac_f32_dpp v132, -v148, v100 row_newbcast:2 row_mask:0xf bank_mask:0xf
	v_fmac_f32_dpp v133, -v148, v101 row_newbcast:3 row_mask:0xf bank_mask:0xf
	v_fmac_f32_dpp v130, -v148, v102 row_newbcast:4 row_mask:0xf bank_mask:0xf
	v_fmac_f32_dpp v131, -v148, v99 row_newbcast:1 row_mask:0xf bank_mask:0xf
	v_fmac_f32_dpp v132, -v148, v104 row_newbcast:6 row_mask:0xf bank_mask:0xf
	v_fmac_f32_dpp v133, -v148, v105 row_newbcast:7 row_mask:0xf bank_mask:0xf
	v_fmac_f32_dpp v130, -v148, v106 row_newbcast:8 row_mask:0xf bank_mask:0xf
	v_fmac_f32_dpp v131, -v148, v103 row_newbcast:5 row_mask:0xf bank_mask:0xf
	v_fmac_f32_dpp v132, -v148, v108 row_newbcast:10 row_mask:0xf bank_mask:0xf
	v_fmac_f32_dpp v133, -v148, v109 row_newbcast:11 row_mask:0xf bank_mask:0xf
	v_fmac_f32_dpp v130, -v148, v110 row_newbcast:12 row_mask:0xf bank_mask:0xf
	v_fmac_f32_dpp v131, -v148, v107 row_newbcast:9 row_mask:0xf bank_mask:0xf
	v_fmac_f32_dpp v132, -v148, v112 row_newbcast:14 row_mask:0xf bank_mask:0xf
	v_fmac_f32_dpp v133, -v148, v113 row_newbcast:15 row_mask:0xf bank_mask:0xf
	v_fmac_f32_dpp v130, -v149, v114 row_newbcast:0 row_mask:0xf bank_mask:0xf
	v_fmac_f32_dpp v131, -v148, v111 row_newbcast:13 row_mask:0xf bank_mask:0xf
	v_fmac_f32_dpp v132, -v149, v116 row_newbcast:2 row_mask:0xf bank_mask:0xf
	v_fmac_f32_dpp v133, -v149, v117 row_newbcast:3 row_mask:0xf bank_mask:0xf
	v_fmac_f32_dpp v130, -v149, v118 row_newbcast:4 row_mask:0xf bank_mask:0xf
	v_fmac_f32_dpp v131, -v149, v115 row_newbcast:1 row_mask:0xf bank_mask:0xf
	v_fmac_f32_dpp v132, -v149, v120 row_newbcast:6 row_mask:0xf bank_mask:0xf
	v_fmac_f32_dpp v133, -v149, v121 row_newbcast:7 row_mask:0xf bank_mask:0xf
	v_fmac_f32_dpp v130, -v149, v122 row_newbcast:8 row_mask:0xf bank_mask:0xf
	v_fmac_f32_dpp v131, -v149, v119 row_newbcast:5 row_mask:0xf bank_mask:0xf
	v_fmac_f32_dpp v132, -v149, v124 row_newbcast:10 row_mask:0xf bank_mask:0xf
	v_fmac_f32_dpp v133, -v149, v125 row_newbcast:11 row_mask:0xf bank_mask:0xf
	v_fmac_f32_dpp v130, -v149, v126 row_newbcast:12 row_mask:0xf bank_mask:0xf
	v_fmac_f32_dpp v131, -v149, v123 row_newbcast:9 row_mask:0xf bank_mask:0xf
	v_fmac_f32_dpp v132, -v149, v128 row_newbcast:14 row_mask:0xf bank_mask:0xf
	v_fmac_f32_dpp v133, -v149, v129 row_newbcast:15 row_mask:0xf bank_mask:0xf
	v_fmac_f32_dpp v131, -v149, v127 row_newbcast:13 row_mask:0xf bank_mask:0xf
	v_cndmask_b32_e64 v134, 0, 1.0, vcc
	v_mov_b32_e32 v135, v18
	v_mov_b32_e32 v136, v18
	v_mov_b32_e32 v137, v18
	v_add_f32_e32 v2, v130, v131
	v_add_f32_e32 v3, v132, v133
	v_add_f32_e32 v98, v2, v3
	ds_read_b32 v148, v138 offset:5856
	ds_read_b32 v149, v138 offset:5920
	ds_read_b32 v150, v138 offset:5984
	s_waitcnt lgkmcnt(6)
	v_cmp_eq_u32_e32 vcc, 30, v1
	v_fmac_f32_dpp v135, -v144, v99 row_newbcast:1 row_mask:0xf bank_mask:0xf
	v_fmac_f32_dpp v136, -v144, v100 row_newbcast:2 row_mask:0xf bank_mask:0xf
	v_fmac_f32_dpp v137, -v144, v101 row_newbcast:3 row_mask:0xf bank_mask:0xf
	v_fmac_f32_dpp v134, -v144, v98 row_newbcast:0 row_mask:0xf bank_mask:0xf
	v_fmac_f32_dpp v135, -v144, v103 row_newbcast:5 row_mask:0xf bank_mask:0xf
	v_fmac_f32_dpp v136, -v144, v104 row_newbcast:6 row_mask:0xf bank_mask:0xf
	v_fmac_f32_dpp v137, -v144, v105 row_newbcast:7 row_mask:0xf bank_mask:0xf
	v_fmac_f32_dpp v134, -v144, v102 row_newbcast:4 row_mask:0xf bank_mask:0xf
	v_fmac_f32_dpp v135, -v144, v107 row_newbcast:9 row_mask:0xf bank_mask:0xf
	v_fmac_f32_dpp v136, -v144, v108 row_newbcast:10 row_mask:0xf bank_mask:0xf
	v_fmac_f32_dpp v137, -v144, v109 row_newbcast:11 row_mask:0xf bank_mask:0xf
	v_fmac_f32_dpp v134, -v144, v106 row_newbcast:8 row_mask:0xf bank_mask:0xf
	v_fmac_f32_dpp v135, -v144, v111 row_newbcast:13 row_mask:0xf bank_mask:0xf
	v_fmac_f32_dpp v136, -v144, v112 row_newbcast:14 row_mask:0xf bank_mask:0xf
	v_fmac_f32_dpp v137, -v144, v113 row_newbcast:15 row_mask:0xf bank_mask:0xf
	v_fmac_f32_dpp v134, -v144, v110 row_newbcast:12 row_mask:0xf bank_mask:0xf
	v_fmac_f32_dpp v135, -v145, v115 row_newbcast:1 row_mask:0xf bank_mask:0xf
	v_fmac_f32_dpp v136, -v145, v116 row_newbcast:2 row_mask:0xf bank_mask:0xf
	v_fmac_f32_dpp v137, -v145, v117 row_newbcast:3 row_mask:0xf bank_mask:0xf
	v_fmac_f32_dpp v134, -v145, v114 row_newbcast:0 row_mask:0xf bank_mask:0xf
	v_fmac_f32_dpp v135, -v145, v119 row_newbcast:5 row_mask:0xf bank_mask:0xf
	v_fmac_f32_dpp v136, -v145, v120 row_newbcast:6 row_mask:0xf bank_mask:0xf
	v_fmac_f32_dpp v137, -v145, v121 row_newbcast:7 row_mask:0xf bank_mask:0xf
	v_fmac_f32_dpp v134, -v145, v118 row_newbcast:4 row_mask:0xf bank_mask:0xf
	v_fmac_f32_dpp v135, -v145, v123 row_newbcast:9 row_mask:0xf bank_mask:0xf
	v_fmac_f32_dpp v136, -v145, v124 row_newbcast:10 row_mask:0xf bank_mask:0xf
	v_fmac_f32_dpp v137, -v145, v125 row_newbcast:11 row_mask:0xf bank_mask:0xf
	v_fmac_f32_dpp v134, -v145, v122 row_newbcast:8 row_mask:0xf bank_mask:0xf
	v_fmac_f32_dpp v135, -v145, v127 row_newbcast:13 row_mask:0xf bank_mask:0xf
	v_fmac_f32_dpp v136, -v145, v128 row_newbcast:14 row_mask:0xf bank_mask:0xf
	v_fmac_f32_dpp v137, -v145, v129 row_newbcast:15 row_mask:0xf bank_mask:0xf
	v_fmac_f32_dpp v134, -v145, v126 row_newbcast:12 row_mask:0xf bank_mask:0xf
	v_cndmask_b32_e64 v130, 0, 1.0, vcc
	v_mov_b32_e32 v131, v18
	v_mov_b32_e32 v132, v18
	v_mov_b32_e32 v133, v18
	v_add_f32_e32 v2, v134, v135
	v_add_f32_e32 v3, v136, v137
	v_add_f32_e32 v97, v2, v3
	ds_read_b32 v144, v138 offset:5712
	ds_read_b32 v145, v138 offset:5776
	ds_read_b32 v146, v138 offset:5840
	s_waitcnt lgkmcnt(6)
	v_cmp_eq_u32_e32 vcc, 29, v1
	v_fmac_f32_dpp v130, -v140, v98 row_newbcast:4 row_mask:0xf bank_mask:0xf
	v_fmac_f32_dpp v131, -v140, v99 row_newbcast:5 row_mask:0xf bank_mask:0xf
	v_fmac_f32_dpp v132, -v140, v100 row_newbcast:6 row_mask:0xf bank_mask:0xf
	v_fmac_f32_dpp v133, -v140, v97 row_newbcast:3 row_mask:0xf bank_mask:0xf
	v_fmac_f32_dpp v130, -v140, v102 row_newbcast:8 row_mask:0xf bank_mask:0xf
	v_fmac_f32_dpp v131, -v140, v103 row_newbcast:9 row_mask:0xf bank_mask:0xf
	v_fmac_f32_dpp v132, -v140, v104 row_newbcast:10 row_mask:0xf bank_mask:0xf
	v_fmac_f32_dpp v133, -v140, v101 row_newbcast:7 row_mask:0xf bank_mask:0xf
	v_fmac_f32_dpp v130, -v140, v106 row_newbcast:12 row_mask:0xf bank_mask:0xf
	v_fmac_f32_dpp v131, -v140, v107 row_newbcast:13 row_mask:0xf bank_mask:0xf
	v_fmac_f32_dpp v132, -v140, v108 row_newbcast:14 row_mask:0xf bank_mask:0xf
	v_fmac_f32_dpp v133, -v140, v105 row_newbcast:11 row_mask:0xf bank_mask:0xf
	v_fmac_f32_dpp v130, -v141, v110 row_newbcast:0 row_mask:0xf bank_mask:0xf
	v_fmac_f32_dpp v131, -v141, v111 row_newbcast:1 row_mask:0xf bank_mask:0xf
	v_fmac_f32_dpp v132, -v141, v112 row_newbcast:2 row_mask:0xf bank_mask:0xf
	v_fmac_f32_dpp v133, -v140, v109 row_newbcast:15 row_mask:0xf bank_mask:0xf
	v_fmac_f32_dpp v130, -v141, v114 row_newbcast:4 row_mask:0xf bank_mask:0xf
	v_fmac_f32_dpp v131, -v141, v115 row_newbcast:5 row_mask:0xf bank_mask:0xf
	v_fmac_f32_dpp v132, -v141, v116 row_newbcast:6 row_mask:0xf bank_mask:0xf
	v_fmac_f32_dpp v133, -v141, v113 row_newbcast:3 row_mask:0xf bank_mask:0xf
	v_fmac_f32_dpp v130, -v141, v118 row_newbcast:8 row_mask:0xf bank_mask:0xf
	v_fmac_f32_dpp v131, -v141, v119 row_newbcast:9 row_mask:0xf bank_mask:0xf
	v_fmac_f32_dpp v132, -v141, v120 row_newbcast:10 row_mask:0xf bank_mask:0xf
	v_fmac_f32_dpp v133, -v141, v117 row_newbcast:7 row_mask:0xf bank_mask:0xf
	v_fmac_f32_dpp v130, -v141, v122 row_newbcast:12 row_mask:0xf bank_mask:0xf
	v_fmac_f32_dpp v131, -v141, v123 row_newbcast:13 row_mask:0xf bank_mask:0xf
	v_fmac_f32_dpp v132, -v141, v124 row_newbcast:14 row_mask:0xf bank_mask:0xf
	v_fmac_f32_dpp v133, -v141, v121 row_newbcast:11 row_mask:0xf bank_mask:0xf
	v_fmac_f32_dpp v130, -v142, v126 row_newbcast:0 row_mask:0xf bank_mask:0xf
	v_fmac_f32_dpp v131, -v142, v127 row_newbcast:1 row_mask:0xf bank_mask:0xf
	v_fmac_f32_dpp v132, -v142, v128 row_newbcast:2 row_mask:0xf bank_mask:0xf
	v_fmac_f32_dpp v133, -v141, v125 row_newbcast:15 row_mask:0xf bank_mask:0xf
	s_nop 1
	v_fmac_f32_dpp v133, -v142, v129 row_newbcast:3 row_mask:0xf bank_mask:0xf
	v_cndmask_b32_e64 v134, 0, 1.0, vcc
	v_mov_b32_e32 v135, v18
	v_mov_b32_e32 v136, v18
	v_mov_b32_e32 v137, v18
	v_add_f32_e32 v2, v130, v131
	v_add_f32_e32 v3, v132, v133
	v_add_f32_e32 v96, v2, v3
	ds_read_b32 v140, v138 offset:5568
	ds_read_b32 v141, v138 offset:5632
	ds_read_b32 v142, v138 offset:5696
	s_waitcnt lgkmcnt(6)
	v_cmp_eq_u32_e32 vcc, 28, v1
	v_fmac_f32_dpp v137, -v148, v97 row_newbcast:3 row_mask:0xf bank_mask:0xf
	v_fmac_f32_dpp v134, -v148, v98 row_newbcast:4 row_mask:0xf bank_mask:0xf
	v_fmac_f32_dpp v135, -v148, v99 row_newbcast:5 row_mask:0xf bank_mask:0xf
	v_fmac_f32_dpp v136, -v148, v96 row_newbcast:2 row_mask:0xf bank_mask:0xf
	v_fmac_f32_dpp v137, -v148, v101 row_newbcast:7 row_mask:0xf bank_mask:0xf
	v_fmac_f32_dpp v134, -v148, v102 row_newbcast:8 row_mask:0xf bank_mask:0xf
	v_fmac_f32_dpp v135, -v148, v103 row_newbcast:9 row_mask:0xf bank_mask:0xf
	v_fmac_f32_dpp v136, -v148, v100 row_newbcast:6 row_mask:0xf bank_mask:0xf
	v_fmac_f32_dpp v137, -v148, v105 row_newbcast:11 row_mask:0xf bank_mask:0xf
	v_fmac_f32_dpp v134, -v148, v106 row_newbcast:12 row_mask:0xf bank_mask:0xf
	v_fmac_f32_dpp v135, -v148, v107 row_newbcast:13 row_mask:0xf bank_mask:0xf
	v_fmac_f32_dpp v136, -v148, v104 row_newbcast:10 row_mask:0xf bank_mask:0xf
	v_fmac_f32_dpp v137, -v148, v109 row_newbcast:15 row_mask:0xf bank_mask:0xf
	v_fmac_f32_dpp v134, -v149, v110 row_newbcast:0 row_mask:0xf bank_mask:0xf
	v_fmac_f32_dpp v135, -v149, v111 row_newbcast:1 row_mask:0xf bank_mask:0xf
	v_fmac_f32_dpp v136, -v148, v108 row_newbcast:14 row_mask:0xf bank_mask:0xf
	v_fmac_f32_dpp v137, -v149, v113 row_newbcast:3 row_mask:0xf bank_mask:0xf
	v_fmac_f32_dpp v134, -v149, v114 row_newbcast:4 row_mask:0xf bank_mask:0xf
	v_fmac_f32_dpp v135, -v149, v115 row_newbcast:5 row_mask:0xf bank_mask:0xf
	v_fmac_f32_dpp v136, -v149, v112 row_newbcast:2 row_mask:0xf bank_mask:0xf
	v_fmac_f32_dpp v137, -v149, v117 row_newbcast:7 row_mask:0xf bank_mask:0xf
	v_fmac_f32_dpp v134, -v149, v118 row_newbcast:8 row_mask:0xf bank_mask:0xf
	v_fmac_f32_dpp v135, -v149, v119 row_newbcast:9 row_mask:0xf bank_mask:0xf
	v_fmac_f32_dpp v136, -v149, v116 row_newbcast:6 row_mask:0xf bank_mask:0xf
	v_fmac_f32_dpp v137, -v149, v121 row_newbcast:11 row_mask:0xf bank_mask:0xf
	v_fmac_f32_dpp v134, -v149, v122 row_newbcast:12 row_mask:0xf bank_mask:0xf
	v_fmac_f32_dpp v135, -v149, v123 row_newbcast:13 row_mask:0xf bank_mask:0xf
	v_fmac_f32_dpp v136, -v149, v120 row_newbcast:10 row_mask:0xf bank_mask:0xf
	v_fmac_f32_dpp v137, -v149, v125 row_newbcast:15 row_mask:0xf bank_mask:0xf
	v_fmac_f32_dpp v134, -v150, v126 row_newbcast:0 row_mask:0xf bank_mask:0xf
	v_fmac_f32_dpp v135, -v150, v127 row_newbcast:1 row_mask:0xf bank_mask:0xf
	v_fmac_f32_dpp v136, -v149, v124 row_newbcast:14 row_mask:0xf bank_mask:0xf
	v_fmac_f32_dpp v137, -v150, v129 row_newbcast:3 row_mask:0xf bank_mask:0xf
	s_nop 0
	v_fmac_f32_dpp v136, -v150, v128 row_newbcast:2 row_mask:0xf bank_mask:0xf
	v_cndmask_b32_e64 v130, 0, 1.0, vcc
	v_mov_b32_e32 v131, v18
	v_mov_b32_e32 v132, v18
	v_mov_b32_e32 v133, v18
	v_add_f32_e32 v2, v134, v135
	v_add_f32_e32 v3, v136, v137
	v_add_f32_e32 v95, v2, v3
	ds_read_b32 v148, v138 offset:5408
	ds_read_b32 v149, v138 offset:5472
	ds_read_b32 v150, v138 offset:5536
	s_waitcnt lgkmcnt(6)
	v_cmp_eq_u32_e32 vcc, 27, v1
	v_fmac_f32_dpp v132, -v144, v96 row_newbcast:2 row_mask:0xf bank_mask:0xf
	v_fmac_f32_dpp v133, -v144, v97 row_newbcast:3 row_mask:0xf bank_mask:0xf
	v_fmac_f32_dpp v130, -v144, v98 row_newbcast:4 row_mask:0xf bank_mask:0xf
	v_fmac_f32_dpp v131, -v144, v95 row_newbcast:1 row_mask:0xf bank_mask:0xf
	v_fmac_f32_dpp v132, -v144, v100 row_newbcast:6 row_mask:0xf bank_mask:0xf
	v_fmac_f32_dpp v133, -v144, v101 row_newbcast:7 row_mask:0xf bank_mask:0xf
	v_fmac_f32_dpp v130, -v144, v102 row_newbcast:8 row_mask:0xf bank_mask:0xf
	v_fmac_f32_dpp v131, -v144, v99 row_newbcast:5 row_mask:0xf bank_mask:0xf
	v_fmac_f32_dpp v132, -v144, v104 row_newbcast:10 row_mask:0xf bank_mask:0xf
	v_fmac_f32_dpp v133, -v144, v105 row_newbcast:11 row_mask:0xf bank_mask:0xf
	v_fmac_f32_dpp v130, -v144, v106 row_newbcast:12 row_mask:0xf bank_mask:0xf
	v_fmac_f32_dpp v131, -v144, v103 row_newbcast:9 row_mask:0xf bank_mask:0xf
	v_fmac_f32_dpp v132, -v144, v108 row_newbcast:14 row_mask:0xf bank_mask:0xf
	v_fmac_f32_dpp v133, -v144, v109 row_newbcast:15 row_mask:0xf bank_mask:0xf
	v_fmac_f32_dpp v130, -v145, v110 row_newbcast:0 row_mask:0xf bank_mask:0xf
	v_fmac_f32_dpp v131, -v144, v107 row_newbcast:13 row_mask:0xf bank_mask:0xf
	v_fmac_f32_dpp v132, -v145, v112 row_newbcast:2 row_mask:0xf bank_mask:0xf
	v_fmac_f32_dpp v133, -v145, v113 row_newbcast:3 row_mask:0xf bank_mask:0xf
	v_fmac_f32_dpp v130, -v145, v114 row_newbcast:4 row_mask:0xf bank_mask:0xf
	v_fmac_f32_dpp v131, -v145, v111 row_newbcast:1 row_mask:0xf bank_mask:0xf
	v_fmac_f32_dpp v132, -v145, v116 row_newbcast:6 row_mask:0xf bank_mask:0xf
	v_fmac_f32_dpp v133, -v145, v117 row_newbcast:7 row_mask:0xf bank_mask:0xf
	v_fmac_f32_dpp v130, -v145, v118 row_newbcast:8 row_mask:0xf bank_mask:0xf
	v_fmac_f32_dpp v131, -v145, v115 row_newbcast:5 row_mask:0xf bank_mask:0xf
	v_fmac_f32_dpp v132, -v145, v120 row_newbcast:10 row_mask:0xf bank_mask:0xf
	v_fmac_f32_dpp v133, -v145, v121 row_newbcast:11 row_mask:0xf bank_mask:0xf
	v_fmac_f32_dpp v130, -v145, v122 row_newbcast:12 row_mask:0xf bank_mask:0xf
	v_fmac_f32_dpp v131, -v145, v119 row_newbcast:9 row_mask:0xf bank_mask:0xf
	v_fmac_f32_dpp v132, -v145, v124 row_newbcast:14 row_mask:0xf bank_mask:0xf
	v_fmac_f32_dpp v133, -v145, v125 row_newbcast:15 row_mask:0xf bank_mask:0xf
	v_fmac_f32_dpp v130, -v146, v126 row_newbcast:0 row_mask:0xf bank_mask:0xf
	v_fmac_f32_dpp v131, -v145, v123 row_newbcast:13 row_mask:0xf bank_mask:0xf
	v_fmac_f32_dpp v132, -v146, v128 row_newbcast:2 row_mask:0xf bank_mask:0xf
	v_fmac_f32_dpp v133, -v146, v129 row_newbcast:3 row_mask:0xf bank_mask:0xf
	v_fmac_f32_dpp v131, -v146, v127 row_newbcast:1 row_mask:0xf bank_mask:0xf
	v_cndmask_b32_e64 v134, 0, 1.0, vcc
	v_mov_b32_e32 v135, v18
	v_mov_b32_e32 v136, v18
	v_mov_b32_e32 v137, v18
	v_add_f32_e32 v2, v130, v131
	v_add_f32_e32 v3, v132, v133
	v_add_f32_e32 v94, v2, v3
	ds_read_b32 v144, v138 offset:5248
	ds_read_b32 v145, v138 offset:5312
	ds_read_b32 v146, v138 offset:5376
	s_waitcnt lgkmcnt(6)
	v_cmp_eq_u32_e32 vcc, 26, v1
	v_fmac_f32_dpp v135, -v140, v95 row_newbcast:1 row_mask:0xf bank_mask:0xf
	v_fmac_f32_dpp v136, -v140, v96 row_newbcast:2 row_mask:0xf bank_mask:0xf
	v_fmac_f32_dpp v137, -v140, v97 row_newbcast:3 row_mask:0xf bank_mask:0xf
	v_fmac_f32_dpp v134, -v140, v94 row_newbcast:0 row_mask:0xf bank_mask:0xf
	v_fmac_f32_dpp v135, -v140, v99 row_newbcast:5 row_mask:0xf bank_mask:0xf
	v_fmac_f32_dpp v136, -v140, v100 row_newbcast:6 row_mask:0xf bank_mask:0xf
	v_fmac_f32_dpp v137, -v140, v101 row_newbcast:7 row_mask:0xf bank_mask:0xf
	v_fmac_f32_dpp v134, -v140, v98 row_newbcast:4 row_mask:0xf bank_mask:0xf
	v_fmac_f32_dpp v135, -v140, v103 row_newbcast:9 row_mask:0xf bank_mask:0xf
	v_fmac_f32_dpp v136, -v140, v104 row_newbcast:10 row_mask:0xf bank_mask:0xf
	v_fmac_f32_dpp v137, -v140, v105 row_newbcast:11 row_mask:0xf bank_mask:0xf
	v_fmac_f32_dpp v134, -v140, v102 row_newbcast:8 row_mask:0xf bank_mask:0xf
	v_fmac_f32_dpp v135, -v140, v107 row_newbcast:13 row_mask:0xf bank_mask:0xf
	v_fmac_f32_dpp v136, -v140, v108 row_newbcast:14 row_mask:0xf bank_mask:0xf
	v_fmac_f32_dpp v137, -v140, v109 row_newbcast:15 row_mask:0xf bank_mask:0xf
	v_fmac_f32_dpp v134, -v140, v106 row_newbcast:12 row_mask:0xf bank_mask:0xf
	v_fmac_f32_dpp v135, -v141, v111 row_newbcast:1 row_mask:0xf bank_mask:0xf
	v_fmac_f32_dpp v136, -v141, v112 row_newbcast:2 row_mask:0xf bank_mask:0xf
	v_fmac_f32_dpp v137, -v141, v113 row_newbcast:3 row_mask:0xf bank_mask:0xf
	v_fmac_f32_dpp v134, -v141, v110 row_newbcast:0 row_mask:0xf bank_mask:0xf
	v_fmac_f32_dpp v135, -v141, v115 row_newbcast:5 row_mask:0xf bank_mask:0xf
	v_fmac_f32_dpp v136, -v141, v116 row_newbcast:6 row_mask:0xf bank_mask:0xf
	v_fmac_f32_dpp v137, -v141, v117 row_newbcast:7 row_mask:0xf bank_mask:0xf
	v_fmac_f32_dpp v134, -v141, v114 row_newbcast:4 row_mask:0xf bank_mask:0xf
	v_fmac_f32_dpp v135, -v141, v119 row_newbcast:9 row_mask:0xf bank_mask:0xf
	v_fmac_f32_dpp v136, -v141, v120 row_newbcast:10 row_mask:0xf bank_mask:0xf
	v_fmac_f32_dpp v137, -v141, v121 row_newbcast:11 row_mask:0xf bank_mask:0xf
	v_fmac_f32_dpp v134, -v141, v118 row_newbcast:8 row_mask:0xf bank_mask:0xf
	v_fmac_f32_dpp v135, -v141, v123 row_newbcast:13 row_mask:0xf bank_mask:0xf
	v_fmac_f32_dpp v136, -v141, v124 row_newbcast:14 row_mask:0xf bank_mask:0xf
	v_fmac_f32_dpp v137, -v141, v125 row_newbcast:15 row_mask:0xf bank_mask:0xf
	v_fmac_f32_dpp v134, -v141, v122 row_newbcast:12 row_mask:0xf bank_mask:0xf
	v_fmac_f32_dpp v135, -v142, v127 row_newbcast:1 row_mask:0xf bank_mask:0xf
	v_fmac_f32_dpp v136, -v142, v128 row_newbcast:2 row_mask:0xf bank_mask:0xf
	v_fmac_f32_dpp v137, -v142, v129 row_newbcast:3 row_mask:0xf bank_mask:0xf
	v_fmac_f32_dpp v134, -v142, v126 row_newbcast:0 row_mask:0xf bank_mask:0xf
	v_cndmask_b32_e64 v130, 0, 1.0, vcc
	v_mov_b32_e32 v131, v18
	v_mov_b32_e32 v132, v18
	v_mov_b32_e32 v133, v18
	v_add_f32_e32 v2, v134, v135
	v_add_f32_e32 v3, v136, v137
	v_add_f32_e32 v93, v2, v3
	ds_read_b32 v140, v138 offset:5088
	ds_read_b32 v141, v138 offset:5152
	ds_read_b32 v142, v138 offset:5216
	s_waitcnt lgkmcnt(6)
	v_cmp_eq_u32_e32 vcc, 25, v1
	v_fmac_f32_dpp v130, -v148, v94 row_newbcast:4 row_mask:0xf bank_mask:0xf
	v_fmac_f32_dpp v131, -v148, v95 row_newbcast:5 row_mask:0xf bank_mask:0xf
	v_fmac_f32_dpp v132, -v148, v96 row_newbcast:6 row_mask:0xf bank_mask:0xf
	v_fmac_f32_dpp v133, -v148, v93 row_newbcast:3 row_mask:0xf bank_mask:0xf
	v_fmac_f32_dpp v130, -v148, v98 row_newbcast:8 row_mask:0xf bank_mask:0xf
	v_fmac_f32_dpp v131, -v148, v99 row_newbcast:9 row_mask:0xf bank_mask:0xf
	v_fmac_f32_dpp v132, -v148, v100 row_newbcast:10 row_mask:0xf bank_mask:0xf
	v_fmac_f32_dpp v133, -v148, v97 row_newbcast:7 row_mask:0xf bank_mask:0xf
	v_fmac_f32_dpp v130, -v148, v102 row_newbcast:12 row_mask:0xf bank_mask:0xf
	v_fmac_f32_dpp v131, -v148, v103 row_newbcast:13 row_mask:0xf bank_mask:0xf
	v_fmac_f32_dpp v132, -v148, v104 row_newbcast:14 row_mask:0xf bank_mask:0xf
	v_fmac_f32_dpp v133, -v148, v101 row_newbcast:11 row_mask:0xf bank_mask:0xf
	v_fmac_f32_dpp v130, -v149, v106 row_newbcast:0 row_mask:0xf bank_mask:0xf
	v_fmac_f32_dpp v131, -v149, v107 row_newbcast:1 row_mask:0xf bank_mask:0xf
	v_fmac_f32_dpp v132, -v149, v108 row_newbcast:2 row_mask:0xf bank_mask:0xf
	v_fmac_f32_dpp v133, -v148, v105 row_newbcast:15 row_mask:0xf bank_mask:0xf
	v_fmac_f32_dpp v130, -v149, v110 row_newbcast:4 row_mask:0xf bank_mask:0xf
	v_fmac_f32_dpp v131, -v149, v111 row_newbcast:5 row_mask:0xf bank_mask:0xf
	v_fmac_f32_dpp v132, -v149, v112 row_newbcast:6 row_mask:0xf bank_mask:0xf
	v_fmac_f32_dpp v133, -v149, v109 row_newbcast:3 row_mask:0xf bank_mask:0xf
	v_fmac_f32_dpp v130, -v149, v114 row_newbcast:8 row_mask:0xf bank_mask:0xf
	v_fmac_f32_dpp v131, -v149, v115 row_newbcast:9 row_mask:0xf bank_mask:0xf
	v_fmac_f32_dpp v132, -v149, v116 row_newbcast:10 row_mask:0xf bank_mask:0xf
	v_fmac_f32_dpp v133, -v149, v113 row_newbcast:7 row_mask:0xf bank_mask:0xf
	v_fmac_f32_dpp v130, -v149, v118 row_newbcast:12 row_mask:0xf bank_mask:0xf
	v_fmac_f32_dpp v131, -v149, v119 row_newbcast:13 row_mask:0xf bank_mask:0xf
	v_fmac_f32_dpp v132, -v149, v120 row_newbcast:14 row_mask:0xf bank_mask:0xf
	v_fmac_f32_dpp v133, -v149, v117 row_newbcast:11 row_mask:0xf bank_mask:0xf
	v_fmac_f32_dpp v130, -v150, v122 row_newbcast:0 row_mask:0xf bank_mask:0xf
	v_fmac_f32_dpp v131, -v150, v123 row_newbcast:1 row_mask:0xf bank_mask:0xf
	v_fmac_f32_dpp v132, -v150, v124 row_newbcast:2 row_mask:0xf bank_mask:0xf
	v_fmac_f32_dpp v133, -v149, v121 row_newbcast:15 row_mask:0xf bank_mask:0xf
	v_fmac_f32_dpp v130, -v150, v126 row_newbcast:4 row_mask:0xf bank_mask:0xf
	v_fmac_f32_dpp v131, -v150, v127 row_newbcast:5 row_mask:0xf bank_mask:0xf
	v_fmac_f32_dpp v132, -v150, v128 row_newbcast:6 row_mask:0xf bank_mask:0xf
	v_fmac_f32_dpp v133, -v150, v125 row_newbcast:3 row_mask:0xf bank_mask:0xf
	s_nop 1
	v_fmac_f32_dpp v133, -v150, v129 row_newbcast:7 row_mask:0xf bank_mask:0xf
	v_cndmask_b32_e64 v134, 0, 1.0, vcc
	v_mov_b32_e32 v135, v18
	v_mov_b32_e32 v136, v18
	v_mov_b32_e32 v137, v18
	v_add_f32_e32 v2, v130, v131
	v_add_f32_e32 v3, v132, v133
	v_add_f32_e32 v92, v2, v3
	ds_read_b32 v148, v138 offset:4928
	ds_read_b32 v149, v138 offset:4992
	ds_read_b32 v150, v138 offset:5056
	s_waitcnt lgkmcnt(6)
	v_cmp_eq_u32_e32 vcc, 24, v1
	v_fmac_f32_dpp v137, -v144, v93 row_newbcast:3 row_mask:0xf bank_mask:0xf
	v_fmac_f32_dpp v134, -v144, v94 row_newbcast:4 row_mask:0xf bank_mask:0xf
	v_fmac_f32_dpp v135, -v144, v95 row_newbcast:5 row_mask:0xf bank_mask:0xf
	v_fmac_f32_dpp v136, -v144, v92 row_newbcast:2 row_mask:0xf bank_mask:0xf
	v_fmac_f32_dpp v137, -v144, v97 row_newbcast:7 row_mask:0xf bank_mask:0xf
	v_fmac_f32_dpp v134, -v144, v98 row_newbcast:8 row_mask:0xf bank_mask:0xf
	v_fmac_f32_dpp v135, -v144, v99 row_newbcast:9 row_mask:0xf bank_mask:0xf
	v_fmac_f32_dpp v136, -v144, v96 row_newbcast:6 row_mask:0xf bank_mask:0xf
	v_fmac_f32_dpp v137, -v144, v101 row_newbcast:11 row_mask:0xf bank_mask:0xf
	v_fmac_f32_dpp v134, -v144, v102 row_newbcast:12 row_mask:0xf bank_mask:0xf
	v_fmac_f32_dpp v135, -v144, v103 row_newbcast:13 row_mask:0xf bank_mask:0xf
	v_fmac_f32_dpp v136, -v144, v100 row_newbcast:10 row_mask:0xf bank_mask:0xf
	v_fmac_f32_dpp v137, -v144, v105 row_newbcast:15 row_mask:0xf bank_mask:0xf
	v_fmac_f32_dpp v134, -v145, v106 row_newbcast:0 row_mask:0xf bank_mask:0xf
	v_fmac_f32_dpp v135, -v145, v107 row_newbcast:1 row_mask:0xf bank_mask:0xf
	v_fmac_f32_dpp v136, -v144, v104 row_newbcast:14 row_mask:0xf bank_mask:0xf
	v_fmac_f32_dpp v137, -v145, v109 row_newbcast:3 row_mask:0xf bank_mask:0xf
	v_fmac_f32_dpp v134, -v145, v110 row_newbcast:4 row_mask:0xf bank_mask:0xf
	v_fmac_f32_dpp v135, -v145, v111 row_newbcast:5 row_mask:0xf bank_mask:0xf
	v_fmac_f32_dpp v136, -v145, v108 row_newbcast:2 row_mask:0xf bank_mask:0xf
	v_fmac_f32_dpp v137, -v145, v113 row_newbcast:7 row_mask:0xf bank_mask:0xf
	v_fmac_f32_dpp v134, -v145, v114 row_newbcast:8 row_mask:0xf bank_mask:0xf
	v_fmac_f32_dpp v135, -v145, v115 row_newbcast:9 row_mask:0xf bank_mask:0xf
	v_fmac_f32_dpp v136, -v145, v112 row_newbcast:6 row_mask:0xf bank_mask:0xf
	v_fmac_f32_dpp v137, -v145, v117 row_newbcast:11 row_mask:0xf bank_mask:0xf
	v_fmac_f32_dpp v134, -v145, v118 row_newbcast:12 row_mask:0xf bank_mask:0xf
	v_fmac_f32_dpp v135, -v145, v119 row_newbcast:13 row_mask:0xf bank_mask:0xf
	v_fmac_f32_dpp v136, -v145, v116 row_newbcast:10 row_mask:0xf bank_mask:0xf
	v_fmac_f32_dpp v137, -v145, v121 row_newbcast:15 row_mask:0xf bank_mask:0xf
	v_fmac_f32_dpp v134, -v146, v122 row_newbcast:0 row_mask:0xf bank_mask:0xf
	v_fmac_f32_dpp v135, -v146, v123 row_newbcast:1 row_mask:0xf bank_mask:0xf
	v_fmac_f32_dpp v136, -v145, v120 row_newbcast:14 row_mask:0xf bank_mask:0xf
	v_fmac_f32_dpp v137, -v146, v125 row_newbcast:3 row_mask:0xf bank_mask:0xf
	v_fmac_f32_dpp v134, -v146, v126 row_newbcast:4 row_mask:0xf bank_mask:0xf
	v_fmac_f32_dpp v135, -v146, v127 row_newbcast:5 row_mask:0xf bank_mask:0xf
	v_fmac_f32_dpp v136, -v146, v124 row_newbcast:2 row_mask:0xf bank_mask:0xf
	v_fmac_f32_dpp v137, -v146, v129 row_newbcast:7 row_mask:0xf bank_mask:0xf
	s_nop 0
	v_fmac_f32_dpp v136, -v146, v128 row_newbcast:6 row_mask:0xf bank_mask:0xf
	v_cndmask_b32_e64 v130, 0, 1.0, vcc
	v_mov_b32_e32 v131, v18
	v_mov_b32_e32 v132, v18
	v_mov_b32_e32 v133, v18
	v_add_f32_e32 v2, v134, v135
	v_add_f32_e32 v3, v136, v137
	v_add_f32_e32 v91, v2, v3
	ds_read_b32 v144, v138 offset:4752
	ds_read_b32 v145, v138 offset:4816
	ds_read_b32 v146, v138 offset:4880
	s_waitcnt lgkmcnt(6)
	v_cmp_eq_u32_e32 vcc, 23, v1
	v_fmac_f32_dpp v132, -v140, v92 row_newbcast:2 row_mask:0xf bank_mask:0xf
	v_fmac_f32_dpp v133, -v140, v93 row_newbcast:3 row_mask:0xf bank_mask:0xf
	v_fmac_f32_dpp v130, -v140, v94 row_newbcast:4 row_mask:0xf bank_mask:0xf
	v_fmac_f32_dpp v131, -v140, v91 row_newbcast:1 row_mask:0xf bank_mask:0xf
	v_fmac_f32_dpp v132, -v140, v96 row_newbcast:6 row_mask:0xf bank_mask:0xf
	v_fmac_f32_dpp v133, -v140, v97 row_newbcast:7 row_mask:0xf bank_mask:0xf
	v_fmac_f32_dpp v130, -v140, v98 row_newbcast:8 row_mask:0xf bank_mask:0xf
	v_fmac_f32_dpp v131, -v140, v95 row_newbcast:5 row_mask:0xf bank_mask:0xf
	v_fmac_f32_dpp v132, -v140, v100 row_newbcast:10 row_mask:0xf bank_mask:0xf
	v_fmac_f32_dpp v133, -v140, v101 row_newbcast:11 row_mask:0xf bank_mask:0xf
	v_fmac_f32_dpp v130, -v140, v102 row_newbcast:12 row_mask:0xf bank_mask:0xf
	v_fmac_f32_dpp v131, -v140, v99 row_newbcast:9 row_mask:0xf bank_mask:0xf
	v_fmac_f32_dpp v132, -v140, v104 row_newbcast:14 row_mask:0xf bank_mask:0xf
	v_fmac_f32_dpp v133, -v140, v105 row_newbcast:15 row_mask:0xf bank_mask:0xf
	v_fmac_f32_dpp v130, -v141, v106 row_newbcast:0 row_mask:0xf bank_mask:0xf
	v_fmac_f32_dpp v131, -v140, v103 row_newbcast:13 row_mask:0xf bank_mask:0xf
	v_fmac_f32_dpp v132, -v141, v108 row_newbcast:2 row_mask:0xf bank_mask:0xf
	v_fmac_f32_dpp v133, -v141, v109 row_newbcast:3 row_mask:0xf bank_mask:0xf
	v_fmac_f32_dpp v130, -v141, v110 row_newbcast:4 row_mask:0xf bank_mask:0xf
	v_fmac_f32_dpp v131, -v141, v107 row_newbcast:1 row_mask:0xf bank_mask:0xf
	v_fmac_f32_dpp v132, -v141, v112 row_newbcast:6 row_mask:0xf bank_mask:0xf
	v_fmac_f32_dpp v133, -v141, v113 row_newbcast:7 row_mask:0xf bank_mask:0xf
	v_fmac_f32_dpp v130, -v141, v114 row_newbcast:8 row_mask:0xf bank_mask:0xf
	v_fmac_f32_dpp v131, -v141, v111 row_newbcast:5 row_mask:0xf bank_mask:0xf
	v_fmac_f32_dpp v132, -v141, v116 row_newbcast:10 row_mask:0xf bank_mask:0xf
	v_fmac_f32_dpp v133, -v141, v117 row_newbcast:11 row_mask:0xf bank_mask:0xf
	v_fmac_f32_dpp v130, -v141, v118 row_newbcast:12 row_mask:0xf bank_mask:0xf
	v_fmac_f32_dpp v131, -v141, v115 row_newbcast:9 row_mask:0xf bank_mask:0xf
	v_fmac_f32_dpp v132, -v141, v120 row_newbcast:14 row_mask:0xf bank_mask:0xf
	v_fmac_f32_dpp v133, -v141, v121 row_newbcast:15 row_mask:0xf bank_mask:0xf
	v_fmac_f32_dpp v130, -v142, v122 row_newbcast:0 row_mask:0xf bank_mask:0xf
	v_fmac_f32_dpp v131, -v141, v119 row_newbcast:13 row_mask:0xf bank_mask:0xf
	v_fmac_f32_dpp v132, -v142, v124 row_newbcast:2 row_mask:0xf bank_mask:0xf
	v_fmac_f32_dpp v133, -v142, v125 row_newbcast:3 row_mask:0xf bank_mask:0xf
	v_fmac_f32_dpp v130, -v142, v126 row_newbcast:4 row_mask:0xf bank_mask:0xf
	v_fmac_f32_dpp v131, -v142, v123 row_newbcast:1 row_mask:0xf bank_mask:0xf
	v_fmac_f32_dpp v132, -v142, v128 row_newbcast:6 row_mask:0xf bank_mask:0xf
	v_fmac_f32_dpp v133, -v142, v129 row_newbcast:7 row_mask:0xf bank_mask:0xf
	v_fmac_f32_dpp v131, -v142, v127 row_newbcast:5 row_mask:0xf bank_mask:0xf
	v_cndmask_b32_e64 v134, 0, 1.0, vcc
	v_mov_b32_e32 v135, v18
	v_mov_b32_e32 v136, v18
	v_mov_b32_e32 v137, v18
	v_add_f32_e32 v2, v130, v131
	v_add_f32_e32 v3, v132, v133
	v_add_f32_e32 v90, v2, v3
	ds_read_b32 v140, v138 offset:4576
	ds_read_b32 v141, v138 offset:4640
	ds_read_b32 v142, v138 offset:4704
	s_waitcnt lgkmcnt(6)
	v_cmp_eq_u32_e32 vcc, 22, v1
	v_fmac_f32_dpp v135, -v148, v91 row_newbcast:1 row_mask:0xf bank_mask:0xf
	v_fmac_f32_dpp v136, -v148, v92 row_newbcast:2 row_mask:0xf bank_mask:0xf
	v_fmac_f32_dpp v137, -v148, v93 row_newbcast:3 row_mask:0xf bank_mask:0xf
	v_fmac_f32_dpp v134, -v148, v90 row_newbcast:0 row_mask:0xf bank_mask:0xf
	v_fmac_f32_dpp v135, -v148, v95 row_newbcast:5 row_mask:0xf bank_mask:0xf
	v_fmac_f32_dpp v136, -v148, v96 row_newbcast:6 row_mask:0xf bank_mask:0xf
	v_fmac_f32_dpp v137, -v148, v97 row_newbcast:7 row_mask:0xf bank_mask:0xf
	v_fmac_f32_dpp v134, -v148, v94 row_newbcast:4 row_mask:0xf bank_mask:0xf
	v_fmac_f32_dpp v135, -v148, v99 row_newbcast:9 row_mask:0xf bank_mask:0xf
	v_fmac_f32_dpp v136, -v148, v100 row_newbcast:10 row_mask:0xf bank_mask:0xf
	v_fmac_f32_dpp v137, -v148, v101 row_newbcast:11 row_mask:0xf bank_mask:0xf
	v_fmac_f32_dpp v134, -v148, v98 row_newbcast:8 row_mask:0xf bank_mask:0xf
	v_fmac_f32_dpp v135, -v148, v103 row_newbcast:13 row_mask:0xf bank_mask:0xf
	v_fmac_f32_dpp v136, -v148, v104 row_newbcast:14 row_mask:0xf bank_mask:0xf
	v_fmac_f32_dpp v137, -v148, v105 row_newbcast:15 row_mask:0xf bank_mask:0xf
	v_fmac_f32_dpp v134, -v148, v102 row_newbcast:12 row_mask:0xf bank_mask:0xf
	v_fmac_f32_dpp v135, -v149, v107 row_newbcast:1 row_mask:0xf bank_mask:0xf
	v_fmac_f32_dpp v136, -v149, v108 row_newbcast:2 row_mask:0xf bank_mask:0xf
	v_fmac_f32_dpp v137, -v149, v109 row_newbcast:3 row_mask:0xf bank_mask:0xf
	v_fmac_f32_dpp v134, -v149, v106 row_newbcast:0 row_mask:0xf bank_mask:0xf
	v_fmac_f32_dpp v135, -v149, v111 row_newbcast:5 row_mask:0xf bank_mask:0xf
	v_fmac_f32_dpp v136, -v149, v112 row_newbcast:6 row_mask:0xf bank_mask:0xf
	v_fmac_f32_dpp v137, -v149, v113 row_newbcast:7 row_mask:0xf bank_mask:0xf
	v_fmac_f32_dpp v134, -v149, v110 row_newbcast:4 row_mask:0xf bank_mask:0xf
	v_fmac_f32_dpp v135, -v149, v115 row_newbcast:9 row_mask:0xf bank_mask:0xf
	v_fmac_f32_dpp v136, -v149, v116 row_newbcast:10 row_mask:0xf bank_mask:0xf
	v_fmac_f32_dpp v137, -v149, v117 row_newbcast:11 row_mask:0xf bank_mask:0xf
	v_fmac_f32_dpp v134, -v149, v114 row_newbcast:8 row_mask:0xf bank_mask:0xf
	v_fmac_f32_dpp v135, -v149, v119 row_newbcast:13 row_mask:0xf bank_mask:0xf
	v_fmac_f32_dpp v136, -v149, v120 row_newbcast:14 row_mask:0xf bank_mask:0xf
	v_fmac_f32_dpp v137, -v149, v121 row_newbcast:15 row_mask:0xf bank_mask:0xf
	v_fmac_f32_dpp v134, -v149, v118 row_newbcast:12 row_mask:0xf bank_mask:0xf
	v_fmac_f32_dpp v135, -v150, v123 row_newbcast:1 row_mask:0xf bank_mask:0xf
	v_fmac_f32_dpp v136, -v150, v124 row_newbcast:2 row_mask:0xf bank_mask:0xf
	v_fmac_f32_dpp v137, -v150, v125 row_newbcast:3 row_mask:0xf bank_mask:0xf
	v_fmac_f32_dpp v134, -v150, v122 row_newbcast:0 row_mask:0xf bank_mask:0xf
	v_fmac_f32_dpp v135, -v150, v127 row_newbcast:5 row_mask:0xf bank_mask:0xf
	v_fmac_f32_dpp v136, -v150, v128 row_newbcast:6 row_mask:0xf bank_mask:0xf
	v_fmac_f32_dpp v137, -v150, v129 row_newbcast:7 row_mask:0xf bank_mask:0xf
	v_fmac_f32_dpp v134, -v150, v126 row_newbcast:4 row_mask:0xf bank_mask:0xf
	v_cndmask_b32_e64 v130, 0, 1.0, vcc
	v_mov_b32_e32 v131, v18
	v_mov_b32_e32 v132, v18
	v_mov_b32_e32 v133, v18
	v_add_f32_e32 v2, v134, v135
	v_add_f32_e32 v3, v136, v137
	v_add_f32_e32 v89, v2, v3
	ds_read_b32 v148, v138 offset:4400
	ds_read_b32 v149, v138 offset:4464
	ds_read_b32 v150, v138 offset:4528
	s_waitcnt lgkmcnt(6)
	v_cmp_eq_u32_e32 vcc, 21, v1
	v_fmac_f32_dpp v130, -v144, v90 row_newbcast:4 row_mask:0xf bank_mask:0xf
	v_fmac_f32_dpp v131, -v144, v91 row_newbcast:5 row_mask:0xf bank_mask:0xf
	v_fmac_f32_dpp v132, -v144, v92 row_newbcast:6 row_mask:0xf bank_mask:0xf
	v_fmac_f32_dpp v133, -v144, v89 row_newbcast:3 row_mask:0xf bank_mask:0xf
	v_fmac_f32_dpp v130, -v144, v94 row_newbcast:8 row_mask:0xf bank_mask:0xf
	v_fmac_f32_dpp v131, -v144, v95 row_newbcast:9 row_mask:0xf bank_mask:0xf
	v_fmac_f32_dpp v132, -v144, v96 row_newbcast:10 row_mask:0xf bank_mask:0xf
	v_fmac_f32_dpp v133, -v144, v93 row_newbcast:7 row_mask:0xf bank_mask:0xf
	v_fmac_f32_dpp v130, -v144, v98 row_newbcast:12 row_mask:0xf bank_mask:0xf
	v_fmac_f32_dpp v131, -v144, v99 row_newbcast:13 row_mask:0xf bank_mask:0xf
	v_fmac_f32_dpp v132, -v144, v100 row_newbcast:14 row_mask:0xf bank_mask:0xf
	v_fmac_f32_dpp v133, -v144, v97 row_newbcast:11 row_mask:0xf bank_mask:0xf
	v_fmac_f32_dpp v130, -v145, v102 row_newbcast:0 row_mask:0xf bank_mask:0xf
	v_fmac_f32_dpp v131, -v145, v103 row_newbcast:1 row_mask:0xf bank_mask:0xf
	v_fmac_f32_dpp v132, -v145, v104 row_newbcast:2 row_mask:0xf bank_mask:0xf
	v_fmac_f32_dpp v133, -v144, v101 row_newbcast:15 row_mask:0xf bank_mask:0xf
	v_fmac_f32_dpp v130, -v145, v106 row_newbcast:4 row_mask:0xf bank_mask:0xf
	v_fmac_f32_dpp v131, -v145, v107 row_newbcast:5 row_mask:0xf bank_mask:0xf
	v_fmac_f32_dpp v132, -v145, v108 row_newbcast:6 row_mask:0xf bank_mask:0xf
	v_fmac_f32_dpp v133, -v145, v105 row_newbcast:3 row_mask:0xf bank_mask:0xf
	v_fmac_f32_dpp v130, -v145, v110 row_newbcast:8 row_mask:0xf bank_mask:0xf
	v_fmac_f32_dpp v131, -v145, v111 row_newbcast:9 row_mask:0xf bank_mask:0xf
	v_fmac_f32_dpp v132, -v145, v112 row_newbcast:10 row_mask:0xf bank_mask:0xf
	v_fmac_f32_dpp v133, -v145, v109 row_newbcast:7 row_mask:0xf bank_mask:0xf
	v_fmac_f32_dpp v130, -v145, v114 row_newbcast:12 row_mask:0xf bank_mask:0xf
	v_fmac_f32_dpp v131, -v145, v115 row_newbcast:13 row_mask:0xf bank_mask:0xf
	v_fmac_f32_dpp v132, -v145, v116 row_newbcast:14 row_mask:0xf bank_mask:0xf
	v_fmac_f32_dpp v133, -v145, v113 row_newbcast:11 row_mask:0xf bank_mask:0xf
	v_fmac_f32_dpp v130, -v146, v118 row_newbcast:0 row_mask:0xf bank_mask:0xf
	v_fmac_f32_dpp v131, -v146, v119 row_newbcast:1 row_mask:0xf bank_mask:0xf
	v_fmac_f32_dpp v132, -v146, v120 row_newbcast:2 row_mask:0xf bank_mask:0xf
	v_fmac_f32_dpp v133, -v145, v117 row_newbcast:15 row_mask:0xf bank_mask:0xf
	v_fmac_f32_dpp v130, -v146, v122 row_newbcast:4 row_mask:0xf bank_mask:0xf
	v_fmac_f32_dpp v131, -v146, v123 row_newbcast:5 row_mask:0xf bank_mask:0xf
	v_fmac_f32_dpp v132, -v146, v124 row_newbcast:6 row_mask:0xf bank_mask:0xf
	v_fmac_f32_dpp v133, -v146, v121 row_newbcast:3 row_mask:0xf bank_mask:0xf
	v_fmac_f32_dpp v130, -v146, v126 row_newbcast:8 row_mask:0xf bank_mask:0xf
	v_fmac_f32_dpp v131, -v146, v127 row_newbcast:9 row_mask:0xf bank_mask:0xf
	v_fmac_f32_dpp v132, -v146, v128 row_newbcast:10 row_mask:0xf bank_mask:0xf
	v_fmac_f32_dpp v133, -v146, v125 row_newbcast:7 row_mask:0xf bank_mask:0xf
	s_nop 1
	v_fmac_f32_dpp v133, -v146, v129 row_newbcast:11 row_mask:0xf bank_mask:0xf
	v_cndmask_b32_e64 v134, 0, 1.0, vcc
	v_mov_b32_e32 v135, v18
	v_mov_b32_e32 v136, v18
	v_mov_b32_e32 v137, v18
	v_add_f32_e32 v2, v130, v131
	v_add_f32_e32 v3, v132, v133
	v_add_f32_e32 v88, v2, v3
	ds_read_b32 v144, v138 offset:4224
	ds_read_b32 v145, v138 offset:4288
	ds_read_b32 v146, v138 offset:4352
	s_waitcnt lgkmcnt(6)
	v_cmp_eq_u32_e32 vcc, 20, v1
	v_fmac_f32_dpp v137, -v140, v89 row_newbcast:3 row_mask:0xf bank_mask:0xf
	v_fmac_f32_dpp v134, -v140, v90 row_newbcast:4 row_mask:0xf bank_mask:0xf
	v_fmac_f32_dpp v135, -v140, v91 row_newbcast:5 row_mask:0xf bank_mask:0xf
	v_fmac_f32_dpp v136, -v140, v88 row_newbcast:2 row_mask:0xf bank_mask:0xf
	v_fmac_f32_dpp v137, -v140, v93 row_newbcast:7 row_mask:0xf bank_mask:0xf
	v_fmac_f32_dpp v134, -v140, v94 row_newbcast:8 row_mask:0xf bank_mask:0xf
	v_fmac_f32_dpp v135, -v140, v95 row_newbcast:9 row_mask:0xf bank_mask:0xf
	v_fmac_f32_dpp v136, -v140, v92 row_newbcast:6 row_mask:0xf bank_mask:0xf
	v_fmac_f32_dpp v137, -v140, v97 row_newbcast:11 row_mask:0xf bank_mask:0xf
	v_fmac_f32_dpp v134, -v140, v98 row_newbcast:12 row_mask:0xf bank_mask:0xf
	v_fmac_f32_dpp v135, -v140, v99 row_newbcast:13 row_mask:0xf bank_mask:0xf
	v_fmac_f32_dpp v136, -v140, v96 row_newbcast:10 row_mask:0xf bank_mask:0xf
	v_fmac_f32_dpp v137, -v140, v101 row_newbcast:15 row_mask:0xf bank_mask:0xf
	v_fmac_f32_dpp v134, -v141, v102 row_newbcast:0 row_mask:0xf bank_mask:0xf
	v_fmac_f32_dpp v135, -v141, v103 row_newbcast:1 row_mask:0xf bank_mask:0xf
	v_fmac_f32_dpp v136, -v140, v100 row_newbcast:14 row_mask:0xf bank_mask:0xf
	v_fmac_f32_dpp v137, -v141, v105 row_newbcast:3 row_mask:0xf bank_mask:0xf
	v_fmac_f32_dpp v134, -v141, v106 row_newbcast:4 row_mask:0xf bank_mask:0xf
	v_fmac_f32_dpp v135, -v141, v107 row_newbcast:5 row_mask:0xf bank_mask:0xf
	v_fmac_f32_dpp v136, -v141, v104 row_newbcast:2 row_mask:0xf bank_mask:0xf
	v_fmac_f32_dpp v137, -v141, v109 row_newbcast:7 row_mask:0xf bank_mask:0xf
	v_fmac_f32_dpp v134, -v141, v110 row_newbcast:8 row_mask:0xf bank_mask:0xf
	v_fmac_f32_dpp v135, -v141, v111 row_newbcast:9 row_mask:0xf bank_mask:0xf
	v_fmac_f32_dpp v136, -v141, v108 row_newbcast:6 row_mask:0xf bank_mask:0xf
	v_fmac_f32_dpp v137, -v141, v113 row_newbcast:11 row_mask:0xf bank_mask:0xf
	v_fmac_f32_dpp v134, -v141, v114 row_newbcast:12 row_mask:0xf bank_mask:0xf
	v_fmac_f32_dpp v135, -v141, v115 row_newbcast:13 row_mask:0xf bank_mask:0xf
	v_fmac_f32_dpp v136, -v141, v112 row_newbcast:10 row_mask:0xf bank_mask:0xf
	v_fmac_f32_dpp v137, -v141, v117 row_newbcast:15 row_mask:0xf bank_mask:0xf
	v_fmac_f32_dpp v134, -v142, v118 row_newbcast:0 row_mask:0xf bank_mask:0xf
	v_fmac_f32_dpp v135, -v142, v119 row_newbcast:1 row_mask:0xf bank_mask:0xf
	v_fmac_f32_dpp v136, -v141, v116 row_newbcast:14 row_mask:0xf bank_mask:0xf
	v_fmac_f32_dpp v137, -v142, v121 row_newbcast:3 row_mask:0xf bank_mask:0xf
	v_fmac_f32_dpp v134, -v142, v122 row_newbcast:4 row_mask:0xf bank_mask:0xf
	v_fmac_f32_dpp v135, -v142, v123 row_newbcast:5 row_mask:0xf bank_mask:0xf
	v_fmac_f32_dpp v136, -v142, v120 row_newbcast:2 row_mask:0xf bank_mask:0xf
	v_fmac_f32_dpp v137, -v142, v125 row_newbcast:7 row_mask:0xf bank_mask:0xf
	v_fmac_f32_dpp v134, -v142, v126 row_newbcast:8 row_mask:0xf bank_mask:0xf
	v_fmac_f32_dpp v135, -v142, v127 row_newbcast:9 row_mask:0xf bank_mask:0xf
	v_fmac_f32_dpp v136, -v142, v124 row_newbcast:6 row_mask:0xf bank_mask:0xf
	v_fmac_f32_dpp v137, -v142, v129 row_newbcast:11 row_mask:0xf bank_mask:0xf
	s_nop 0
	v_fmac_f32_dpp v136, -v142, v128 row_newbcast:10 row_mask:0xf bank_mask:0xf
	v_cndmask_b32_e64 v130, 0, 1.0, vcc
	v_mov_b32_e32 v131, v18
	v_mov_b32_e32 v132, v18
	v_mov_b32_e32 v133, v18
	v_add_f32_e32 v2, v134, v135
	v_add_f32_e32 v3, v136, v137
	v_add_f32_e32 v87, v2, v3
	ds_read_b32 v140, v138 offset:4032
	ds_read_b32 v141, v138 offset:4096
	ds_read_b32 v142, v138 offset:4160
	s_waitcnt lgkmcnt(6)
	v_cmp_eq_u32_e32 vcc, 19, v1
	v_fmac_f32_dpp v132, -v148, v88 row_newbcast:2 row_mask:0xf bank_mask:0xf
	v_fmac_f32_dpp v133, -v148, v89 row_newbcast:3 row_mask:0xf bank_mask:0xf
	v_fmac_f32_dpp v130, -v148, v90 row_newbcast:4 row_mask:0xf bank_mask:0xf
	v_fmac_f32_dpp v131, -v148, v87 row_newbcast:1 row_mask:0xf bank_mask:0xf
	v_fmac_f32_dpp v132, -v148, v92 row_newbcast:6 row_mask:0xf bank_mask:0xf
	v_fmac_f32_dpp v133, -v148, v93 row_newbcast:7 row_mask:0xf bank_mask:0xf
	v_fmac_f32_dpp v130, -v148, v94 row_newbcast:8 row_mask:0xf bank_mask:0xf
	v_fmac_f32_dpp v131, -v148, v91 row_newbcast:5 row_mask:0xf bank_mask:0xf
	v_fmac_f32_dpp v132, -v148, v96 row_newbcast:10 row_mask:0xf bank_mask:0xf
	v_fmac_f32_dpp v133, -v148, v97 row_newbcast:11 row_mask:0xf bank_mask:0xf
	v_fmac_f32_dpp v130, -v148, v98 row_newbcast:12 row_mask:0xf bank_mask:0xf
	v_fmac_f32_dpp v131, -v148, v95 row_newbcast:9 row_mask:0xf bank_mask:0xf
	v_fmac_f32_dpp v132, -v148, v100 row_newbcast:14 row_mask:0xf bank_mask:0xf
	v_fmac_f32_dpp v133, -v148, v101 row_newbcast:15 row_mask:0xf bank_mask:0xf
	v_fmac_f32_dpp v130, -v149, v102 row_newbcast:0 row_mask:0xf bank_mask:0xf
	v_fmac_f32_dpp v131, -v148, v99 row_newbcast:13 row_mask:0xf bank_mask:0xf
	v_fmac_f32_dpp v132, -v149, v104 row_newbcast:2 row_mask:0xf bank_mask:0xf
	v_fmac_f32_dpp v133, -v149, v105 row_newbcast:3 row_mask:0xf bank_mask:0xf
	v_fmac_f32_dpp v130, -v149, v106 row_newbcast:4 row_mask:0xf bank_mask:0xf
	v_fmac_f32_dpp v131, -v149, v103 row_newbcast:1 row_mask:0xf bank_mask:0xf
	v_fmac_f32_dpp v132, -v149, v108 row_newbcast:6 row_mask:0xf bank_mask:0xf
	v_fmac_f32_dpp v133, -v149, v109 row_newbcast:7 row_mask:0xf bank_mask:0xf
	v_fmac_f32_dpp v130, -v149, v110 row_newbcast:8 row_mask:0xf bank_mask:0xf
	v_fmac_f32_dpp v131, -v149, v107 row_newbcast:5 row_mask:0xf bank_mask:0xf
	v_fmac_f32_dpp v132, -v149, v112 row_newbcast:10 row_mask:0xf bank_mask:0xf
	v_fmac_f32_dpp v133, -v149, v113 row_newbcast:11 row_mask:0xf bank_mask:0xf
	v_fmac_f32_dpp v130, -v149, v114 row_newbcast:12 row_mask:0xf bank_mask:0xf
	v_fmac_f32_dpp v131, -v149, v111 row_newbcast:9 row_mask:0xf bank_mask:0xf
	v_fmac_f32_dpp v132, -v149, v116 row_newbcast:14 row_mask:0xf bank_mask:0xf
	v_fmac_f32_dpp v133, -v149, v117 row_newbcast:15 row_mask:0xf bank_mask:0xf
	v_fmac_f32_dpp v130, -v150, v118 row_newbcast:0 row_mask:0xf bank_mask:0xf
	v_fmac_f32_dpp v131, -v149, v115 row_newbcast:13 row_mask:0xf bank_mask:0xf
	v_fmac_f32_dpp v132, -v150, v120 row_newbcast:2 row_mask:0xf bank_mask:0xf
	v_fmac_f32_dpp v133, -v150, v121 row_newbcast:3 row_mask:0xf bank_mask:0xf
	v_fmac_f32_dpp v130, -v150, v122 row_newbcast:4 row_mask:0xf bank_mask:0xf
	v_fmac_f32_dpp v131, -v150, v119 row_newbcast:1 row_mask:0xf bank_mask:0xf
	v_fmac_f32_dpp v132, -v150, v124 row_newbcast:6 row_mask:0xf bank_mask:0xf
	v_fmac_f32_dpp v133, -v150, v125 row_newbcast:7 row_mask:0xf bank_mask:0xf
	v_fmac_f32_dpp v130, -v150, v126 row_newbcast:8 row_mask:0xf bank_mask:0xf
	v_fmac_f32_dpp v131, -v150, v123 row_newbcast:5 row_mask:0xf bank_mask:0xf
	v_fmac_f32_dpp v132, -v150, v128 row_newbcast:10 row_mask:0xf bank_mask:0xf
	v_fmac_f32_dpp v133, -v150, v129 row_newbcast:11 row_mask:0xf bank_mask:0xf
	v_fmac_f32_dpp v131, -v150, v127 row_newbcast:9 row_mask:0xf bank_mask:0xf
	v_cndmask_b32_e64 v134, 0, 1.0, vcc
	v_mov_b32_e32 v135, v18
	v_mov_b32_e32 v136, v18
	v_mov_b32_e32 v137, v18
	v_add_f32_e32 v2, v130, v131
	v_add_f32_e32 v3, v132, v133
	v_add_f32_e32 v86, v2, v3
	ds_read_b32 v148, v138 offset:3840
	ds_read_b32 v149, v138 offset:3904
	ds_read_b32 v150, v138 offset:3968
	s_waitcnt lgkmcnt(6)
	v_cmp_eq_u32_e32 vcc, 18, v1
	v_fmac_f32_dpp v135, -v144, v87 row_newbcast:1 row_mask:0xf bank_mask:0xf
	v_fmac_f32_dpp v136, -v144, v88 row_newbcast:2 row_mask:0xf bank_mask:0xf
	v_fmac_f32_dpp v137, -v144, v89 row_newbcast:3 row_mask:0xf bank_mask:0xf
	v_fmac_f32_dpp v134, -v144, v86 row_newbcast:0 row_mask:0xf bank_mask:0xf
	v_fmac_f32_dpp v135, -v144, v91 row_newbcast:5 row_mask:0xf bank_mask:0xf
	v_fmac_f32_dpp v136, -v144, v92 row_newbcast:6 row_mask:0xf bank_mask:0xf
	v_fmac_f32_dpp v137, -v144, v93 row_newbcast:7 row_mask:0xf bank_mask:0xf
	v_fmac_f32_dpp v134, -v144, v90 row_newbcast:4 row_mask:0xf bank_mask:0xf
	v_fmac_f32_dpp v135, -v144, v95 row_newbcast:9 row_mask:0xf bank_mask:0xf
	v_fmac_f32_dpp v136, -v144, v96 row_newbcast:10 row_mask:0xf bank_mask:0xf
	v_fmac_f32_dpp v137, -v144, v97 row_newbcast:11 row_mask:0xf bank_mask:0xf
	v_fmac_f32_dpp v134, -v144, v94 row_newbcast:8 row_mask:0xf bank_mask:0xf
	v_fmac_f32_dpp v135, -v144, v99 row_newbcast:13 row_mask:0xf bank_mask:0xf
	v_fmac_f32_dpp v136, -v144, v100 row_newbcast:14 row_mask:0xf bank_mask:0xf
	v_fmac_f32_dpp v137, -v144, v101 row_newbcast:15 row_mask:0xf bank_mask:0xf
	v_fmac_f32_dpp v134, -v144, v98 row_newbcast:12 row_mask:0xf bank_mask:0xf
	v_fmac_f32_dpp v135, -v145, v103 row_newbcast:1 row_mask:0xf bank_mask:0xf
	v_fmac_f32_dpp v136, -v145, v104 row_newbcast:2 row_mask:0xf bank_mask:0xf
	v_fmac_f32_dpp v137, -v145, v105 row_newbcast:3 row_mask:0xf bank_mask:0xf
	v_fmac_f32_dpp v134, -v145, v102 row_newbcast:0 row_mask:0xf bank_mask:0xf
	v_fmac_f32_dpp v135, -v145, v107 row_newbcast:5 row_mask:0xf bank_mask:0xf
	v_fmac_f32_dpp v136, -v145, v108 row_newbcast:6 row_mask:0xf bank_mask:0xf
	v_fmac_f32_dpp v137, -v145, v109 row_newbcast:7 row_mask:0xf bank_mask:0xf
	v_fmac_f32_dpp v134, -v145, v106 row_newbcast:4 row_mask:0xf bank_mask:0xf
	v_fmac_f32_dpp v135, -v145, v111 row_newbcast:9 row_mask:0xf bank_mask:0xf
	v_fmac_f32_dpp v136, -v145, v112 row_newbcast:10 row_mask:0xf bank_mask:0xf
	v_fmac_f32_dpp v137, -v145, v113 row_newbcast:11 row_mask:0xf bank_mask:0xf
	v_fmac_f32_dpp v134, -v145, v110 row_newbcast:8 row_mask:0xf bank_mask:0xf
	v_fmac_f32_dpp v135, -v145, v115 row_newbcast:13 row_mask:0xf bank_mask:0xf
	v_fmac_f32_dpp v136, -v145, v116 row_newbcast:14 row_mask:0xf bank_mask:0xf
	v_fmac_f32_dpp v137, -v145, v117 row_newbcast:15 row_mask:0xf bank_mask:0xf
	v_fmac_f32_dpp v134, -v145, v114 row_newbcast:12 row_mask:0xf bank_mask:0xf
	v_fmac_f32_dpp v135, -v146, v119 row_newbcast:1 row_mask:0xf bank_mask:0xf
	v_fmac_f32_dpp v136, -v146, v120 row_newbcast:2 row_mask:0xf bank_mask:0xf
	v_fmac_f32_dpp v137, -v146, v121 row_newbcast:3 row_mask:0xf bank_mask:0xf
	v_fmac_f32_dpp v134, -v146, v118 row_newbcast:0 row_mask:0xf bank_mask:0xf
	v_fmac_f32_dpp v135, -v146, v123 row_newbcast:5 row_mask:0xf bank_mask:0xf
	v_fmac_f32_dpp v136, -v146, v124 row_newbcast:6 row_mask:0xf bank_mask:0xf
	v_fmac_f32_dpp v137, -v146, v125 row_newbcast:7 row_mask:0xf bank_mask:0xf
	v_fmac_f32_dpp v134, -v146, v122 row_newbcast:4 row_mask:0xf bank_mask:0xf
	v_fmac_f32_dpp v135, -v146, v127 row_newbcast:9 row_mask:0xf bank_mask:0xf
	v_fmac_f32_dpp v136, -v146, v128 row_newbcast:10 row_mask:0xf bank_mask:0xf
	v_fmac_f32_dpp v137, -v146, v129 row_newbcast:11 row_mask:0xf bank_mask:0xf
	v_fmac_f32_dpp v134, -v146, v126 row_newbcast:8 row_mask:0xf bank_mask:0xf
	v_cndmask_b32_e64 v130, 0, 1.0, vcc
	v_mov_b32_e32 v131, v18
	v_mov_b32_e32 v132, v18
	v_mov_b32_e32 v133, v18
	v_add_f32_e32 v2, v134, v135
	v_add_f32_e32 v3, v136, v137
	v_add_f32_e32 v85, v2, v3
	ds_read_b32 v144, v138 offset:3648
	ds_read_b32 v145, v138 offset:3712
	ds_read_b32 v146, v138 offset:3776
	s_waitcnt lgkmcnt(6)
	v_cmp_eq_u32_e32 vcc, 17, v1
	v_fmac_f32_dpp v130, -v140, v86 row_newbcast:4 row_mask:0xf bank_mask:0xf
	v_fmac_f32_dpp v131, -v140, v87 row_newbcast:5 row_mask:0xf bank_mask:0xf
	v_fmac_f32_dpp v132, -v140, v88 row_newbcast:6 row_mask:0xf bank_mask:0xf
	v_fmac_f32_dpp v133, -v140, v85 row_newbcast:3 row_mask:0xf bank_mask:0xf
	v_fmac_f32_dpp v130, -v140, v90 row_newbcast:8 row_mask:0xf bank_mask:0xf
	v_fmac_f32_dpp v131, -v140, v91 row_newbcast:9 row_mask:0xf bank_mask:0xf
	v_fmac_f32_dpp v132, -v140, v92 row_newbcast:10 row_mask:0xf bank_mask:0xf
	v_fmac_f32_dpp v133, -v140, v89 row_newbcast:7 row_mask:0xf bank_mask:0xf
	v_fmac_f32_dpp v130, -v140, v94 row_newbcast:12 row_mask:0xf bank_mask:0xf
	v_fmac_f32_dpp v131, -v140, v95 row_newbcast:13 row_mask:0xf bank_mask:0xf
	v_fmac_f32_dpp v132, -v140, v96 row_newbcast:14 row_mask:0xf bank_mask:0xf
	v_fmac_f32_dpp v133, -v140, v93 row_newbcast:11 row_mask:0xf bank_mask:0xf
	v_fmac_f32_dpp v130, -v141, v98 row_newbcast:0 row_mask:0xf bank_mask:0xf
	v_fmac_f32_dpp v131, -v141, v99 row_newbcast:1 row_mask:0xf bank_mask:0xf
	v_fmac_f32_dpp v132, -v141, v100 row_newbcast:2 row_mask:0xf bank_mask:0xf
	v_fmac_f32_dpp v133, -v140, v97 row_newbcast:15 row_mask:0xf bank_mask:0xf
	v_fmac_f32_dpp v130, -v141, v102 row_newbcast:4 row_mask:0xf bank_mask:0xf
	v_fmac_f32_dpp v131, -v141, v103 row_newbcast:5 row_mask:0xf bank_mask:0xf
	v_fmac_f32_dpp v132, -v141, v104 row_newbcast:6 row_mask:0xf bank_mask:0xf
	v_fmac_f32_dpp v133, -v141, v101 row_newbcast:3 row_mask:0xf bank_mask:0xf
	v_fmac_f32_dpp v130, -v141, v106 row_newbcast:8 row_mask:0xf bank_mask:0xf
	v_fmac_f32_dpp v131, -v141, v107 row_newbcast:9 row_mask:0xf bank_mask:0xf
	v_fmac_f32_dpp v132, -v141, v108 row_newbcast:10 row_mask:0xf bank_mask:0xf
	v_fmac_f32_dpp v133, -v141, v105 row_newbcast:7 row_mask:0xf bank_mask:0xf
	v_fmac_f32_dpp v130, -v141, v110 row_newbcast:12 row_mask:0xf bank_mask:0xf
	v_fmac_f32_dpp v131, -v141, v111 row_newbcast:13 row_mask:0xf bank_mask:0xf
	v_fmac_f32_dpp v132, -v141, v112 row_newbcast:14 row_mask:0xf bank_mask:0xf
	v_fmac_f32_dpp v133, -v141, v109 row_newbcast:11 row_mask:0xf bank_mask:0xf
	v_fmac_f32_dpp v130, -v142, v114 row_newbcast:0 row_mask:0xf bank_mask:0xf
	v_fmac_f32_dpp v131, -v142, v115 row_newbcast:1 row_mask:0xf bank_mask:0xf
	v_fmac_f32_dpp v132, -v142, v116 row_newbcast:2 row_mask:0xf bank_mask:0xf
	v_fmac_f32_dpp v133, -v141, v113 row_newbcast:15 row_mask:0xf bank_mask:0xf
	v_fmac_f32_dpp v130, -v142, v118 row_newbcast:4 row_mask:0xf bank_mask:0xf
	v_fmac_f32_dpp v131, -v142, v119 row_newbcast:5 row_mask:0xf bank_mask:0xf
	v_fmac_f32_dpp v132, -v142, v120 row_newbcast:6 row_mask:0xf bank_mask:0xf
	v_fmac_f32_dpp v133, -v142, v117 row_newbcast:3 row_mask:0xf bank_mask:0xf
	v_fmac_f32_dpp v130, -v142, v122 row_newbcast:8 row_mask:0xf bank_mask:0xf
	v_fmac_f32_dpp v131, -v142, v123 row_newbcast:9 row_mask:0xf bank_mask:0xf
	v_fmac_f32_dpp v132, -v142, v124 row_newbcast:10 row_mask:0xf bank_mask:0xf
	v_fmac_f32_dpp v133, -v142, v121 row_newbcast:7 row_mask:0xf bank_mask:0xf
	v_fmac_f32_dpp v130, -v142, v126 row_newbcast:12 row_mask:0xf bank_mask:0xf
	v_fmac_f32_dpp v131, -v142, v127 row_newbcast:13 row_mask:0xf bank_mask:0xf
	v_fmac_f32_dpp v132, -v142, v128 row_newbcast:14 row_mask:0xf bank_mask:0xf
	v_fmac_f32_dpp v133, -v142, v125 row_newbcast:11 row_mask:0xf bank_mask:0xf
	s_nop 1
	v_fmac_f32_dpp v133, -v142, v129 row_newbcast:15 row_mask:0xf bank_mask:0xf
	v_cndmask_b32_e64 v134, 0, 1.0, vcc
	v_mov_b32_e32 v135, v18
	v_mov_b32_e32 v136, v18
	v_mov_b32_e32 v137, v18
	v_add_f32_e32 v2, v130, v131
	v_add_f32_e32 v3, v132, v133
	v_add_f32_e32 v84, v2, v3
	ds_read_b32 v140, v138 offset:3456
	ds_read_b32 v141, v138 offset:3520
	ds_read_b32 v142, v138 offset:3584
	s_waitcnt lgkmcnt(6)
	v_cmp_eq_u32_e32 vcc, 16, v1
	v_fmac_f32_dpp v137, -v148, v85 row_newbcast:3 row_mask:0xf bank_mask:0xf
	v_fmac_f32_dpp v134, -v148, v86 row_newbcast:4 row_mask:0xf bank_mask:0xf
	v_fmac_f32_dpp v135, -v148, v87 row_newbcast:5 row_mask:0xf bank_mask:0xf
	v_fmac_f32_dpp v136, -v148, v84 row_newbcast:2 row_mask:0xf bank_mask:0xf
	v_fmac_f32_dpp v137, -v148, v89 row_newbcast:7 row_mask:0xf bank_mask:0xf
	v_fmac_f32_dpp v134, -v148, v90 row_newbcast:8 row_mask:0xf bank_mask:0xf
	v_fmac_f32_dpp v135, -v148, v91 row_newbcast:9 row_mask:0xf bank_mask:0xf
	v_fmac_f32_dpp v136, -v148, v88 row_newbcast:6 row_mask:0xf bank_mask:0xf
	v_fmac_f32_dpp v137, -v148, v93 row_newbcast:11 row_mask:0xf bank_mask:0xf
	v_fmac_f32_dpp v134, -v148, v94 row_newbcast:12 row_mask:0xf bank_mask:0xf
	v_fmac_f32_dpp v135, -v148, v95 row_newbcast:13 row_mask:0xf bank_mask:0xf
	v_fmac_f32_dpp v136, -v148, v92 row_newbcast:10 row_mask:0xf bank_mask:0xf
	v_fmac_f32_dpp v137, -v148, v97 row_newbcast:15 row_mask:0xf bank_mask:0xf
	v_fmac_f32_dpp v134, -v149, v98 row_newbcast:0 row_mask:0xf bank_mask:0xf
	v_fmac_f32_dpp v135, -v149, v99 row_newbcast:1 row_mask:0xf bank_mask:0xf
	v_fmac_f32_dpp v136, -v148, v96 row_newbcast:14 row_mask:0xf bank_mask:0xf
	v_fmac_f32_dpp v137, -v149, v101 row_newbcast:3 row_mask:0xf bank_mask:0xf
	v_fmac_f32_dpp v134, -v149, v102 row_newbcast:4 row_mask:0xf bank_mask:0xf
	v_fmac_f32_dpp v135, -v149, v103 row_newbcast:5 row_mask:0xf bank_mask:0xf
	v_fmac_f32_dpp v136, -v149, v100 row_newbcast:2 row_mask:0xf bank_mask:0xf
	v_fmac_f32_dpp v137, -v149, v105 row_newbcast:7 row_mask:0xf bank_mask:0xf
	v_fmac_f32_dpp v134, -v149, v106 row_newbcast:8 row_mask:0xf bank_mask:0xf
	v_fmac_f32_dpp v135, -v149, v107 row_newbcast:9 row_mask:0xf bank_mask:0xf
	v_fmac_f32_dpp v136, -v149, v104 row_newbcast:6 row_mask:0xf bank_mask:0xf
	v_fmac_f32_dpp v137, -v149, v109 row_newbcast:11 row_mask:0xf bank_mask:0xf
	v_fmac_f32_dpp v134, -v149, v110 row_newbcast:12 row_mask:0xf bank_mask:0xf
	v_fmac_f32_dpp v135, -v149, v111 row_newbcast:13 row_mask:0xf bank_mask:0xf
	v_fmac_f32_dpp v136, -v149, v108 row_newbcast:10 row_mask:0xf bank_mask:0xf
	v_fmac_f32_dpp v137, -v149, v113 row_newbcast:15 row_mask:0xf bank_mask:0xf
	v_fmac_f32_dpp v134, -v150, v114 row_newbcast:0 row_mask:0xf bank_mask:0xf
	v_fmac_f32_dpp v135, -v150, v115 row_newbcast:1 row_mask:0xf bank_mask:0xf
	v_fmac_f32_dpp v136, -v149, v112 row_newbcast:14 row_mask:0xf bank_mask:0xf
	v_fmac_f32_dpp v137, -v150, v117 row_newbcast:3 row_mask:0xf bank_mask:0xf
	v_fmac_f32_dpp v134, -v150, v118 row_newbcast:4 row_mask:0xf bank_mask:0xf
	v_fmac_f32_dpp v135, -v150, v119 row_newbcast:5 row_mask:0xf bank_mask:0xf
	v_fmac_f32_dpp v136, -v150, v116 row_newbcast:2 row_mask:0xf bank_mask:0xf
	v_fmac_f32_dpp v137, -v150, v121 row_newbcast:7 row_mask:0xf bank_mask:0xf
	v_fmac_f32_dpp v134, -v150, v122 row_newbcast:8 row_mask:0xf bank_mask:0xf
	v_fmac_f32_dpp v135, -v150, v123 row_newbcast:9 row_mask:0xf bank_mask:0xf
	v_fmac_f32_dpp v136, -v150, v120 row_newbcast:6 row_mask:0xf bank_mask:0xf
	v_fmac_f32_dpp v137, -v150, v125 row_newbcast:11 row_mask:0xf bank_mask:0xf
	v_fmac_f32_dpp v134, -v150, v126 row_newbcast:12 row_mask:0xf bank_mask:0xf
	v_fmac_f32_dpp v135, -v150, v127 row_newbcast:13 row_mask:0xf bank_mask:0xf
	v_fmac_f32_dpp v136, -v150, v124 row_newbcast:10 row_mask:0xf bank_mask:0xf
	v_fmac_f32_dpp v137, -v150, v129 row_newbcast:15 row_mask:0xf bank_mask:0xf
	s_nop 0
	v_fmac_f32_dpp v136, -v150, v128 row_newbcast:14 row_mask:0xf bank_mask:0xf
	v_cndmask_b32_e64 v130, 0, 1.0, vcc
	v_mov_b32_e32 v131, v18
	v_mov_b32_e32 v132, v18
	v_mov_b32_e32 v133, v18
	v_add_f32_e32 v2, v134, v135
	v_add_f32_e32 v3, v136, v137
	v_add_f32_e32 v83, v2, v3
	ds_read_b32 v148, v138 offset:3248
	ds_read_b32 v149, v138 offset:3312
	ds_read_b32 v150, v138 offset:3376
	ds_read_b32 v151, v138 offset:3440
	s_waitcnt lgkmcnt(7)
	v_cmp_eq_u32_e32 vcc, 15, v1
	v_fmac_f32_dpp v132, -v144, v84 row_newbcast:2 row_mask:0xf bank_mask:0xf
	v_fmac_f32_dpp v133, -v144, v85 row_newbcast:3 row_mask:0xf bank_mask:0xf
	v_fmac_f32_dpp v130, -v144, v86 row_newbcast:4 row_mask:0xf bank_mask:0xf
	v_fmac_f32_dpp v131, -v144, v83 row_newbcast:1 row_mask:0xf bank_mask:0xf
	v_fmac_f32_dpp v132, -v144, v88 row_newbcast:6 row_mask:0xf bank_mask:0xf
	v_fmac_f32_dpp v133, -v144, v89 row_newbcast:7 row_mask:0xf bank_mask:0xf
	v_fmac_f32_dpp v130, -v144, v90 row_newbcast:8 row_mask:0xf bank_mask:0xf
	v_fmac_f32_dpp v131, -v144, v87 row_newbcast:5 row_mask:0xf bank_mask:0xf
	v_fmac_f32_dpp v132, -v144, v92 row_newbcast:10 row_mask:0xf bank_mask:0xf
	v_fmac_f32_dpp v133, -v144, v93 row_newbcast:11 row_mask:0xf bank_mask:0xf
	v_fmac_f32_dpp v130, -v144, v94 row_newbcast:12 row_mask:0xf bank_mask:0xf
	v_fmac_f32_dpp v131, -v144, v91 row_newbcast:9 row_mask:0xf bank_mask:0xf
	v_fmac_f32_dpp v132, -v144, v96 row_newbcast:14 row_mask:0xf bank_mask:0xf
	v_fmac_f32_dpp v133, -v144, v97 row_newbcast:15 row_mask:0xf bank_mask:0xf
	v_fmac_f32_dpp v130, -v145, v98 row_newbcast:0 row_mask:0xf bank_mask:0xf
	v_fmac_f32_dpp v131, -v144, v95 row_newbcast:13 row_mask:0xf bank_mask:0xf
	v_fmac_f32_dpp v132, -v145, v100 row_newbcast:2 row_mask:0xf bank_mask:0xf
	v_fmac_f32_dpp v133, -v145, v101 row_newbcast:3 row_mask:0xf bank_mask:0xf
	v_fmac_f32_dpp v130, -v145, v102 row_newbcast:4 row_mask:0xf bank_mask:0xf
	v_fmac_f32_dpp v131, -v145, v99 row_newbcast:1 row_mask:0xf bank_mask:0xf
	v_fmac_f32_dpp v132, -v145, v104 row_newbcast:6 row_mask:0xf bank_mask:0xf
	v_fmac_f32_dpp v133, -v145, v105 row_newbcast:7 row_mask:0xf bank_mask:0xf
	v_fmac_f32_dpp v130, -v145, v106 row_newbcast:8 row_mask:0xf bank_mask:0xf
	v_fmac_f32_dpp v131, -v145, v103 row_newbcast:5 row_mask:0xf bank_mask:0xf
	v_fmac_f32_dpp v132, -v145, v108 row_newbcast:10 row_mask:0xf bank_mask:0xf
	v_fmac_f32_dpp v133, -v145, v109 row_newbcast:11 row_mask:0xf bank_mask:0xf
	v_fmac_f32_dpp v130, -v145, v110 row_newbcast:12 row_mask:0xf bank_mask:0xf
	v_fmac_f32_dpp v131, -v145, v107 row_newbcast:9 row_mask:0xf bank_mask:0xf
	v_fmac_f32_dpp v132, -v145, v112 row_newbcast:14 row_mask:0xf bank_mask:0xf
	v_fmac_f32_dpp v133, -v145, v113 row_newbcast:15 row_mask:0xf bank_mask:0xf
	v_fmac_f32_dpp v130, -v146, v114 row_newbcast:0 row_mask:0xf bank_mask:0xf
	v_fmac_f32_dpp v131, -v145, v111 row_newbcast:13 row_mask:0xf bank_mask:0xf
	v_fmac_f32_dpp v132, -v146, v116 row_newbcast:2 row_mask:0xf bank_mask:0xf
	v_fmac_f32_dpp v133, -v146, v117 row_newbcast:3 row_mask:0xf bank_mask:0xf
	v_fmac_f32_dpp v130, -v146, v118 row_newbcast:4 row_mask:0xf bank_mask:0xf
	v_fmac_f32_dpp v131, -v146, v115 row_newbcast:1 row_mask:0xf bank_mask:0xf
	v_fmac_f32_dpp v132, -v146, v120 row_newbcast:6 row_mask:0xf bank_mask:0xf
	v_fmac_f32_dpp v133, -v146, v121 row_newbcast:7 row_mask:0xf bank_mask:0xf
	v_fmac_f32_dpp v130, -v146, v122 row_newbcast:8 row_mask:0xf bank_mask:0xf
	v_fmac_f32_dpp v131, -v146, v119 row_newbcast:5 row_mask:0xf bank_mask:0xf
	v_fmac_f32_dpp v132, -v146, v124 row_newbcast:10 row_mask:0xf bank_mask:0xf
	v_fmac_f32_dpp v133, -v146, v125 row_newbcast:11 row_mask:0xf bank_mask:0xf
	v_fmac_f32_dpp v130, -v146, v126 row_newbcast:12 row_mask:0xf bank_mask:0xf
	v_fmac_f32_dpp v131, -v146, v123 row_newbcast:9 row_mask:0xf bank_mask:0xf
	v_fmac_f32_dpp v132, -v146, v128 row_newbcast:14 row_mask:0xf bank_mask:0xf
	v_fmac_f32_dpp v133, -v146, v129 row_newbcast:15 row_mask:0xf bank_mask:0xf
	v_fmac_f32_dpp v131, -v146, v127 row_newbcast:13 row_mask:0xf bank_mask:0xf
	v_cndmask_b32_e64 v134, 0, 1.0, vcc
	v_mov_b32_e32 v135, v18
	v_mov_b32_e32 v136, v18
	v_mov_b32_e32 v137, v18
	v_add_f32_e32 v2, v130, v131
	v_add_f32_e32 v3, v132, v133
	v_add_f32_e32 v82, v2, v3
	ds_read_b32 v144, v138 offset:3040
	ds_read_b32 v145, v138 offset:3104
	ds_read_b32 v146, v138 offset:3168
	ds_read_b32 v147, v138 offset:3232
	s_waitcnt lgkmcnt(8)
	v_cmp_eq_u32_e32 vcc, 14, v1
	v_fmac_f32_dpp v135, -v140, v83 row_newbcast:1 row_mask:0xf bank_mask:0xf
	v_fmac_f32_dpp v136, -v140, v84 row_newbcast:2 row_mask:0xf bank_mask:0xf
	v_fmac_f32_dpp v137, -v140, v85 row_newbcast:3 row_mask:0xf bank_mask:0xf
	v_fmac_f32_dpp v134, -v140, v82 row_newbcast:0 row_mask:0xf bank_mask:0xf
	v_fmac_f32_dpp v135, -v140, v87 row_newbcast:5 row_mask:0xf bank_mask:0xf
	v_fmac_f32_dpp v136, -v140, v88 row_newbcast:6 row_mask:0xf bank_mask:0xf
	v_fmac_f32_dpp v137, -v140, v89 row_newbcast:7 row_mask:0xf bank_mask:0xf
	v_fmac_f32_dpp v134, -v140, v86 row_newbcast:4 row_mask:0xf bank_mask:0xf
	v_fmac_f32_dpp v135, -v140, v91 row_newbcast:9 row_mask:0xf bank_mask:0xf
	v_fmac_f32_dpp v136, -v140, v92 row_newbcast:10 row_mask:0xf bank_mask:0xf
	v_fmac_f32_dpp v137, -v140, v93 row_newbcast:11 row_mask:0xf bank_mask:0xf
	v_fmac_f32_dpp v134, -v140, v90 row_newbcast:8 row_mask:0xf bank_mask:0xf
	v_fmac_f32_dpp v135, -v140, v95 row_newbcast:13 row_mask:0xf bank_mask:0xf
	v_fmac_f32_dpp v136, -v140, v96 row_newbcast:14 row_mask:0xf bank_mask:0xf
	v_fmac_f32_dpp v137, -v140, v97 row_newbcast:15 row_mask:0xf bank_mask:0xf
	v_fmac_f32_dpp v134, -v140, v94 row_newbcast:12 row_mask:0xf bank_mask:0xf
	v_fmac_f32_dpp v135, -v141, v99 row_newbcast:1 row_mask:0xf bank_mask:0xf
	v_fmac_f32_dpp v136, -v141, v100 row_newbcast:2 row_mask:0xf bank_mask:0xf
	v_fmac_f32_dpp v137, -v141, v101 row_newbcast:3 row_mask:0xf bank_mask:0xf
	v_fmac_f32_dpp v134, -v141, v98 row_newbcast:0 row_mask:0xf bank_mask:0xf
	v_fmac_f32_dpp v135, -v141, v103 row_newbcast:5 row_mask:0xf bank_mask:0xf
	v_fmac_f32_dpp v136, -v141, v104 row_newbcast:6 row_mask:0xf bank_mask:0xf
	v_fmac_f32_dpp v137, -v141, v105 row_newbcast:7 row_mask:0xf bank_mask:0xf
	v_fmac_f32_dpp v134, -v141, v102 row_newbcast:4 row_mask:0xf bank_mask:0xf
	v_fmac_f32_dpp v135, -v141, v107 row_newbcast:9 row_mask:0xf bank_mask:0xf
	v_fmac_f32_dpp v136, -v141, v108 row_newbcast:10 row_mask:0xf bank_mask:0xf
	v_fmac_f32_dpp v137, -v141, v109 row_newbcast:11 row_mask:0xf bank_mask:0xf
	v_fmac_f32_dpp v134, -v141, v106 row_newbcast:8 row_mask:0xf bank_mask:0xf
	v_fmac_f32_dpp v135, -v141, v111 row_newbcast:13 row_mask:0xf bank_mask:0xf
	v_fmac_f32_dpp v136, -v141, v112 row_newbcast:14 row_mask:0xf bank_mask:0xf
	v_fmac_f32_dpp v137, -v141, v113 row_newbcast:15 row_mask:0xf bank_mask:0xf
	v_fmac_f32_dpp v134, -v141, v110 row_newbcast:12 row_mask:0xf bank_mask:0xf
	v_fmac_f32_dpp v135, -v142, v115 row_newbcast:1 row_mask:0xf bank_mask:0xf
	v_fmac_f32_dpp v136, -v142, v116 row_newbcast:2 row_mask:0xf bank_mask:0xf
	v_fmac_f32_dpp v137, -v142, v117 row_newbcast:3 row_mask:0xf bank_mask:0xf
	v_fmac_f32_dpp v134, -v142, v114 row_newbcast:0 row_mask:0xf bank_mask:0xf
	v_fmac_f32_dpp v135, -v142, v119 row_newbcast:5 row_mask:0xf bank_mask:0xf
	v_fmac_f32_dpp v136, -v142, v120 row_newbcast:6 row_mask:0xf bank_mask:0xf
	v_fmac_f32_dpp v137, -v142, v121 row_newbcast:7 row_mask:0xf bank_mask:0xf
	v_fmac_f32_dpp v134, -v142, v118 row_newbcast:4 row_mask:0xf bank_mask:0xf
	v_fmac_f32_dpp v135, -v142, v123 row_newbcast:9 row_mask:0xf bank_mask:0xf
	v_fmac_f32_dpp v136, -v142, v124 row_newbcast:10 row_mask:0xf bank_mask:0xf
	v_fmac_f32_dpp v137, -v142, v125 row_newbcast:11 row_mask:0xf bank_mask:0xf
	v_fmac_f32_dpp v134, -v142, v122 row_newbcast:8 row_mask:0xf bank_mask:0xf
	v_fmac_f32_dpp v135, -v142, v127 row_newbcast:13 row_mask:0xf bank_mask:0xf
	v_fmac_f32_dpp v136, -v142, v128 row_newbcast:14 row_mask:0xf bank_mask:0xf
	v_fmac_f32_dpp v137, -v142, v129 row_newbcast:15 row_mask:0xf bank_mask:0xf
	v_fmac_f32_dpp v134, -v142, v126 row_newbcast:12 row_mask:0xf bank_mask:0xf
	v_cndmask_b32_e64 v130, 0, 1.0, vcc
	v_mov_b32_e32 v131, v18
	v_mov_b32_e32 v132, v18
	v_mov_b32_e32 v133, v18
	v_add_f32_e32 v2, v134, v135
	v_add_f32_e32 v3, v136, v137
	v_add_f32_e32 v81, v2, v3
	ds_read_b32 v140, v138 offset:2832
	ds_read_b32 v141, v138 offset:2896
	ds_read_b32 v142, v138 offset:2960
	ds_read_b32 v143, v138 offset:3024
	s_waitcnt lgkmcnt(8)
	v_cmp_eq_u32_e32 vcc, 13, v1
	v_fmac_f32_dpp v130, -v148, v82 row_newbcast:4 row_mask:0xf bank_mask:0xf
	v_fmac_f32_dpp v131, -v148, v83 row_newbcast:5 row_mask:0xf bank_mask:0xf
	v_fmac_f32_dpp v132, -v148, v84 row_newbcast:6 row_mask:0xf bank_mask:0xf
	v_fmac_f32_dpp v133, -v148, v81 row_newbcast:3 row_mask:0xf bank_mask:0xf
	v_fmac_f32_dpp v130, -v148, v86 row_newbcast:8 row_mask:0xf bank_mask:0xf
	v_fmac_f32_dpp v131, -v148, v87 row_newbcast:9 row_mask:0xf bank_mask:0xf
	v_fmac_f32_dpp v132, -v148, v88 row_newbcast:10 row_mask:0xf bank_mask:0xf
	v_fmac_f32_dpp v133, -v148, v85 row_newbcast:7 row_mask:0xf bank_mask:0xf
	v_fmac_f32_dpp v130, -v148, v90 row_newbcast:12 row_mask:0xf bank_mask:0xf
	v_fmac_f32_dpp v131, -v148, v91 row_newbcast:13 row_mask:0xf bank_mask:0xf
	v_fmac_f32_dpp v132, -v148, v92 row_newbcast:14 row_mask:0xf bank_mask:0xf
	v_fmac_f32_dpp v133, -v148, v89 row_newbcast:11 row_mask:0xf bank_mask:0xf
	v_fmac_f32_dpp v130, -v149, v94 row_newbcast:0 row_mask:0xf bank_mask:0xf
	v_fmac_f32_dpp v131, -v149, v95 row_newbcast:1 row_mask:0xf bank_mask:0xf
	v_fmac_f32_dpp v132, -v149, v96 row_newbcast:2 row_mask:0xf bank_mask:0xf
	v_fmac_f32_dpp v133, -v148, v93 row_newbcast:15 row_mask:0xf bank_mask:0xf
	v_fmac_f32_dpp v130, -v149, v98 row_newbcast:4 row_mask:0xf bank_mask:0xf
	v_fmac_f32_dpp v131, -v149, v99 row_newbcast:5 row_mask:0xf bank_mask:0xf
	v_fmac_f32_dpp v132, -v149, v100 row_newbcast:6 row_mask:0xf bank_mask:0xf
	v_fmac_f32_dpp v133, -v149, v97 row_newbcast:3 row_mask:0xf bank_mask:0xf
	v_fmac_f32_dpp v130, -v149, v102 row_newbcast:8 row_mask:0xf bank_mask:0xf
	v_fmac_f32_dpp v131, -v149, v103 row_newbcast:9 row_mask:0xf bank_mask:0xf
	v_fmac_f32_dpp v132, -v149, v104 row_newbcast:10 row_mask:0xf bank_mask:0xf
	v_fmac_f32_dpp v133, -v149, v101 row_newbcast:7 row_mask:0xf bank_mask:0xf
	v_fmac_f32_dpp v130, -v149, v106 row_newbcast:12 row_mask:0xf bank_mask:0xf
	v_fmac_f32_dpp v131, -v149, v107 row_newbcast:13 row_mask:0xf bank_mask:0xf
	v_fmac_f32_dpp v132, -v149, v108 row_newbcast:14 row_mask:0xf bank_mask:0xf
	v_fmac_f32_dpp v133, -v149, v105 row_newbcast:11 row_mask:0xf bank_mask:0xf
	v_fmac_f32_dpp v130, -v150, v110 row_newbcast:0 row_mask:0xf bank_mask:0xf
	v_fmac_f32_dpp v131, -v150, v111 row_newbcast:1 row_mask:0xf bank_mask:0xf
	v_fmac_f32_dpp v132, -v150, v112 row_newbcast:2 row_mask:0xf bank_mask:0xf
	v_fmac_f32_dpp v133, -v149, v109 row_newbcast:15 row_mask:0xf bank_mask:0xf
	v_fmac_f32_dpp v130, -v150, v114 row_newbcast:4 row_mask:0xf bank_mask:0xf
	v_fmac_f32_dpp v131, -v150, v115 row_newbcast:5 row_mask:0xf bank_mask:0xf
	v_fmac_f32_dpp v132, -v150, v116 row_newbcast:6 row_mask:0xf bank_mask:0xf
	v_fmac_f32_dpp v133, -v150, v113 row_newbcast:3 row_mask:0xf bank_mask:0xf
	v_fmac_f32_dpp v130, -v150, v118 row_newbcast:8 row_mask:0xf bank_mask:0xf
	v_fmac_f32_dpp v131, -v150, v119 row_newbcast:9 row_mask:0xf bank_mask:0xf
	v_fmac_f32_dpp v132, -v150, v120 row_newbcast:10 row_mask:0xf bank_mask:0xf
	v_fmac_f32_dpp v133, -v150, v117 row_newbcast:7 row_mask:0xf bank_mask:0xf
	v_fmac_f32_dpp v130, -v150, v122 row_newbcast:12 row_mask:0xf bank_mask:0xf
	v_fmac_f32_dpp v131, -v150, v123 row_newbcast:13 row_mask:0xf bank_mask:0xf
	v_fmac_f32_dpp v132, -v150, v124 row_newbcast:14 row_mask:0xf bank_mask:0xf
	v_fmac_f32_dpp v133, -v150, v121 row_newbcast:11 row_mask:0xf bank_mask:0xf
	v_fmac_f32_dpp v130, -v151, v126 row_newbcast:0 row_mask:0xf bank_mask:0xf
	v_fmac_f32_dpp v131, -v151, v127 row_newbcast:1 row_mask:0xf bank_mask:0xf
	v_fmac_f32_dpp v132, -v151, v128 row_newbcast:2 row_mask:0xf bank_mask:0xf
	v_fmac_f32_dpp v133, -v150, v125 row_newbcast:15 row_mask:0xf bank_mask:0xf
	s_nop 1
	v_fmac_f32_dpp v133, -v151, v129 row_newbcast:3 row_mask:0xf bank_mask:0xf
	v_cndmask_b32_e64 v134, 0, 1.0, vcc
	v_mov_b32_e32 v135, v18
	v_mov_b32_e32 v136, v18
	v_mov_b32_e32 v137, v18
	v_add_f32_e32 v2, v130, v131
	v_add_f32_e32 v3, v132, v133
	v_add_f32_e32 v80, v2, v3
	ds_read_b32 v148, v138 offset:2624
	ds_read_b32 v149, v138 offset:2688
	ds_read_b32 v150, v138 offset:2752
	ds_read_b32 v151, v138 offset:2816
	s_waitcnt lgkmcnt(8)
	v_cmp_eq_u32_e32 vcc, 12, v1
	v_fmac_f32_dpp v137, -v144, v81 row_newbcast:3 row_mask:0xf bank_mask:0xf
	v_fmac_f32_dpp v134, -v144, v82 row_newbcast:4 row_mask:0xf bank_mask:0xf
	v_fmac_f32_dpp v135, -v144, v83 row_newbcast:5 row_mask:0xf bank_mask:0xf
	v_fmac_f32_dpp v136, -v144, v80 row_newbcast:2 row_mask:0xf bank_mask:0xf
	v_fmac_f32_dpp v137, -v144, v85 row_newbcast:7 row_mask:0xf bank_mask:0xf
	v_fmac_f32_dpp v134, -v144, v86 row_newbcast:8 row_mask:0xf bank_mask:0xf
	v_fmac_f32_dpp v135, -v144, v87 row_newbcast:9 row_mask:0xf bank_mask:0xf
	v_fmac_f32_dpp v136, -v144, v84 row_newbcast:6 row_mask:0xf bank_mask:0xf
	v_fmac_f32_dpp v137, -v144, v89 row_newbcast:11 row_mask:0xf bank_mask:0xf
	v_fmac_f32_dpp v134, -v144, v90 row_newbcast:12 row_mask:0xf bank_mask:0xf
	v_fmac_f32_dpp v135, -v144, v91 row_newbcast:13 row_mask:0xf bank_mask:0xf
	v_fmac_f32_dpp v136, -v144, v88 row_newbcast:10 row_mask:0xf bank_mask:0xf
	v_fmac_f32_dpp v137, -v144, v93 row_newbcast:15 row_mask:0xf bank_mask:0xf
	v_fmac_f32_dpp v134, -v145, v94 row_newbcast:0 row_mask:0xf bank_mask:0xf
	v_fmac_f32_dpp v135, -v145, v95 row_newbcast:1 row_mask:0xf bank_mask:0xf
	v_fmac_f32_dpp v136, -v144, v92 row_newbcast:14 row_mask:0xf bank_mask:0xf
	v_fmac_f32_dpp v137, -v145, v97 row_newbcast:3 row_mask:0xf bank_mask:0xf
	v_fmac_f32_dpp v134, -v145, v98 row_newbcast:4 row_mask:0xf bank_mask:0xf
	v_fmac_f32_dpp v135, -v145, v99 row_newbcast:5 row_mask:0xf bank_mask:0xf
	v_fmac_f32_dpp v136, -v145, v96 row_newbcast:2 row_mask:0xf bank_mask:0xf
	v_fmac_f32_dpp v137, -v145, v101 row_newbcast:7 row_mask:0xf bank_mask:0xf
	v_fmac_f32_dpp v134, -v145, v102 row_newbcast:8 row_mask:0xf bank_mask:0xf
	v_fmac_f32_dpp v135, -v145, v103 row_newbcast:9 row_mask:0xf bank_mask:0xf
	v_fmac_f32_dpp v136, -v145, v100 row_newbcast:6 row_mask:0xf bank_mask:0xf
	v_fmac_f32_dpp v137, -v145, v105 row_newbcast:11 row_mask:0xf bank_mask:0xf
	v_fmac_f32_dpp v134, -v145, v106 row_newbcast:12 row_mask:0xf bank_mask:0xf
	v_fmac_f32_dpp v135, -v145, v107 row_newbcast:13 row_mask:0xf bank_mask:0xf
	v_fmac_f32_dpp v136, -v145, v104 row_newbcast:10 row_mask:0xf bank_mask:0xf
	v_fmac_f32_dpp v137, -v145, v109 row_newbcast:15 row_mask:0xf bank_mask:0xf
	v_fmac_f32_dpp v134, -v146, v110 row_newbcast:0 row_mask:0xf bank_mask:0xf
	v_fmac_f32_dpp v135, -v146, v111 row_newbcast:1 row_mask:0xf bank_mask:0xf
	v_fmac_f32_dpp v136, -v145, v108 row_newbcast:14 row_mask:0xf bank_mask:0xf
	v_fmac_f32_dpp v137, -v146, v113 row_newbcast:3 row_mask:0xf bank_mask:0xf
	v_fmac_f32_dpp v134, -v146, v114 row_newbcast:4 row_mask:0xf bank_mask:0xf
	v_fmac_f32_dpp v135, -v146, v115 row_newbcast:5 row_mask:0xf bank_mask:0xf
	v_fmac_f32_dpp v136, -v146, v112 row_newbcast:2 row_mask:0xf bank_mask:0xf
	v_fmac_f32_dpp v137, -v146, v117 row_newbcast:7 row_mask:0xf bank_mask:0xf
	v_fmac_f32_dpp v134, -v146, v118 row_newbcast:8 row_mask:0xf bank_mask:0xf
	v_fmac_f32_dpp v135, -v146, v119 row_newbcast:9 row_mask:0xf bank_mask:0xf
	v_fmac_f32_dpp v136, -v146, v116 row_newbcast:6 row_mask:0xf bank_mask:0xf
	v_fmac_f32_dpp v137, -v146, v121 row_newbcast:11 row_mask:0xf bank_mask:0xf
	v_fmac_f32_dpp v134, -v146, v122 row_newbcast:12 row_mask:0xf bank_mask:0xf
	v_fmac_f32_dpp v135, -v146, v123 row_newbcast:13 row_mask:0xf bank_mask:0xf
	v_fmac_f32_dpp v136, -v146, v120 row_newbcast:10 row_mask:0xf bank_mask:0xf
	v_fmac_f32_dpp v137, -v146, v125 row_newbcast:15 row_mask:0xf bank_mask:0xf
	v_fmac_f32_dpp v134, -v147, v126 row_newbcast:0 row_mask:0xf bank_mask:0xf
	v_fmac_f32_dpp v135, -v147, v127 row_newbcast:1 row_mask:0xf bank_mask:0xf
	v_fmac_f32_dpp v136, -v146, v124 row_newbcast:14 row_mask:0xf bank_mask:0xf
	v_fmac_f32_dpp v137, -v147, v129 row_newbcast:3 row_mask:0xf bank_mask:0xf
	s_nop 0
	v_fmac_f32_dpp v136, -v147, v128 row_newbcast:2 row_mask:0xf bank_mask:0xf
	v_cndmask_b32_e64 v130, 0, 1.0, vcc
	v_mov_b32_e32 v131, v18
	v_mov_b32_e32 v132, v18
	v_mov_b32_e32 v133, v18
	v_add_f32_e32 v2, v134, v135
	v_add_f32_e32 v3, v136, v137
	v_add_f32_e32 v79, v2, v3
	ds_read_b32 v144, v138 offset:2400
	ds_read_b32 v145, v138 offset:2464
	ds_read_b32 v146, v138 offset:2528
	ds_read_b32 v147, v138 offset:2592
	s_waitcnt lgkmcnt(8)
	v_cmp_eq_u32_e32 vcc, 11, v1
	v_fmac_f32_dpp v132, -v140, v80 row_newbcast:2 row_mask:0xf bank_mask:0xf
	v_fmac_f32_dpp v133, -v140, v81 row_newbcast:3 row_mask:0xf bank_mask:0xf
	v_fmac_f32_dpp v130, -v140, v82 row_newbcast:4 row_mask:0xf bank_mask:0xf
	v_fmac_f32_dpp v131, -v140, v79 row_newbcast:1 row_mask:0xf bank_mask:0xf
	v_fmac_f32_dpp v132, -v140, v84 row_newbcast:6 row_mask:0xf bank_mask:0xf
	v_fmac_f32_dpp v133, -v140, v85 row_newbcast:7 row_mask:0xf bank_mask:0xf
	v_fmac_f32_dpp v130, -v140, v86 row_newbcast:8 row_mask:0xf bank_mask:0xf
	v_fmac_f32_dpp v131, -v140, v83 row_newbcast:5 row_mask:0xf bank_mask:0xf
	v_fmac_f32_dpp v132, -v140, v88 row_newbcast:10 row_mask:0xf bank_mask:0xf
	v_fmac_f32_dpp v133, -v140, v89 row_newbcast:11 row_mask:0xf bank_mask:0xf
	v_fmac_f32_dpp v130, -v140, v90 row_newbcast:12 row_mask:0xf bank_mask:0xf
	v_fmac_f32_dpp v131, -v140, v87 row_newbcast:9 row_mask:0xf bank_mask:0xf
	v_fmac_f32_dpp v132, -v140, v92 row_newbcast:14 row_mask:0xf bank_mask:0xf
	v_fmac_f32_dpp v133, -v140, v93 row_newbcast:15 row_mask:0xf bank_mask:0xf
	v_fmac_f32_dpp v130, -v141, v94 row_newbcast:0 row_mask:0xf bank_mask:0xf
	v_fmac_f32_dpp v131, -v140, v91 row_newbcast:13 row_mask:0xf bank_mask:0xf
	v_fmac_f32_dpp v132, -v141, v96 row_newbcast:2 row_mask:0xf bank_mask:0xf
	v_fmac_f32_dpp v133, -v141, v97 row_newbcast:3 row_mask:0xf bank_mask:0xf
	v_fmac_f32_dpp v130, -v141, v98 row_newbcast:4 row_mask:0xf bank_mask:0xf
	v_fmac_f32_dpp v131, -v141, v95 row_newbcast:1 row_mask:0xf bank_mask:0xf
	v_fmac_f32_dpp v132, -v141, v100 row_newbcast:6 row_mask:0xf bank_mask:0xf
	v_fmac_f32_dpp v133, -v141, v101 row_newbcast:7 row_mask:0xf bank_mask:0xf
	v_fmac_f32_dpp v130, -v141, v102 row_newbcast:8 row_mask:0xf bank_mask:0xf
	v_fmac_f32_dpp v131, -v141, v99 row_newbcast:5 row_mask:0xf bank_mask:0xf
	v_fmac_f32_dpp v132, -v141, v104 row_newbcast:10 row_mask:0xf bank_mask:0xf
	v_fmac_f32_dpp v133, -v141, v105 row_newbcast:11 row_mask:0xf bank_mask:0xf
	v_fmac_f32_dpp v130, -v141, v106 row_newbcast:12 row_mask:0xf bank_mask:0xf
	v_fmac_f32_dpp v131, -v141, v103 row_newbcast:9 row_mask:0xf bank_mask:0xf
	v_fmac_f32_dpp v132, -v141, v108 row_newbcast:14 row_mask:0xf bank_mask:0xf
	v_fmac_f32_dpp v133, -v141, v109 row_newbcast:15 row_mask:0xf bank_mask:0xf
	v_fmac_f32_dpp v130, -v142, v110 row_newbcast:0 row_mask:0xf bank_mask:0xf
	v_fmac_f32_dpp v131, -v141, v107 row_newbcast:13 row_mask:0xf bank_mask:0xf
	v_fmac_f32_dpp v132, -v142, v112 row_newbcast:2 row_mask:0xf bank_mask:0xf
	v_fmac_f32_dpp v133, -v142, v113 row_newbcast:3 row_mask:0xf bank_mask:0xf
	v_fmac_f32_dpp v130, -v142, v114 row_newbcast:4 row_mask:0xf bank_mask:0xf
	v_fmac_f32_dpp v131, -v142, v111 row_newbcast:1 row_mask:0xf bank_mask:0xf
	v_fmac_f32_dpp v132, -v142, v116 row_newbcast:6 row_mask:0xf bank_mask:0xf
	v_fmac_f32_dpp v133, -v142, v117 row_newbcast:7 row_mask:0xf bank_mask:0xf
	v_fmac_f32_dpp v130, -v142, v118 row_newbcast:8 row_mask:0xf bank_mask:0xf
	v_fmac_f32_dpp v131, -v142, v115 row_newbcast:5 row_mask:0xf bank_mask:0xf
	v_fmac_f32_dpp v132, -v142, v120 row_newbcast:10 row_mask:0xf bank_mask:0xf
	v_fmac_f32_dpp v133, -v142, v121 row_newbcast:11 row_mask:0xf bank_mask:0xf
	v_fmac_f32_dpp v130, -v142, v122 row_newbcast:12 row_mask:0xf bank_mask:0xf
	v_fmac_f32_dpp v131, -v142, v119 row_newbcast:9 row_mask:0xf bank_mask:0xf
	v_fmac_f32_dpp v132, -v142, v124 row_newbcast:14 row_mask:0xf bank_mask:0xf
	v_fmac_f32_dpp v133, -v142, v125 row_newbcast:15 row_mask:0xf bank_mask:0xf
	v_fmac_f32_dpp v130, -v143, v126 row_newbcast:0 row_mask:0xf bank_mask:0xf
	v_fmac_f32_dpp v131, -v142, v123 row_newbcast:13 row_mask:0xf bank_mask:0xf
	v_fmac_f32_dpp v132, -v143, v128 row_newbcast:2 row_mask:0xf bank_mask:0xf
	v_fmac_f32_dpp v133, -v143, v129 row_newbcast:3 row_mask:0xf bank_mask:0xf
	v_fmac_f32_dpp v131, -v143, v127 row_newbcast:1 row_mask:0xf bank_mask:0xf
	v_cndmask_b32_e64 v134, 0, 1.0, vcc
	v_mov_b32_e32 v135, v18
	v_mov_b32_e32 v136, v18
	v_mov_b32_e32 v137, v18
	v_add_f32_e32 v2, v130, v131
	v_add_f32_e32 v3, v132, v133
	v_add_f32_e32 v78, v2, v3
	ds_read_b32 v140, v138 offset:2176
	ds_read_b32 v141, v138 offset:2240
	ds_read_b32 v142, v138 offset:2304
	ds_read_b32 v143, v138 offset:2368
	s_waitcnt lgkmcnt(8)
	v_cmp_eq_u32_e32 vcc, 10, v1
	v_fmac_f32_dpp v135, -v148, v79 row_newbcast:1 row_mask:0xf bank_mask:0xf
	v_fmac_f32_dpp v136, -v148, v80 row_newbcast:2 row_mask:0xf bank_mask:0xf
	v_fmac_f32_dpp v137, -v148, v81 row_newbcast:3 row_mask:0xf bank_mask:0xf
	v_fmac_f32_dpp v134, -v148, v78 row_newbcast:0 row_mask:0xf bank_mask:0xf
	v_fmac_f32_dpp v135, -v148, v83 row_newbcast:5 row_mask:0xf bank_mask:0xf
	v_fmac_f32_dpp v136, -v148, v84 row_newbcast:6 row_mask:0xf bank_mask:0xf
	v_fmac_f32_dpp v137, -v148, v85 row_newbcast:7 row_mask:0xf bank_mask:0xf
	v_fmac_f32_dpp v134, -v148, v82 row_newbcast:4 row_mask:0xf bank_mask:0xf
	v_fmac_f32_dpp v135, -v148, v87 row_newbcast:9 row_mask:0xf bank_mask:0xf
	v_fmac_f32_dpp v136, -v148, v88 row_newbcast:10 row_mask:0xf bank_mask:0xf
	v_fmac_f32_dpp v137, -v148, v89 row_newbcast:11 row_mask:0xf bank_mask:0xf
	v_fmac_f32_dpp v134, -v148, v86 row_newbcast:8 row_mask:0xf bank_mask:0xf
	v_fmac_f32_dpp v135, -v148, v91 row_newbcast:13 row_mask:0xf bank_mask:0xf
	v_fmac_f32_dpp v136, -v148, v92 row_newbcast:14 row_mask:0xf bank_mask:0xf
	v_fmac_f32_dpp v137, -v148, v93 row_newbcast:15 row_mask:0xf bank_mask:0xf
	v_fmac_f32_dpp v134, -v148, v90 row_newbcast:12 row_mask:0xf bank_mask:0xf
	v_fmac_f32_dpp v135, -v149, v95 row_newbcast:1 row_mask:0xf bank_mask:0xf
	v_fmac_f32_dpp v136, -v149, v96 row_newbcast:2 row_mask:0xf bank_mask:0xf
	v_fmac_f32_dpp v137, -v149, v97 row_newbcast:3 row_mask:0xf bank_mask:0xf
	v_fmac_f32_dpp v134, -v149, v94 row_newbcast:0 row_mask:0xf bank_mask:0xf
	v_fmac_f32_dpp v135, -v149, v99 row_newbcast:5 row_mask:0xf bank_mask:0xf
	v_fmac_f32_dpp v136, -v149, v100 row_newbcast:6 row_mask:0xf bank_mask:0xf
	v_fmac_f32_dpp v137, -v149, v101 row_newbcast:7 row_mask:0xf bank_mask:0xf
	v_fmac_f32_dpp v134, -v149, v98 row_newbcast:4 row_mask:0xf bank_mask:0xf
	v_fmac_f32_dpp v135, -v149, v103 row_newbcast:9 row_mask:0xf bank_mask:0xf
	v_fmac_f32_dpp v136, -v149, v104 row_newbcast:10 row_mask:0xf bank_mask:0xf
	v_fmac_f32_dpp v137, -v149, v105 row_newbcast:11 row_mask:0xf bank_mask:0xf
	v_fmac_f32_dpp v134, -v149, v102 row_newbcast:8 row_mask:0xf bank_mask:0xf
	v_fmac_f32_dpp v135, -v149, v107 row_newbcast:13 row_mask:0xf bank_mask:0xf
	v_fmac_f32_dpp v136, -v149, v108 row_newbcast:14 row_mask:0xf bank_mask:0xf
	v_fmac_f32_dpp v137, -v149, v109 row_newbcast:15 row_mask:0xf bank_mask:0xf
	v_fmac_f32_dpp v134, -v149, v106 row_newbcast:12 row_mask:0xf bank_mask:0xf
	v_fmac_f32_dpp v135, -v150, v111 row_newbcast:1 row_mask:0xf bank_mask:0xf
	v_fmac_f32_dpp v136, -v150, v112 row_newbcast:2 row_mask:0xf bank_mask:0xf
	v_fmac_f32_dpp v137, -v150, v113 row_newbcast:3 row_mask:0xf bank_mask:0xf
	v_fmac_f32_dpp v134, -v150, v110 row_newbcast:0 row_mask:0xf bank_mask:0xf
	v_fmac_f32_dpp v135, -v150, v115 row_newbcast:5 row_mask:0xf bank_mask:0xf
	v_fmac_f32_dpp v136, -v150, v116 row_newbcast:6 row_mask:0xf bank_mask:0xf
	v_fmac_f32_dpp v137, -v150, v117 row_newbcast:7 row_mask:0xf bank_mask:0xf
	v_fmac_f32_dpp v134, -v150, v114 row_newbcast:4 row_mask:0xf bank_mask:0xf
	v_fmac_f32_dpp v135, -v150, v119 row_newbcast:9 row_mask:0xf bank_mask:0xf
	v_fmac_f32_dpp v136, -v150, v120 row_newbcast:10 row_mask:0xf bank_mask:0xf
	v_fmac_f32_dpp v137, -v150, v121 row_newbcast:11 row_mask:0xf bank_mask:0xf
	v_fmac_f32_dpp v134, -v150, v118 row_newbcast:8 row_mask:0xf bank_mask:0xf
	v_fmac_f32_dpp v135, -v150, v123 row_newbcast:13 row_mask:0xf bank_mask:0xf
	v_fmac_f32_dpp v136, -v150, v124 row_newbcast:14 row_mask:0xf bank_mask:0xf
	v_fmac_f32_dpp v137, -v150, v125 row_newbcast:15 row_mask:0xf bank_mask:0xf
	v_fmac_f32_dpp v134, -v150, v122 row_newbcast:12 row_mask:0xf bank_mask:0xf
	v_fmac_f32_dpp v135, -v151, v127 row_newbcast:1 row_mask:0xf bank_mask:0xf
	v_fmac_f32_dpp v136, -v151, v128 row_newbcast:2 row_mask:0xf bank_mask:0xf
	v_fmac_f32_dpp v137, -v151, v129 row_newbcast:3 row_mask:0xf bank_mask:0xf
	v_fmac_f32_dpp v134, -v151, v126 row_newbcast:0 row_mask:0xf bank_mask:0xf
	v_cndmask_b32_e64 v130, 0, 1.0, vcc
	v_mov_b32_e32 v131, v18
	v_mov_b32_e32 v132, v18
	v_mov_b32_e32 v133, v18
	v_add_f32_e32 v2, v134, v135
	v_add_f32_e32 v3, v136, v137
	v_add_f32_e32 v77, v2, v3
	ds_read_b32 v148, v138 offset:1952
	ds_read_b32 v149, v138 offset:2016
	ds_read_b32 v150, v138 offset:2080
	ds_read_b32 v151, v138 offset:2144
	s_waitcnt lgkmcnt(8)
	v_cmp_eq_u32_e32 vcc, 9, v1
	v_fmac_f32_dpp v130, -v144, v78 row_newbcast:4 row_mask:0xf bank_mask:0xf
	v_fmac_f32_dpp v131, -v144, v79 row_newbcast:5 row_mask:0xf bank_mask:0xf
	v_fmac_f32_dpp v132, -v144, v80 row_newbcast:6 row_mask:0xf bank_mask:0xf
	v_fmac_f32_dpp v133, -v144, v77 row_newbcast:3 row_mask:0xf bank_mask:0xf
	v_fmac_f32_dpp v130, -v144, v82 row_newbcast:8 row_mask:0xf bank_mask:0xf
	v_fmac_f32_dpp v131, -v144, v83 row_newbcast:9 row_mask:0xf bank_mask:0xf
	v_fmac_f32_dpp v132, -v144, v84 row_newbcast:10 row_mask:0xf bank_mask:0xf
	v_fmac_f32_dpp v133, -v144, v81 row_newbcast:7 row_mask:0xf bank_mask:0xf
	v_fmac_f32_dpp v130, -v144, v86 row_newbcast:12 row_mask:0xf bank_mask:0xf
	v_fmac_f32_dpp v131, -v144, v87 row_newbcast:13 row_mask:0xf bank_mask:0xf
	v_fmac_f32_dpp v132, -v144, v88 row_newbcast:14 row_mask:0xf bank_mask:0xf
	v_fmac_f32_dpp v133, -v144, v85 row_newbcast:11 row_mask:0xf bank_mask:0xf
	v_fmac_f32_dpp v130, -v145, v90 row_newbcast:0 row_mask:0xf bank_mask:0xf
	v_fmac_f32_dpp v131, -v145, v91 row_newbcast:1 row_mask:0xf bank_mask:0xf
	v_fmac_f32_dpp v132, -v145, v92 row_newbcast:2 row_mask:0xf bank_mask:0xf
	v_fmac_f32_dpp v133, -v144, v89 row_newbcast:15 row_mask:0xf bank_mask:0xf
	v_fmac_f32_dpp v130, -v145, v94 row_newbcast:4 row_mask:0xf bank_mask:0xf
	v_fmac_f32_dpp v131, -v145, v95 row_newbcast:5 row_mask:0xf bank_mask:0xf
	v_fmac_f32_dpp v132, -v145, v96 row_newbcast:6 row_mask:0xf bank_mask:0xf
	v_fmac_f32_dpp v133, -v145, v93 row_newbcast:3 row_mask:0xf bank_mask:0xf
	v_fmac_f32_dpp v130, -v145, v98 row_newbcast:8 row_mask:0xf bank_mask:0xf
	v_fmac_f32_dpp v131, -v145, v99 row_newbcast:9 row_mask:0xf bank_mask:0xf
	v_fmac_f32_dpp v132, -v145, v100 row_newbcast:10 row_mask:0xf bank_mask:0xf
	v_fmac_f32_dpp v133, -v145, v97 row_newbcast:7 row_mask:0xf bank_mask:0xf
	v_fmac_f32_dpp v130, -v145, v102 row_newbcast:12 row_mask:0xf bank_mask:0xf
	v_fmac_f32_dpp v131, -v145, v103 row_newbcast:13 row_mask:0xf bank_mask:0xf
	v_fmac_f32_dpp v132, -v145, v104 row_newbcast:14 row_mask:0xf bank_mask:0xf
	v_fmac_f32_dpp v133, -v145, v101 row_newbcast:11 row_mask:0xf bank_mask:0xf
	v_fmac_f32_dpp v130, -v146, v106 row_newbcast:0 row_mask:0xf bank_mask:0xf
	v_fmac_f32_dpp v131, -v146, v107 row_newbcast:1 row_mask:0xf bank_mask:0xf
	v_fmac_f32_dpp v132, -v146, v108 row_newbcast:2 row_mask:0xf bank_mask:0xf
	v_fmac_f32_dpp v133, -v145, v105 row_newbcast:15 row_mask:0xf bank_mask:0xf
	v_fmac_f32_dpp v130, -v146, v110 row_newbcast:4 row_mask:0xf bank_mask:0xf
	v_fmac_f32_dpp v131, -v146, v111 row_newbcast:5 row_mask:0xf bank_mask:0xf
	v_fmac_f32_dpp v132, -v146, v112 row_newbcast:6 row_mask:0xf bank_mask:0xf
	v_fmac_f32_dpp v133, -v146, v109 row_newbcast:3 row_mask:0xf bank_mask:0xf
	v_fmac_f32_dpp v130, -v146, v114 row_newbcast:8 row_mask:0xf bank_mask:0xf
	v_fmac_f32_dpp v131, -v146, v115 row_newbcast:9 row_mask:0xf bank_mask:0xf
	v_fmac_f32_dpp v132, -v146, v116 row_newbcast:10 row_mask:0xf bank_mask:0xf
	v_fmac_f32_dpp v133, -v146, v113 row_newbcast:7 row_mask:0xf bank_mask:0xf
	v_fmac_f32_dpp v130, -v146, v118 row_newbcast:12 row_mask:0xf bank_mask:0xf
	v_fmac_f32_dpp v131, -v146, v119 row_newbcast:13 row_mask:0xf bank_mask:0xf
	v_fmac_f32_dpp v132, -v146, v120 row_newbcast:14 row_mask:0xf bank_mask:0xf
	v_fmac_f32_dpp v133, -v146, v117 row_newbcast:11 row_mask:0xf bank_mask:0xf
	v_fmac_f32_dpp v130, -v147, v122 row_newbcast:0 row_mask:0xf bank_mask:0xf
	v_fmac_f32_dpp v131, -v147, v123 row_newbcast:1 row_mask:0xf bank_mask:0xf
	v_fmac_f32_dpp v132, -v147, v124 row_newbcast:2 row_mask:0xf bank_mask:0xf
	v_fmac_f32_dpp v133, -v146, v121 row_newbcast:15 row_mask:0xf bank_mask:0xf
	v_fmac_f32_dpp v130, -v147, v126 row_newbcast:4 row_mask:0xf bank_mask:0xf
	v_fmac_f32_dpp v131, -v147, v127 row_newbcast:5 row_mask:0xf bank_mask:0xf
	v_fmac_f32_dpp v132, -v147, v128 row_newbcast:6 row_mask:0xf bank_mask:0xf
	v_fmac_f32_dpp v133, -v147, v125 row_newbcast:3 row_mask:0xf bank_mask:0xf
	s_nop 1
	v_fmac_f32_dpp v133, -v147, v129 row_newbcast:7 row_mask:0xf bank_mask:0xf
	v_cndmask_b32_e64 v134, 0, 1.0, vcc
	v_mov_b32_e32 v135, v18
	v_mov_b32_e32 v136, v18
	v_mov_b32_e32 v137, v18
	v_add_f32_e32 v2, v130, v131
	v_add_f32_e32 v3, v132, v133
	v_add_f32_e32 v76, v2, v3
	ds_read_b32 v144, v138 offset:1728
	ds_read_b32 v145, v138 offset:1792
	ds_read_b32 v146, v138 offset:1856
	ds_read_b32 v147, v138 offset:1920
	s_waitcnt lgkmcnt(8)
	v_cmp_eq_u32_e32 vcc, 8, v1
	v_fmac_f32_dpp v137, -v140, v77 row_newbcast:3 row_mask:0xf bank_mask:0xf
	v_fmac_f32_dpp v134, -v140, v78 row_newbcast:4 row_mask:0xf bank_mask:0xf
	v_fmac_f32_dpp v135, -v140, v79 row_newbcast:5 row_mask:0xf bank_mask:0xf
	v_fmac_f32_dpp v136, -v140, v76 row_newbcast:2 row_mask:0xf bank_mask:0xf
	v_fmac_f32_dpp v137, -v140, v81 row_newbcast:7 row_mask:0xf bank_mask:0xf
	v_fmac_f32_dpp v134, -v140, v82 row_newbcast:8 row_mask:0xf bank_mask:0xf
	v_fmac_f32_dpp v135, -v140, v83 row_newbcast:9 row_mask:0xf bank_mask:0xf
	v_fmac_f32_dpp v136, -v140, v80 row_newbcast:6 row_mask:0xf bank_mask:0xf
	v_fmac_f32_dpp v137, -v140, v85 row_newbcast:11 row_mask:0xf bank_mask:0xf
	v_fmac_f32_dpp v134, -v140, v86 row_newbcast:12 row_mask:0xf bank_mask:0xf
	v_fmac_f32_dpp v135, -v140, v87 row_newbcast:13 row_mask:0xf bank_mask:0xf
	v_fmac_f32_dpp v136, -v140, v84 row_newbcast:10 row_mask:0xf bank_mask:0xf
	v_fmac_f32_dpp v137, -v140, v89 row_newbcast:15 row_mask:0xf bank_mask:0xf
	v_fmac_f32_dpp v134, -v141, v90 row_newbcast:0 row_mask:0xf bank_mask:0xf
	v_fmac_f32_dpp v135, -v141, v91 row_newbcast:1 row_mask:0xf bank_mask:0xf
	v_fmac_f32_dpp v136, -v140, v88 row_newbcast:14 row_mask:0xf bank_mask:0xf
	v_fmac_f32_dpp v137, -v141, v93 row_newbcast:3 row_mask:0xf bank_mask:0xf
	v_fmac_f32_dpp v134, -v141, v94 row_newbcast:4 row_mask:0xf bank_mask:0xf
	v_fmac_f32_dpp v135, -v141, v95 row_newbcast:5 row_mask:0xf bank_mask:0xf
	v_fmac_f32_dpp v136, -v141, v92 row_newbcast:2 row_mask:0xf bank_mask:0xf
	v_fmac_f32_dpp v137, -v141, v97 row_newbcast:7 row_mask:0xf bank_mask:0xf
	v_fmac_f32_dpp v134, -v141, v98 row_newbcast:8 row_mask:0xf bank_mask:0xf
	v_fmac_f32_dpp v135, -v141, v99 row_newbcast:9 row_mask:0xf bank_mask:0xf
	v_fmac_f32_dpp v136, -v141, v96 row_newbcast:6 row_mask:0xf bank_mask:0xf
	v_fmac_f32_dpp v137, -v141, v101 row_newbcast:11 row_mask:0xf bank_mask:0xf
	v_fmac_f32_dpp v134, -v141, v102 row_newbcast:12 row_mask:0xf bank_mask:0xf
	v_fmac_f32_dpp v135, -v141, v103 row_newbcast:13 row_mask:0xf bank_mask:0xf
	v_fmac_f32_dpp v136, -v141, v100 row_newbcast:10 row_mask:0xf bank_mask:0xf
	v_fmac_f32_dpp v137, -v141, v105 row_newbcast:15 row_mask:0xf bank_mask:0xf
	v_fmac_f32_dpp v134, -v142, v106 row_newbcast:0 row_mask:0xf bank_mask:0xf
	v_fmac_f32_dpp v135, -v142, v107 row_newbcast:1 row_mask:0xf bank_mask:0xf
	v_fmac_f32_dpp v136, -v141, v104 row_newbcast:14 row_mask:0xf bank_mask:0xf
	v_fmac_f32_dpp v137, -v142, v109 row_newbcast:3 row_mask:0xf bank_mask:0xf
	v_fmac_f32_dpp v134, -v142, v110 row_newbcast:4 row_mask:0xf bank_mask:0xf
	v_fmac_f32_dpp v135, -v142, v111 row_newbcast:5 row_mask:0xf bank_mask:0xf
	v_fmac_f32_dpp v136, -v142, v108 row_newbcast:2 row_mask:0xf bank_mask:0xf
	v_fmac_f32_dpp v137, -v142, v113 row_newbcast:7 row_mask:0xf bank_mask:0xf
	v_fmac_f32_dpp v134, -v142, v114 row_newbcast:8 row_mask:0xf bank_mask:0xf
	v_fmac_f32_dpp v135, -v142, v115 row_newbcast:9 row_mask:0xf bank_mask:0xf
	v_fmac_f32_dpp v136, -v142, v112 row_newbcast:6 row_mask:0xf bank_mask:0xf
	v_fmac_f32_dpp v137, -v142, v117 row_newbcast:11 row_mask:0xf bank_mask:0xf
	v_fmac_f32_dpp v134, -v142, v118 row_newbcast:12 row_mask:0xf bank_mask:0xf
	v_fmac_f32_dpp v135, -v142, v119 row_newbcast:13 row_mask:0xf bank_mask:0xf
	v_fmac_f32_dpp v136, -v142, v116 row_newbcast:10 row_mask:0xf bank_mask:0xf
	v_fmac_f32_dpp v137, -v142, v121 row_newbcast:15 row_mask:0xf bank_mask:0xf
	v_fmac_f32_dpp v134, -v143, v122 row_newbcast:0 row_mask:0xf bank_mask:0xf
	v_fmac_f32_dpp v135, -v143, v123 row_newbcast:1 row_mask:0xf bank_mask:0xf
	v_fmac_f32_dpp v136, -v142, v120 row_newbcast:14 row_mask:0xf bank_mask:0xf
	v_fmac_f32_dpp v137, -v143, v125 row_newbcast:3 row_mask:0xf bank_mask:0xf
	v_fmac_f32_dpp v134, -v143, v126 row_newbcast:4 row_mask:0xf bank_mask:0xf
	v_fmac_f32_dpp v135, -v143, v127 row_newbcast:5 row_mask:0xf bank_mask:0xf
	v_fmac_f32_dpp v136, -v143, v124 row_newbcast:2 row_mask:0xf bank_mask:0xf
	v_fmac_f32_dpp v137, -v143, v129 row_newbcast:7 row_mask:0xf bank_mask:0xf
	s_nop 0
	v_fmac_f32_dpp v136, -v143, v128 row_newbcast:6 row_mask:0xf bank_mask:0xf
	v_cndmask_b32_e64 v130, 0, 1.0, vcc
	v_mov_b32_e32 v131, v18
	v_mov_b32_e32 v132, v18
	v_mov_b32_e32 v133, v18
	v_add_f32_e32 v2, v134, v135
	v_add_f32_e32 v3, v136, v137
	v_add_f32_e32 v75, v2, v3
	ds_read_b32 v140, v138 offset:1488
	ds_read_b32 v141, v138 offset:1552
	ds_read_b32 v142, v138 offset:1616
	ds_read_b32 v143, v138 offset:1680
	s_waitcnt lgkmcnt(8)
	v_cmp_eq_u32_e32 vcc, 7, v1
	v_fmac_f32_dpp v132, -v148, v76 row_newbcast:2 row_mask:0xf bank_mask:0xf
	v_fmac_f32_dpp v133, -v148, v77 row_newbcast:3 row_mask:0xf bank_mask:0xf
	v_fmac_f32_dpp v130, -v148, v78 row_newbcast:4 row_mask:0xf bank_mask:0xf
	v_fmac_f32_dpp v131, -v148, v75 row_newbcast:1 row_mask:0xf bank_mask:0xf
	v_fmac_f32_dpp v132, -v148, v80 row_newbcast:6 row_mask:0xf bank_mask:0xf
	v_fmac_f32_dpp v133, -v148, v81 row_newbcast:7 row_mask:0xf bank_mask:0xf
	v_fmac_f32_dpp v130, -v148, v82 row_newbcast:8 row_mask:0xf bank_mask:0xf
	v_fmac_f32_dpp v131, -v148, v79 row_newbcast:5 row_mask:0xf bank_mask:0xf
	v_fmac_f32_dpp v132, -v148, v84 row_newbcast:10 row_mask:0xf bank_mask:0xf
	v_fmac_f32_dpp v133, -v148, v85 row_newbcast:11 row_mask:0xf bank_mask:0xf
	v_fmac_f32_dpp v130, -v148, v86 row_newbcast:12 row_mask:0xf bank_mask:0xf
	v_fmac_f32_dpp v131, -v148, v83 row_newbcast:9 row_mask:0xf bank_mask:0xf
	v_fmac_f32_dpp v132, -v148, v88 row_newbcast:14 row_mask:0xf bank_mask:0xf
	v_fmac_f32_dpp v133, -v148, v89 row_newbcast:15 row_mask:0xf bank_mask:0xf
	v_fmac_f32_dpp v130, -v149, v90 row_newbcast:0 row_mask:0xf bank_mask:0xf
	v_fmac_f32_dpp v131, -v148, v87 row_newbcast:13 row_mask:0xf bank_mask:0xf
	v_fmac_f32_dpp v132, -v149, v92 row_newbcast:2 row_mask:0xf bank_mask:0xf
	v_fmac_f32_dpp v133, -v149, v93 row_newbcast:3 row_mask:0xf bank_mask:0xf
	v_fmac_f32_dpp v130, -v149, v94 row_newbcast:4 row_mask:0xf bank_mask:0xf
	v_fmac_f32_dpp v131, -v149, v91 row_newbcast:1 row_mask:0xf bank_mask:0xf
	v_fmac_f32_dpp v132, -v149, v96 row_newbcast:6 row_mask:0xf bank_mask:0xf
	v_fmac_f32_dpp v133, -v149, v97 row_newbcast:7 row_mask:0xf bank_mask:0xf
	v_fmac_f32_dpp v130, -v149, v98 row_newbcast:8 row_mask:0xf bank_mask:0xf
	v_fmac_f32_dpp v131, -v149, v95 row_newbcast:5 row_mask:0xf bank_mask:0xf
	v_fmac_f32_dpp v132, -v149, v100 row_newbcast:10 row_mask:0xf bank_mask:0xf
	v_fmac_f32_dpp v133, -v149, v101 row_newbcast:11 row_mask:0xf bank_mask:0xf
	v_fmac_f32_dpp v130, -v149, v102 row_newbcast:12 row_mask:0xf bank_mask:0xf
	v_fmac_f32_dpp v131, -v149, v99 row_newbcast:9 row_mask:0xf bank_mask:0xf
	v_fmac_f32_dpp v132, -v149, v104 row_newbcast:14 row_mask:0xf bank_mask:0xf
	v_fmac_f32_dpp v133, -v149, v105 row_newbcast:15 row_mask:0xf bank_mask:0xf
	v_fmac_f32_dpp v130, -v150, v106 row_newbcast:0 row_mask:0xf bank_mask:0xf
	v_fmac_f32_dpp v131, -v149, v103 row_newbcast:13 row_mask:0xf bank_mask:0xf
	v_fmac_f32_dpp v132, -v150, v108 row_newbcast:2 row_mask:0xf bank_mask:0xf
	v_fmac_f32_dpp v133, -v150, v109 row_newbcast:3 row_mask:0xf bank_mask:0xf
	v_fmac_f32_dpp v130, -v150, v110 row_newbcast:4 row_mask:0xf bank_mask:0xf
	v_fmac_f32_dpp v131, -v150, v107 row_newbcast:1 row_mask:0xf bank_mask:0xf
	v_fmac_f32_dpp v132, -v150, v112 row_newbcast:6 row_mask:0xf bank_mask:0xf
	v_fmac_f32_dpp v133, -v150, v113 row_newbcast:7 row_mask:0xf bank_mask:0xf
	v_fmac_f32_dpp v130, -v150, v114 row_newbcast:8 row_mask:0xf bank_mask:0xf
	v_fmac_f32_dpp v131, -v150, v111 row_newbcast:5 row_mask:0xf bank_mask:0xf
	v_fmac_f32_dpp v132, -v150, v116 row_newbcast:10 row_mask:0xf bank_mask:0xf
	v_fmac_f32_dpp v133, -v150, v117 row_newbcast:11 row_mask:0xf bank_mask:0xf
	v_fmac_f32_dpp v130, -v150, v118 row_newbcast:12 row_mask:0xf bank_mask:0xf
	v_fmac_f32_dpp v131, -v150, v115 row_newbcast:9 row_mask:0xf bank_mask:0xf
	v_fmac_f32_dpp v132, -v150, v120 row_newbcast:14 row_mask:0xf bank_mask:0xf
	v_fmac_f32_dpp v133, -v150, v121 row_newbcast:15 row_mask:0xf bank_mask:0xf
	v_fmac_f32_dpp v130, -v151, v122 row_newbcast:0 row_mask:0xf bank_mask:0xf
	v_fmac_f32_dpp v131, -v150, v119 row_newbcast:13 row_mask:0xf bank_mask:0xf
	v_fmac_f32_dpp v132, -v151, v124 row_newbcast:2 row_mask:0xf bank_mask:0xf
	v_fmac_f32_dpp v133, -v151, v125 row_newbcast:3 row_mask:0xf bank_mask:0xf
	v_fmac_f32_dpp v130, -v151, v126 row_newbcast:4 row_mask:0xf bank_mask:0xf
	v_fmac_f32_dpp v131, -v151, v123 row_newbcast:1 row_mask:0xf bank_mask:0xf
	v_fmac_f32_dpp v132, -v151, v128 row_newbcast:6 row_mask:0xf bank_mask:0xf
	v_fmac_f32_dpp v133, -v151, v129 row_newbcast:7 row_mask:0xf bank_mask:0xf
	v_fmac_f32_dpp v131, -v151, v127 row_newbcast:5 row_mask:0xf bank_mask:0xf
	v_cndmask_b32_e64 v134, 0, 1.0, vcc
	v_mov_b32_e32 v135, v18
	v_mov_b32_e32 v136, v18
	v_mov_b32_e32 v137, v18
	v_add_f32_e32 v2, v130, v131
	v_add_f32_e32 v3, v132, v133
	v_add_f32_e32 v74, v2, v3
	ds_read_b32 v148, v138 offset:1248
	ds_read_b32 v149, v138 offset:1312
	ds_read_b32 v150, v138 offset:1376
	ds_read_b32 v151, v138 offset:1440
	s_waitcnt lgkmcnt(8)
	v_cmp_eq_u32_e32 vcc, 6, v1
	v_fmac_f32_dpp v135, -v144, v75 row_newbcast:1 row_mask:0xf bank_mask:0xf
	v_fmac_f32_dpp v136, -v144, v76 row_newbcast:2 row_mask:0xf bank_mask:0xf
	v_fmac_f32_dpp v137, -v144, v77 row_newbcast:3 row_mask:0xf bank_mask:0xf
	v_fmac_f32_dpp v134, -v144, v74 row_newbcast:0 row_mask:0xf bank_mask:0xf
	v_fmac_f32_dpp v135, -v144, v79 row_newbcast:5 row_mask:0xf bank_mask:0xf
	v_fmac_f32_dpp v136, -v144, v80 row_newbcast:6 row_mask:0xf bank_mask:0xf
	v_fmac_f32_dpp v137, -v144, v81 row_newbcast:7 row_mask:0xf bank_mask:0xf
	v_fmac_f32_dpp v134, -v144, v78 row_newbcast:4 row_mask:0xf bank_mask:0xf
	v_fmac_f32_dpp v135, -v144, v83 row_newbcast:9 row_mask:0xf bank_mask:0xf
	v_fmac_f32_dpp v136, -v144, v84 row_newbcast:10 row_mask:0xf bank_mask:0xf
	v_fmac_f32_dpp v137, -v144, v85 row_newbcast:11 row_mask:0xf bank_mask:0xf
	v_fmac_f32_dpp v134, -v144, v82 row_newbcast:8 row_mask:0xf bank_mask:0xf
	v_fmac_f32_dpp v135, -v144, v87 row_newbcast:13 row_mask:0xf bank_mask:0xf
	v_fmac_f32_dpp v136, -v144, v88 row_newbcast:14 row_mask:0xf bank_mask:0xf
	v_fmac_f32_dpp v137, -v144, v89 row_newbcast:15 row_mask:0xf bank_mask:0xf
	v_fmac_f32_dpp v134, -v144, v86 row_newbcast:12 row_mask:0xf bank_mask:0xf
	v_fmac_f32_dpp v135, -v145, v91 row_newbcast:1 row_mask:0xf bank_mask:0xf
	v_fmac_f32_dpp v136, -v145, v92 row_newbcast:2 row_mask:0xf bank_mask:0xf
	v_fmac_f32_dpp v137, -v145, v93 row_newbcast:3 row_mask:0xf bank_mask:0xf
	v_fmac_f32_dpp v134, -v145, v90 row_newbcast:0 row_mask:0xf bank_mask:0xf
	v_fmac_f32_dpp v135, -v145, v95 row_newbcast:5 row_mask:0xf bank_mask:0xf
	v_fmac_f32_dpp v136, -v145, v96 row_newbcast:6 row_mask:0xf bank_mask:0xf
	v_fmac_f32_dpp v137, -v145, v97 row_newbcast:7 row_mask:0xf bank_mask:0xf
	v_fmac_f32_dpp v134, -v145, v94 row_newbcast:4 row_mask:0xf bank_mask:0xf
	v_fmac_f32_dpp v135, -v145, v99 row_newbcast:9 row_mask:0xf bank_mask:0xf
	v_fmac_f32_dpp v136, -v145, v100 row_newbcast:10 row_mask:0xf bank_mask:0xf
	v_fmac_f32_dpp v137, -v145, v101 row_newbcast:11 row_mask:0xf bank_mask:0xf
	v_fmac_f32_dpp v134, -v145, v98 row_newbcast:8 row_mask:0xf bank_mask:0xf
	v_fmac_f32_dpp v135, -v145, v103 row_newbcast:13 row_mask:0xf bank_mask:0xf
	v_fmac_f32_dpp v136, -v145, v104 row_newbcast:14 row_mask:0xf bank_mask:0xf
	v_fmac_f32_dpp v137, -v145, v105 row_newbcast:15 row_mask:0xf bank_mask:0xf
	v_fmac_f32_dpp v134, -v145, v102 row_newbcast:12 row_mask:0xf bank_mask:0xf
	v_fmac_f32_dpp v135, -v146, v107 row_newbcast:1 row_mask:0xf bank_mask:0xf
	v_fmac_f32_dpp v136, -v146, v108 row_newbcast:2 row_mask:0xf bank_mask:0xf
	v_fmac_f32_dpp v137, -v146, v109 row_newbcast:3 row_mask:0xf bank_mask:0xf
	v_fmac_f32_dpp v134, -v146, v106 row_newbcast:0 row_mask:0xf bank_mask:0xf
	v_fmac_f32_dpp v135, -v146, v111 row_newbcast:5 row_mask:0xf bank_mask:0xf
	v_fmac_f32_dpp v136, -v146, v112 row_newbcast:6 row_mask:0xf bank_mask:0xf
	v_fmac_f32_dpp v137, -v146, v113 row_newbcast:7 row_mask:0xf bank_mask:0xf
	v_fmac_f32_dpp v134, -v146, v110 row_newbcast:4 row_mask:0xf bank_mask:0xf
	v_fmac_f32_dpp v135, -v146, v115 row_newbcast:9 row_mask:0xf bank_mask:0xf
	v_fmac_f32_dpp v136, -v146, v116 row_newbcast:10 row_mask:0xf bank_mask:0xf
	v_fmac_f32_dpp v137, -v146, v117 row_newbcast:11 row_mask:0xf bank_mask:0xf
	v_fmac_f32_dpp v134, -v146, v114 row_newbcast:8 row_mask:0xf bank_mask:0xf
	v_fmac_f32_dpp v135, -v146, v119 row_newbcast:13 row_mask:0xf bank_mask:0xf
	v_fmac_f32_dpp v136, -v146, v120 row_newbcast:14 row_mask:0xf bank_mask:0xf
	v_fmac_f32_dpp v137, -v146, v121 row_newbcast:15 row_mask:0xf bank_mask:0xf
	v_fmac_f32_dpp v134, -v146, v118 row_newbcast:12 row_mask:0xf bank_mask:0xf
	v_fmac_f32_dpp v135, -v147, v123 row_newbcast:1 row_mask:0xf bank_mask:0xf
	v_fmac_f32_dpp v136, -v147, v124 row_newbcast:2 row_mask:0xf bank_mask:0xf
	v_fmac_f32_dpp v137, -v147, v125 row_newbcast:3 row_mask:0xf bank_mask:0xf
	v_fmac_f32_dpp v134, -v147, v122 row_newbcast:0 row_mask:0xf bank_mask:0xf
	v_fmac_f32_dpp v135, -v147, v127 row_newbcast:5 row_mask:0xf bank_mask:0xf
	v_fmac_f32_dpp v136, -v147, v128 row_newbcast:6 row_mask:0xf bank_mask:0xf
	v_fmac_f32_dpp v137, -v147, v129 row_newbcast:7 row_mask:0xf bank_mask:0xf
	v_fmac_f32_dpp v134, -v147, v126 row_newbcast:4 row_mask:0xf bank_mask:0xf
	v_cndmask_b32_e64 v130, 0, 1.0, vcc
	v_mov_b32_e32 v131, v18
	v_mov_b32_e32 v132, v18
	v_mov_b32_e32 v133, v18
	v_add_f32_e32 v2, v134, v135
	v_add_f32_e32 v3, v136, v137
	v_add_f32_e32 v73, v2, v3
	ds_read_b32 v144, v138 offset:1008
	ds_read_b32 v145, v138 offset:1072
	ds_read_b32 v146, v138 offset:1136
	ds_read_b32 v147, v138 offset:1200
	s_waitcnt lgkmcnt(8)
	v_cmp_eq_u32_e32 vcc, 5, v1
	v_fmac_f32_dpp v130, -v140, v74 row_newbcast:4 row_mask:0xf bank_mask:0xf
	v_fmac_f32_dpp v131, -v140, v75 row_newbcast:5 row_mask:0xf bank_mask:0xf
	v_fmac_f32_dpp v132, -v140, v76 row_newbcast:6 row_mask:0xf bank_mask:0xf
	v_fmac_f32_dpp v133, -v140, v73 row_newbcast:3 row_mask:0xf bank_mask:0xf
	v_fmac_f32_dpp v130, -v140, v78 row_newbcast:8 row_mask:0xf bank_mask:0xf
	v_fmac_f32_dpp v131, -v140, v79 row_newbcast:9 row_mask:0xf bank_mask:0xf
	v_fmac_f32_dpp v132, -v140, v80 row_newbcast:10 row_mask:0xf bank_mask:0xf
	v_fmac_f32_dpp v133, -v140, v77 row_newbcast:7 row_mask:0xf bank_mask:0xf
	v_fmac_f32_dpp v130, -v140, v82 row_newbcast:12 row_mask:0xf bank_mask:0xf
	v_fmac_f32_dpp v131, -v140, v83 row_newbcast:13 row_mask:0xf bank_mask:0xf
	v_fmac_f32_dpp v132, -v140, v84 row_newbcast:14 row_mask:0xf bank_mask:0xf
	v_fmac_f32_dpp v133, -v140, v81 row_newbcast:11 row_mask:0xf bank_mask:0xf
	v_fmac_f32_dpp v130, -v141, v86 row_newbcast:0 row_mask:0xf bank_mask:0xf
	v_fmac_f32_dpp v131, -v141, v87 row_newbcast:1 row_mask:0xf bank_mask:0xf
	v_fmac_f32_dpp v132, -v141, v88 row_newbcast:2 row_mask:0xf bank_mask:0xf
	v_fmac_f32_dpp v133, -v140, v85 row_newbcast:15 row_mask:0xf bank_mask:0xf
	v_fmac_f32_dpp v130, -v141, v90 row_newbcast:4 row_mask:0xf bank_mask:0xf
	v_fmac_f32_dpp v131, -v141, v91 row_newbcast:5 row_mask:0xf bank_mask:0xf
	v_fmac_f32_dpp v132, -v141, v92 row_newbcast:6 row_mask:0xf bank_mask:0xf
	v_fmac_f32_dpp v133, -v141, v89 row_newbcast:3 row_mask:0xf bank_mask:0xf
	v_fmac_f32_dpp v130, -v141, v94 row_newbcast:8 row_mask:0xf bank_mask:0xf
	v_fmac_f32_dpp v131, -v141, v95 row_newbcast:9 row_mask:0xf bank_mask:0xf
	v_fmac_f32_dpp v132, -v141, v96 row_newbcast:10 row_mask:0xf bank_mask:0xf
	v_fmac_f32_dpp v133, -v141, v93 row_newbcast:7 row_mask:0xf bank_mask:0xf
	v_fmac_f32_dpp v130, -v141, v98 row_newbcast:12 row_mask:0xf bank_mask:0xf
	v_fmac_f32_dpp v131, -v141, v99 row_newbcast:13 row_mask:0xf bank_mask:0xf
	v_fmac_f32_dpp v132, -v141, v100 row_newbcast:14 row_mask:0xf bank_mask:0xf
	v_fmac_f32_dpp v133, -v141, v97 row_newbcast:11 row_mask:0xf bank_mask:0xf
	v_fmac_f32_dpp v130, -v142, v102 row_newbcast:0 row_mask:0xf bank_mask:0xf
	v_fmac_f32_dpp v131, -v142, v103 row_newbcast:1 row_mask:0xf bank_mask:0xf
	v_fmac_f32_dpp v132, -v142, v104 row_newbcast:2 row_mask:0xf bank_mask:0xf
	v_fmac_f32_dpp v133, -v141, v101 row_newbcast:15 row_mask:0xf bank_mask:0xf
	v_fmac_f32_dpp v130, -v142, v106 row_newbcast:4 row_mask:0xf bank_mask:0xf
	v_fmac_f32_dpp v131, -v142, v107 row_newbcast:5 row_mask:0xf bank_mask:0xf
	v_fmac_f32_dpp v132, -v142, v108 row_newbcast:6 row_mask:0xf bank_mask:0xf
	v_fmac_f32_dpp v133, -v142, v105 row_newbcast:3 row_mask:0xf bank_mask:0xf
	v_fmac_f32_dpp v130, -v142, v110 row_newbcast:8 row_mask:0xf bank_mask:0xf
	v_fmac_f32_dpp v131, -v142, v111 row_newbcast:9 row_mask:0xf bank_mask:0xf
	v_fmac_f32_dpp v132, -v142, v112 row_newbcast:10 row_mask:0xf bank_mask:0xf
	v_fmac_f32_dpp v133, -v142, v109 row_newbcast:7 row_mask:0xf bank_mask:0xf
	v_fmac_f32_dpp v130, -v142, v114 row_newbcast:12 row_mask:0xf bank_mask:0xf
	v_fmac_f32_dpp v131, -v142, v115 row_newbcast:13 row_mask:0xf bank_mask:0xf
	v_fmac_f32_dpp v132, -v142, v116 row_newbcast:14 row_mask:0xf bank_mask:0xf
	v_fmac_f32_dpp v133, -v142, v113 row_newbcast:11 row_mask:0xf bank_mask:0xf
	v_fmac_f32_dpp v130, -v143, v118 row_newbcast:0 row_mask:0xf bank_mask:0xf
	v_fmac_f32_dpp v131, -v143, v119 row_newbcast:1 row_mask:0xf bank_mask:0xf
	v_fmac_f32_dpp v132, -v143, v120 row_newbcast:2 row_mask:0xf bank_mask:0xf
	v_fmac_f32_dpp v133, -v142, v117 row_newbcast:15 row_mask:0xf bank_mask:0xf
	v_fmac_f32_dpp v130, -v143, v122 row_newbcast:4 row_mask:0xf bank_mask:0xf
	v_fmac_f32_dpp v131, -v143, v123 row_newbcast:5 row_mask:0xf bank_mask:0xf
	v_fmac_f32_dpp v132, -v143, v124 row_newbcast:6 row_mask:0xf bank_mask:0xf
	v_fmac_f32_dpp v133, -v143, v121 row_newbcast:3 row_mask:0xf bank_mask:0xf
	v_fmac_f32_dpp v130, -v143, v126 row_newbcast:8 row_mask:0xf bank_mask:0xf
	v_fmac_f32_dpp v131, -v143, v127 row_newbcast:9 row_mask:0xf bank_mask:0xf
	v_fmac_f32_dpp v132, -v143, v128 row_newbcast:10 row_mask:0xf bank_mask:0xf
	v_fmac_f32_dpp v133, -v143, v125 row_newbcast:7 row_mask:0xf bank_mask:0xf
	s_nop 1
	v_fmac_f32_dpp v133, -v143, v129 row_newbcast:11 row_mask:0xf bank_mask:0xf
	v_cndmask_b32_e64 v134, 0, 1.0, vcc
	v_mov_b32_e32 v135, v18
	v_mov_b32_e32 v136, v18
	v_mov_b32_e32 v137, v18
	v_add_f32_e32 v2, v130, v131
	v_add_f32_e32 v3, v132, v133
	v_add_f32_e32 v72, v2, v3
	ds_read_b32 v140, v138 offset:768
	ds_read_b32 v141, v138 offset:832
	ds_read_b32 v142, v138 offset:896
	ds_read_b32 v143, v138 offset:960
	s_waitcnt lgkmcnt(8)
	v_cmp_eq_u32_e32 vcc, 4, v1
	v_fmac_f32_dpp v137, -v148, v73 row_newbcast:3 row_mask:0xf bank_mask:0xf
	v_fmac_f32_dpp v134, -v148, v74 row_newbcast:4 row_mask:0xf bank_mask:0xf
	v_fmac_f32_dpp v135, -v148, v75 row_newbcast:5 row_mask:0xf bank_mask:0xf
	v_fmac_f32_dpp v136, -v148, v72 row_newbcast:2 row_mask:0xf bank_mask:0xf
	v_fmac_f32_dpp v137, -v148, v77 row_newbcast:7 row_mask:0xf bank_mask:0xf
	v_fmac_f32_dpp v134, -v148, v78 row_newbcast:8 row_mask:0xf bank_mask:0xf
	v_fmac_f32_dpp v135, -v148, v79 row_newbcast:9 row_mask:0xf bank_mask:0xf
	v_fmac_f32_dpp v136, -v148, v76 row_newbcast:6 row_mask:0xf bank_mask:0xf
	v_fmac_f32_dpp v137, -v148, v81 row_newbcast:11 row_mask:0xf bank_mask:0xf
	v_fmac_f32_dpp v134, -v148, v82 row_newbcast:12 row_mask:0xf bank_mask:0xf
	v_fmac_f32_dpp v135, -v148, v83 row_newbcast:13 row_mask:0xf bank_mask:0xf
	v_fmac_f32_dpp v136, -v148, v80 row_newbcast:10 row_mask:0xf bank_mask:0xf
	v_fmac_f32_dpp v137, -v148, v85 row_newbcast:15 row_mask:0xf bank_mask:0xf
	v_fmac_f32_dpp v134, -v149, v86 row_newbcast:0 row_mask:0xf bank_mask:0xf
	v_fmac_f32_dpp v135, -v149, v87 row_newbcast:1 row_mask:0xf bank_mask:0xf
	v_fmac_f32_dpp v136, -v148, v84 row_newbcast:14 row_mask:0xf bank_mask:0xf
	v_fmac_f32_dpp v137, -v149, v89 row_newbcast:3 row_mask:0xf bank_mask:0xf
	v_fmac_f32_dpp v134, -v149, v90 row_newbcast:4 row_mask:0xf bank_mask:0xf
	v_fmac_f32_dpp v135, -v149, v91 row_newbcast:5 row_mask:0xf bank_mask:0xf
	v_fmac_f32_dpp v136, -v149, v88 row_newbcast:2 row_mask:0xf bank_mask:0xf
	v_fmac_f32_dpp v137, -v149, v93 row_newbcast:7 row_mask:0xf bank_mask:0xf
	v_fmac_f32_dpp v134, -v149, v94 row_newbcast:8 row_mask:0xf bank_mask:0xf
	v_fmac_f32_dpp v135, -v149, v95 row_newbcast:9 row_mask:0xf bank_mask:0xf
	v_fmac_f32_dpp v136, -v149, v92 row_newbcast:6 row_mask:0xf bank_mask:0xf
	v_fmac_f32_dpp v137, -v149, v97 row_newbcast:11 row_mask:0xf bank_mask:0xf
	v_fmac_f32_dpp v134, -v149, v98 row_newbcast:12 row_mask:0xf bank_mask:0xf
	v_fmac_f32_dpp v135, -v149, v99 row_newbcast:13 row_mask:0xf bank_mask:0xf
	v_fmac_f32_dpp v136, -v149, v96 row_newbcast:10 row_mask:0xf bank_mask:0xf
	v_fmac_f32_dpp v137, -v149, v101 row_newbcast:15 row_mask:0xf bank_mask:0xf
	v_fmac_f32_dpp v134, -v150, v102 row_newbcast:0 row_mask:0xf bank_mask:0xf
	v_fmac_f32_dpp v135, -v150, v103 row_newbcast:1 row_mask:0xf bank_mask:0xf
	v_fmac_f32_dpp v136, -v149, v100 row_newbcast:14 row_mask:0xf bank_mask:0xf
	v_fmac_f32_dpp v137, -v150, v105 row_newbcast:3 row_mask:0xf bank_mask:0xf
	v_fmac_f32_dpp v134, -v150, v106 row_newbcast:4 row_mask:0xf bank_mask:0xf
	v_fmac_f32_dpp v135, -v150, v107 row_newbcast:5 row_mask:0xf bank_mask:0xf
	v_fmac_f32_dpp v136, -v150, v104 row_newbcast:2 row_mask:0xf bank_mask:0xf
	v_fmac_f32_dpp v137, -v150, v109 row_newbcast:7 row_mask:0xf bank_mask:0xf
	v_fmac_f32_dpp v134, -v150, v110 row_newbcast:8 row_mask:0xf bank_mask:0xf
	v_fmac_f32_dpp v135, -v150, v111 row_newbcast:9 row_mask:0xf bank_mask:0xf
	v_fmac_f32_dpp v136, -v150, v108 row_newbcast:6 row_mask:0xf bank_mask:0xf
	v_fmac_f32_dpp v137, -v150, v113 row_newbcast:11 row_mask:0xf bank_mask:0xf
	v_fmac_f32_dpp v134, -v150, v114 row_newbcast:12 row_mask:0xf bank_mask:0xf
	v_fmac_f32_dpp v135, -v150, v115 row_newbcast:13 row_mask:0xf bank_mask:0xf
	v_fmac_f32_dpp v136, -v150, v112 row_newbcast:10 row_mask:0xf bank_mask:0xf
	v_fmac_f32_dpp v137, -v150, v117 row_newbcast:15 row_mask:0xf bank_mask:0xf
	v_fmac_f32_dpp v134, -v151, v118 row_newbcast:0 row_mask:0xf bank_mask:0xf
	v_fmac_f32_dpp v135, -v151, v119 row_newbcast:1 row_mask:0xf bank_mask:0xf
	v_fmac_f32_dpp v136, -v150, v116 row_newbcast:14 row_mask:0xf bank_mask:0xf
	v_fmac_f32_dpp v137, -v151, v121 row_newbcast:3 row_mask:0xf bank_mask:0xf
	v_fmac_f32_dpp v134, -v151, v122 row_newbcast:4 row_mask:0xf bank_mask:0xf
	v_fmac_f32_dpp v135, -v151, v123 row_newbcast:5 row_mask:0xf bank_mask:0xf
	v_fmac_f32_dpp v136, -v151, v120 row_newbcast:2 row_mask:0xf bank_mask:0xf
	v_fmac_f32_dpp v137, -v151, v125 row_newbcast:7 row_mask:0xf bank_mask:0xf
	v_fmac_f32_dpp v134, -v151, v126 row_newbcast:8 row_mask:0xf bank_mask:0xf
	v_fmac_f32_dpp v135, -v151, v127 row_newbcast:9 row_mask:0xf bank_mask:0xf
	v_fmac_f32_dpp v136, -v151, v124 row_newbcast:6 row_mask:0xf bank_mask:0xf
	v_fmac_f32_dpp v137, -v151, v129 row_newbcast:11 row_mask:0xf bank_mask:0xf
	s_nop 0
	v_fmac_f32_dpp v136, -v151, v128 row_newbcast:10 row_mask:0xf bank_mask:0xf
	v_cndmask_b32_e64 v130, 0, 1.0, vcc
	v_mov_b32_e32 v131, v18
	v_mov_b32_e32 v132, v18
	v_mov_b32_e32 v133, v18
	v_add_f32_e32 v2, v134, v135
	v_add_f32_e32 v3, v136, v137
	v_add_f32_e32 v71, v2, v3
	ds_read_b32 v148, v138 offset:512
	ds_read_b32 v149, v138 offset:576
	ds_read_b32 v150, v138 offset:640
	ds_read_b32 v151, v138 offset:704
	s_waitcnt lgkmcnt(8)
	v_cmp_eq_u32_e32 vcc, 3, v1
	v_fmac_f32_dpp v132, -v144, v72 row_newbcast:2 row_mask:0xf bank_mask:0xf
	v_fmac_f32_dpp v133, -v144, v73 row_newbcast:3 row_mask:0xf bank_mask:0xf
	v_fmac_f32_dpp v130, -v144, v74 row_newbcast:4 row_mask:0xf bank_mask:0xf
	v_fmac_f32_dpp v131, -v144, v71 row_newbcast:1 row_mask:0xf bank_mask:0xf
	v_fmac_f32_dpp v132, -v144, v76 row_newbcast:6 row_mask:0xf bank_mask:0xf
	v_fmac_f32_dpp v133, -v144, v77 row_newbcast:7 row_mask:0xf bank_mask:0xf
	v_fmac_f32_dpp v130, -v144, v78 row_newbcast:8 row_mask:0xf bank_mask:0xf
	v_fmac_f32_dpp v131, -v144, v75 row_newbcast:5 row_mask:0xf bank_mask:0xf
	v_fmac_f32_dpp v132, -v144, v80 row_newbcast:10 row_mask:0xf bank_mask:0xf
	v_fmac_f32_dpp v133, -v144, v81 row_newbcast:11 row_mask:0xf bank_mask:0xf
	v_fmac_f32_dpp v130, -v144, v82 row_newbcast:12 row_mask:0xf bank_mask:0xf
	v_fmac_f32_dpp v131, -v144, v79 row_newbcast:9 row_mask:0xf bank_mask:0xf
	v_fmac_f32_dpp v132, -v144, v84 row_newbcast:14 row_mask:0xf bank_mask:0xf
	v_fmac_f32_dpp v133, -v144, v85 row_newbcast:15 row_mask:0xf bank_mask:0xf
	v_fmac_f32_dpp v130, -v145, v86 row_newbcast:0 row_mask:0xf bank_mask:0xf
	v_fmac_f32_dpp v131, -v144, v83 row_newbcast:13 row_mask:0xf bank_mask:0xf
	v_fmac_f32_dpp v132, -v145, v88 row_newbcast:2 row_mask:0xf bank_mask:0xf
	v_fmac_f32_dpp v133, -v145, v89 row_newbcast:3 row_mask:0xf bank_mask:0xf
	v_fmac_f32_dpp v130, -v145, v90 row_newbcast:4 row_mask:0xf bank_mask:0xf
	v_fmac_f32_dpp v131, -v145, v87 row_newbcast:1 row_mask:0xf bank_mask:0xf
	v_fmac_f32_dpp v132, -v145, v92 row_newbcast:6 row_mask:0xf bank_mask:0xf
	v_fmac_f32_dpp v133, -v145, v93 row_newbcast:7 row_mask:0xf bank_mask:0xf
	v_fmac_f32_dpp v130, -v145, v94 row_newbcast:8 row_mask:0xf bank_mask:0xf
	v_fmac_f32_dpp v131, -v145, v91 row_newbcast:5 row_mask:0xf bank_mask:0xf
	v_fmac_f32_dpp v132, -v145, v96 row_newbcast:10 row_mask:0xf bank_mask:0xf
	v_fmac_f32_dpp v133, -v145, v97 row_newbcast:11 row_mask:0xf bank_mask:0xf
	v_fmac_f32_dpp v130, -v145, v98 row_newbcast:12 row_mask:0xf bank_mask:0xf
	v_fmac_f32_dpp v131, -v145, v95 row_newbcast:9 row_mask:0xf bank_mask:0xf
	v_fmac_f32_dpp v132, -v145, v100 row_newbcast:14 row_mask:0xf bank_mask:0xf
	v_fmac_f32_dpp v133, -v145, v101 row_newbcast:15 row_mask:0xf bank_mask:0xf
	v_fmac_f32_dpp v130, -v146, v102 row_newbcast:0 row_mask:0xf bank_mask:0xf
	v_fmac_f32_dpp v131, -v145, v99 row_newbcast:13 row_mask:0xf bank_mask:0xf
	v_fmac_f32_dpp v132, -v146, v104 row_newbcast:2 row_mask:0xf bank_mask:0xf
	v_fmac_f32_dpp v133, -v146, v105 row_newbcast:3 row_mask:0xf bank_mask:0xf
	v_fmac_f32_dpp v130, -v146, v106 row_newbcast:4 row_mask:0xf bank_mask:0xf
	v_fmac_f32_dpp v131, -v146, v103 row_newbcast:1 row_mask:0xf bank_mask:0xf
	v_fmac_f32_dpp v132, -v146, v108 row_newbcast:6 row_mask:0xf bank_mask:0xf
	v_fmac_f32_dpp v133, -v146, v109 row_newbcast:7 row_mask:0xf bank_mask:0xf
	v_fmac_f32_dpp v130, -v146, v110 row_newbcast:8 row_mask:0xf bank_mask:0xf
	v_fmac_f32_dpp v131, -v146, v107 row_newbcast:5 row_mask:0xf bank_mask:0xf
	v_fmac_f32_dpp v132, -v146, v112 row_newbcast:10 row_mask:0xf bank_mask:0xf
	v_fmac_f32_dpp v133, -v146, v113 row_newbcast:11 row_mask:0xf bank_mask:0xf
	v_fmac_f32_dpp v130, -v146, v114 row_newbcast:12 row_mask:0xf bank_mask:0xf
	v_fmac_f32_dpp v131, -v146, v111 row_newbcast:9 row_mask:0xf bank_mask:0xf
	v_fmac_f32_dpp v132, -v146, v116 row_newbcast:14 row_mask:0xf bank_mask:0xf
	v_fmac_f32_dpp v133, -v146, v117 row_newbcast:15 row_mask:0xf bank_mask:0xf
	v_fmac_f32_dpp v130, -v147, v118 row_newbcast:0 row_mask:0xf bank_mask:0xf
	v_fmac_f32_dpp v131, -v146, v115 row_newbcast:13 row_mask:0xf bank_mask:0xf
	v_fmac_f32_dpp v132, -v147, v120 row_newbcast:2 row_mask:0xf bank_mask:0xf
	v_fmac_f32_dpp v133, -v147, v121 row_newbcast:3 row_mask:0xf bank_mask:0xf
	v_fmac_f32_dpp v130, -v147, v122 row_newbcast:4 row_mask:0xf bank_mask:0xf
	v_fmac_f32_dpp v131, -v147, v119 row_newbcast:1 row_mask:0xf bank_mask:0xf
	v_fmac_f32_dpp v132, -v147, v124 row_newbcast:6 row_mask:0xf bank_mask:0xf
	v_fmac_f32_dpp v133, -v147, v125 row_newbcast:7 row_mask:0xf bank_mask:0xf
	v_fmac_f32_dpp v130, -v147, v126 row_newbcast:8 row_mask:0xf bank_mask:0xf
	v_fmac_f32_dpp v131, -v147, v123 row_newbcast:5 row_mask:0xf bank_mask:0xf
	v_fmac_f32_dpp v132, -v147, v128 row_newbcast:10 row_mask:0xf bank_mask:0xf
	v_fmac_f32_dpp v133, -v147, v129 row_newbcast:11 row_mask:0xf bank_mask:0xf
	v_fmac_f32_dpp v131, -v147, v127 row_newbcast:9 row_mask:0xf bank_mask:0xf
	v_cndmask_b32_e64 v134, 0, 1.0, vcc
	v_mov_b32_e32 v135, v18
	v_mov_b32_e32 v136, v18
	v_mov_b32_e32 v137, v18
	v_add_f32_e32 v2, v130, v131
	v_add_f32_e32 v3, v132, v133
	v_add_f32_e32 v70, v2, v3
	ds_read_b32 v144, v138 offset:256
	ds_read_b32 v145, v138 offset:320
	ds_read_b32 v146, v138 offset:384
	ds_read_b32 v147, v138 offset:448
	s_waitcnt lgkmcnt(8)
	v_cmp_eq_u32_e32 vcc, 2, v1
	v_fmac_f32_dpp v135, -v140, v71 row_newbcast:1 row_mask:0xf bank_mask:0xf
	v_fmac_f32_dpp v136, -v140, v72 row_newbcast:2 row_mask:0xf bank_mask:0xf
	v_fmac_f32_dpp v137, -v140, v73 row_newbcast:3 row_mask:0xf bank_mask:0xf
	v_fmac_f32_dpp v134, -v140, v70 row_newbcast:0 row_mask:0xf bank_mask:0xf
	v_fmac_f32_dpp v135, -v140, v75 row_newbcast:5 row_mask:0xf bank_mask:0xf
	v_fmac_f32_dpp v136, -v140, v76 row_newbcast:6 row_mask:0xf bank_mask:0xf
	v_fmac_f32_dpp v137, -v140, v77 row_newbcast:7 row_mask:0xf bank_mask:0xf
	v_fmac_f32_dpp v134, -v140, v74 row_newbcast:4 row_mask:0xf bank_mask:0xf
	v_fmac_f32_dpp v135, -v140, v79 row_newbcast:9 row_mask:0xf bank_mask:0xf
	v_fmac_f32_dpp v136, -v140, v80 row_newbcast:10 row_mask:0xf bank_mask:0xf
	v_fmac_f32_dpp v137, -v140, v81 row_newbcast:11 row_mask:0xf bank_mask:0xf
	v_fmac_f32_dpp v134, -v140, v78 row_newbcast:8 row_mask:0xf bank_mask:0xf
	v_fmac_f32_dpp v135, -v140, v83 row_newbcast:13 row_mask:0xf bank_mask:0xf
	v_fmac_f32_dpp v136, -v140, v84 row_newbcast:14 row_mask:0xf bank_mask:0xf
	v_fmac_f32_dpp v137, -v140, v85 row_newbcast:15 row_mask:0xf bank_mask:0xf
	v_fmac_f32_dpp v134, -v140, v82 row_newbcast:12 row_mask:0xf bank_mask:0xf
	v_fmac_f32_dpp v135, -v141, v87 row_newbcast:1 row_mask:0xf bank_mask:0xf
	v_fmac_f32_dpp v136, -v141, v88 row_newbcast:2 row_mask:0xf bank_mask:0xf
	v_fmac_f32_dpp v137, -v141, v89 row_newbcast:3 row_mask:0xf bank_mask:0xf
	v_fmac_f32_dpp v134, -v141, v86 row_newbcast:0 row_mask:0xf bank_mask:0xf
	v_fmac_f32_dpp v135, -v141, v91 row_newbcast:5 row_mask:0xf bank_mask:0xf
	v_fmac_f32_dpp v136, -v141, v92 row_newbcast:6 row_mask:0xf bank_mask:0xf
	v_fmac_f32_dpp v137, -v141, v93 row_newbcast:7 row_mask:0xf bank_mask:0xf
	v_fmac_f32_dpp v134, -v141, v90 row_newbcast:4 row_mask:0xf bank_mask:0xf
	v_fmac_f32_dpp v135, -v141, v95 row_newbcast:9 row_mask:0xf bank_mask:0xf
	v_fmac_f32_dpp v136, -v141, v96 row_newbcast:10 row_mask:0xf bank_mask:0xf
	v_fmac_f32_dpp v137, -v141, v97 row_newbcast:11 row_mask:0xf bank_mask:0xf
	v_fmac_f32_dpp v134, -v141, v94 row_newbcast:8 row_mask:0xf bank_mask:0xf
	v_fmac_f32_dpp v135, -v141, v99 row_newbcast:13 row_mask:0xf bank_mask:0xf
	v_fmac_f32_dpp v136, -v141, v100 row_newbcast:14 row_mask:0xf bank_mask:0xf
	v_fmac_f32_dpp v137, -v141, v101 row_newbcast:15 row_mask:0xf bank_mask:0xf
	v_fmac_f32_dpp v134, -v141, v98 row_newbcast:12 row_mask:0xf bank_mask:0xf
	v_fmac_f32_dpp v135, -v142, v103 row_newbcast:1 row_mask:0xf bank_mask:0xf
	v_fmac_f32_dpp v136, -v142, v104 row_newbcast:2 row_mask:0xf bank_mask:0xf
	v_fmac_f32_dpp v137, -v142, v105 row_newbcast:3 row_mask:0xf bank_mask:0xf
	v_fmac_f32_dpp v134, -v142, v102 row_newbcast:0 row_mask:0xf bank_mask:0xf
	v_fmac_f32_dpp v135, -v142, v107 row_newbcast:5 row_mask:0xf bank_mask:0xf
	v_fmac_f32_dpp v136, -v142, v108 row_newbcast:6 row_mask:0xf bank_mask:0xf
	v_fmac_f32_dpp v137, -v142, v109 row_newbcast:7 row_mask:0xf bank_mask:0xf
	v_fmac_f32_dpp v134, -v142, v106 row_newbcast:4 row_mask:0xf bank_mask:0xf
	v_fmac_f32_dpp v135, -v142, v111 row_newbcast:9 row_mask:0xf bank_mask:0xf
	v_fmac_f32_dpp v136, -v142, v112 row_newbcast:10 row_mask:0xf bank_mask:0xf
	v_fmac_f32_dpp v137, -v142, v113 row_newbcast:11 row_mask:0xf bank_mask:0xf
	v_fmac_f32_dpp v134, -v142, v110 row_newbcast:8 row_mask:0xf bank_mask:0xf
	v_fmac_f32_dpp v135, -v142, v115 row_newbcast:13 row_mask:0xf bank_mask:0xf
	v_fmac_f32_dpp v136, -v142, v116 row_newbcast:14 row_mask:0xf bank_mask:0xf
	v_fmac_f32_dpp v137, -v142, v117 row_newbcast:15 row_mask:0xf bank_mask:0xf
	v_fmac_f32_dpp v134, -v142, v114 row_newbcast:12 row_mask:0xf bank_mask:0xf
	v_fmac_f32_dpp v135, -v143, v119 row_newbcast:1 row_mask:0xf bank_mask:0xf
	v_fmac_f32_dpp v136, -v143, v120 row_newbcast:2 row_mask:0xf bank_mask:0xf
	v_fmac_f32_dpp v137, -v143, v121 row_newbcast:3 row_mask:0xf bank_mask:0xf
	v_fmac_f32_dpp v134, -v143, v118 row_newbcast:0 row_mask:0xf bank_mask:0xf
	v_fmac_f32_dpp v135, -v143, v123 row_newbcast:5 row_mask:0xf bank_mask:0xf
	v_fmac_f32_dpp v136, -v143, v124 row_newbcast:6 row_mask:0xf bank_mask:0xf
	v_fmac_f32_dpp v137, -v143, v125 row_newbcast:7 row_mask:0xf bank_mask:0xf
	v_fmac_f32_dpp v134, -v143, v122 row_newbcast:4 row_mask:0xf bank_mask:0xf
	v_fmac_f32_dpp v135, -v143, v127 row_newbcast:9 row_mask:0xf bank_mask:0xf
	v_fmac_f32_dpp v136, -v143, v128 row_newbcast:10 row_mask:0xf bank_mask:0xf
	v_fmac_f32_dpp v137, -v143, v129 row_newbcast:11 row_mask:0xf bank_mask:0xf
	v_fmac_f32_dpp v134, -v143, v126 row_newbcast:8 row_mask:0xf bank_mask:0xf
	v_cndmask_b32_e64 v130, 0, 1.0, vcc
	v_mov_b32_e32 v131, v18
	v_mov_b32_e32 v132, v18
	v_mov_b32_e32 v133, v18
	v_add_f32_e32 v2, v134, v135
	v_add_f32_e32 v3, v136, v137
	v_add_f32_e32 v69, v2, v3
	ds_read_b32 v140, v138 offset:0
	ds_read_b32 v141, v138 offset:64
	ds_read_b32 v142, v138 offset:128
	ds_read_b32 v143, v138 offset:192
	s_waitcnt lgkmcnt(8)
	v_cmp_eq_u32_e32 vcc, 1, v1
	v_fmac_f32_dpp v130, -v148, v70 row_newbcast:4 row_mask:0xf bank_mask:0xf
	v_fmac_f32_dpp v131, -v148, v71 row_newbcast:5 row_mask:0xf bank_mask:0xf
	v_fmac_f32_dpp v132, -v148, v72 row_newbcast:6 row_mask:0xf bank_mask:0xf
	v_fmac_f32_dpp v133, -v148, v69 row_newbcast:3 row_mask:0xf bank_mask:0xf
	v_fmac_f32_dpp v130, -v148, v74 row_newbcast:8 row_mask:0xf bank_mask:0xf
	v_fmac_f32_dpp v131, -v148, v75 row_newbcast:9 row_mask:0xf bank_mask:0xf
	v_fmac_f32_dpp v132, -v148, v76 row_newbcast:10 row_mask:0xf bank_mask:0xf
	v_fmac_f32_dpp v133, -v148, v73 row_newbcast:7 row_mask:0xf bank_mask:0xf
	v_fmac_f32_dpp v130, -v148, v78 row_newbcast:12 row_mask:0xf bank_mask:0xf
	v_fmac_f32_dpp v131, -v148, v79 row_newbcast:13 row_mask:0xf bank_mask:0xf
	v_fmac_f32_dpp v132, -v148, v80 row_newbcast:14 row_mask:0xf bank_mask:0xf
	v_fmac_f32_dpp v133, -v148, v77 row_newbcast:11 row_mask:0xf bank_mask:0xf
	v_fmac_f32_dpp v130, -v149, v82 row_newbcast:0 row_mask:0xf bank_mask:0xf
	v_fmac_f32_dpp v131, -v149, v83 row_newbcast:1 row_mask:0xf bank_mask:0xf
	v_fmac_f32_dpp v132, -v149, v84 row_newbcast:2 row_mask:0xf bank_mask:0xf
	v_fmac_f32_dpp v133, -v148, v81 row_newbcast:15 row_mask:0xf bank_mask:0xf
	v_fmac_f32_dpp v130, -v149, v86 row_newbcast:4 row_mask:0xf bank_mask:0xf
	v_fmac_f32_dpp v131, -v149, v87 row_newbcast:5 row_mask:0xf bank_mask:0xf
	v_fmac_f32_dpp v132, -v149, v88 row_newbcast:6 row_mask:0xf bank_mask:0xf
	v_fmac_f32_dpp v133, -v149, v85 row_newbcast:3 row_mask:0xf bank_mask:0xf
	v_fmac_f32_dpp v130, -v149, v90 row_newbcast:8 row_mask:0xf bank_mask:0xf
	v_fmac_f32_dpp v131, -v149, v91 row_newbcast:9 row_mask:0xf bank_mask:0xf
	v_fmac_f32_dpp v132, -v149, v92 row_newbcast:10 row_mask:0xf bank_mask:0xf
	v_fmac_f32_dpp v133, -v149, v89 row_newbcast:7 row_mask:0xf bank_mask:0xf
	v_fmac_f32_dpp v130, -v149, v94 row_newbcast:12 row_mask:0xf bank_mask:0xf
	v_fmac_f32_dpp v131, -v149, v95 row_newbcast:13 row_mask:0xf bank_mask:0xf
	v_fmac_f32_dpp v132, -v149, v96 row_newbcast:14 row_mask:0xf bank_mask:0xf
	v_fmac_f32_dpp v133, -v149, v93 row_newbcast:11 row_mask:0xf bank_mask:0xf
	v_fmac_f32_dpp v130, -v150, v98 row_newbcast:0 row_mask:0xf bank_mask:0xf
	v_fmac_f32_dpp v131, -v150, v99 row_newbcast:1 row_mask:0xf bank_mask:0xf
	v_fmac_f32_dpp v132, -v150, v100 row_newbcast:2 row_mask:0xf bank_mask:0xf
	v_fmac_f32_dpp v133, -v149, v97 row_newbcast:15 row_mask:0xf bank_mask:0xf
	v_fmac_f32_dpp v130, -v150, v102 row_newbcast:4 row_mask:0xf bank_mask:0xf
	v_fmac_f32_dpp v131, -v150, v103 row_newbcast:5 row_mask:0xf bank_mask:0xf
	v_fmac_f32_dpp v132, -v150, v104 row_newbcast:6 row_mask:0xf bank_mask:0xf
	v_fmac_f32_dpp v133, -v150, v101 row_newbcast:3 row_mask:0xf bank_mask:0xf
	v_fmac_f32_dpp v130, -v150, v106 row_newbcast:8 row_mask:0xf bank_mask:0xf
	v_fmac_f32_dpp v131, -v150, v107 row_newbcast:9 row_mask:0xf bank_mask:0xf
	v_fmac_f32_dpp v132, -v150, v108 row_newbcast:10 row_mask:0xf bank_mask:0xf
	v_fmac_f32_dpp v133, -v150, v105 row_newbcast:7 row_mask:0xf bank_mask:0xf
	v_fmac_f32_dpp v130, -v150, v110 row_newbcast:12 row_mask:0xf bank_mask:0xf
	v_fmac_f32_dpp v131, -v150, v111 row_newbcast:13 row_mask:0xf bank_mask:0xf
	v_fmac_f32_dpp v132, -v150, v112 row_newbcast:14 row_mask:0xf bank_mask:0xf
	v_fmac_f32_dpp v133, -v150, v109 row_newbcast:11 row_mask:0xf bank_mask:0xf
	v_fmac_f32_dpp v130, -v151, v114 row_newbcast:0 row_mask:0xf bank_mask:0xf
	v_fmac_f32_dpp v131, -v151, v115 row_newbcast:1 row_mask:0xf bank_mask:0xf
	v_fmac_f32_dpp v132, -v151, v116 row_newbcast:2 row_mask:0xf bank_mask:0xf
	v_fmac_f32_dpp v133, -v150, v113 row_newbcast:15 row_mask:0xf bank_mask:0xf
	v_fmac_f32_dpp v130, -v151, v118 row_newbcast:4 row_mask:0xf bank_mask:0xf
	v_fmac_f32_dpp v131, -v151, v119 row_newbcast:5 row_mask:0xf bank_mask:0xf
	v_fmac_f32_dpp v132, -v151, v120 row_newbcast:6 row_mask:0xf bank_mask:0xf
	v_fmac_f32_dpp v133, -v151, v117 row_newbcast:3 row_mask:0xf bank_mask:0xf
	v_fmac_f32_dpp v130, -v151, v122 row_newbcast:8 row_mask:0xf bank_mask:0xf
	v_fmac_f32_dpp v131, -v151, v123 row_newbcast:9 row_mask:0xf bank_mask:0xf
	v_fmac_f32_dpp v132, -v151, v124 row_newbcast:10 row_mask:0xf bank_mask:0xf
	v_fmac_f32_dpp v133, -v151, v121 row_newbcast:7 row_mask:0xf bank_mask:0xf
	v_fmac_f32_dpp v130, -v151, v126 row_newbcast:12 row_mask:0xf bank_mask:0xf
	v_fmac_f32_dpp v131, -v151, v127 row_newbcast:13 row_mask:0xf bank_mask:0xf
	v_fmac_f32_dpp v132, -v151, v128 row_newbcast:14 row_mask:0xf bank_mask:0xf
	v_fmac_f32_dpp v133, -v151, v125 row_newbcast:11 row_mask:0xf bank_mask:0xf
	s_nop 1
	v_fmac_f32_dpp v133, -v151, v129 row_newbcast:15 row_mask:0xf bank_mask:0xf
	v_cndmask_b32_e64 v134, 0, 1.0, vcc
	v_mov_b32_e32 v135, v18
	v_mov_b32_e32 v136, v18
	v_mov_b32_e32 v137, v18
	v_add_f32_e32 v2, v130, v131
	v_add_f32_e32 v3, v132, v133
	v_add_f32_e32 v68, v2, v3
	s_waitcnt lgkmcnt(4)
	v_cmp_eq_u32_e32 vcc, 0, v1
	v_fmac_f32_dpp v137, -v144, v69 row_newbcast:3 row_mask:0xf bank_mask:0xf
	v_fmac_f32_dpp v134, -v144, v70 row_newbcast:4 row_mask:0xf bank_mask:0xf
	v_fmac_f32_dpp v135, -v144, v71 row_newbcast:5 row_mask:0xf bank_mask:0xf
	v_fmac_f32_dpp v136, -v144, v68 row_newbcast:2 row_mask:0xf bank_mask:0xf
	v_fmac_f32_dpp v137, -v144, v73 row_newbcast:7 row_mask:0xf bank_mask:0xf
	v_fmac_f32_dpp v134, -v144, v74 row_newbcast:8 row_mask:0xf bank_mask:0xf
	v_fmac_f32_dpp v135, -v144, v75 row_newbcast:9 row_mask:0xf bank_mask:0xf
	v_fmac_f32_dpp v136, -v144, v72 row_newbcast:6 row_mask:0xf bank_mask:0xf
	v_fmac_f32_dpp v137, -v144, v77 row_newbcast:11 row_mask:0xf bank_mask:0xf
	v_fmac_f32_dpp v134, -v144, v78 row_newbcast:12 row_mask:0xf bank_mask:0xf
	v_fmac_f32_dpp v135, -v144, v79 row_newbcast:13 row_mask:0xf bank_mask:0xf
	v_fmac_f32_dpp v136, -v144, v76 row_newbcast:10 row_mask:0xf bank_mask:0xf
	v_fmac_f32_dpp v137, -v144, v81 row_newbcast:15 row_mask:0xf bank_mask:0xf
	v_fmac_f32_dpp v134, -v145, v82 row_newbcast:0 row_mask:0xf bank_mask:0xf
	v_fmac_f32_dpp v135, -v145, v83 row_newbcast:1 row_mask:0xf bank_mask:0xf
	v_fmac_f32_dpp v136, -v144, v80 row_newbcast:14 row_mask:0xf bank_mask:0xf
	v_fmac_f32_dpp v137, -v145, v85 row_newbcast:3 row_mask:0xf bank_mask:0xf
	v_fmac_f32_dpp v134, -v145, v86 row_newbcast:4 row_mask:0xf bank_mask:0xf
	v_fmac_f32_dpp v135, -v145, v87 row_newbcast:5 row_mask:0xf bank_mask:0xf
	v_fmac_f32_dpp v136, -v145, v84 row_newbcast:2 row_mask:0xf bank_mask:0xf
	v_fmac_f32_dpp v137, -v145, v89 row_newbcast:7 row_mask:0xf bank_mask:0xf
	v_fmac_f32_dpp v134, -v145, v90 row_newbcast:8 row_mask:0xf bank_mask:0xf
	v_fmac_f32_dpp v135, -v145, v91 row_newbcast:9 row_mask:0xf bank_mask:0xf
	v_fmac_f32_dpp v136, -v145, v88 row_newbcast:6 row_mask:0xf bank_mask:0xf
	v_fmac_f32_dpp v137, -v145, v93 row_newbcast:11 row_mask:0xf bank_mask:0xf
	v_fmac_f32_dpp v134, -v145, v94 row_newbcast:12 row_mask:0xf bank_mask:0xf
	v_fmac_f32_dpp v135, -v145, v95 row_newbcast:13 row_mask:0xf bank_mask:0xf
	v_fmac_f32_dpp v136, -v145, v92 row_newbcast:10 row_mask:0xf bank_mask:0xf
	v_fmac_f32_dpp v137, -v145, v97 row_newbcast:15 row_mask:0xf bank_mask:0xf
	v_fmac_f32_dpp v134, -v146, v98 row_newbcast:0 row_mask:0xf bank_mask:0xf
	v_fmac_f32_dpp v135, -v146, v99 row_newbcast:1 row_mask:0xf bank_mask:0xf
	v_fmac_f32_dpp v136, -v145, v96 row_newbcast:14 row_mask:0xf bank_mask:0xf
	v_fmac_f32_dpp v137, -v146, v101 row_newbcast:3 row_mask:0xf bank_mask:0xf
	v_fmac_f32_dpp v134, -v146, v102 row_newbcast:4 row_mask:0xf bank_mask:0xf
	v_fmac_f32_dpp v135, -v146, v103 row_newbcast:5 row_mask:0xf bank_mask:0xf
	v_fmac_f32_dpp v136, -v146, v100 row_newbcast:2 row_mask:0xf bank_mask:0xf
	v_fmac_f32_dpp v137, -v146, v105 row_newbcast:7 row_mask:0xf bank_mask:0xf
	v_fmac_f32_dpp v134, -v146, v106 row_newbcast:8 row_mask:0xf bank_mask:0xf
	v_fmac_f32_dpp v135, -v146, v107 row_newbcast:9 row_mask:0xf bank_mask:0xf
	v_fmac_f32_dpp v136, -v146, v104 row_newbcast:6 row_mask:0xf bank_mask:0xf
	v_fmac_f32_dpp v137, -v146, v109 row_newbcast:11 row_mask:0xf bank_mask:0xf
	v_fmac_f32_dpp v134, -v146, v110 row_newbcast:12 row_mask:0xf bank_mask:0xf
	v_fmac_f32_dpp v135, -v146, v111 row_newbcast:13 row_mask:0xf bank_mask:0xf
	v_fmac_f32_dpp v136, -v146, v108 row_newbcast:10 row_mask:0xf bank_mask:0xf
	v_fmac_f32_dpp v137, -v146, v113 row_newbcast:15 row_mask:0xf bank_mask:0xf
	v_fmac_f32_dpp v134, -v147, v114 row_newbcast:0 row_mask:0xf bank_mask:0xf
	v_fmac_f32_dpp v135, -v147, v115 row_newbcast:1 row_mask:0xf bank_mask:0xf
	v_fmac_f32_dpp v136, -v146, v112 row_newbcast:14 row_mask:0xf bank_mask:0xf
	v_fmac_f32_dpp v137, -v147, v117 row_newbcast:3 row_mask:0xf bank_mask:0xf
	v_fmac_f32_dpp v134, -v147, v118 row_newbcast:4 row_mask:0xf bank_mask:0xf
	v_fmac_f32_dpp v135, -v147, v119 row_newbcast:5 row_mask:0xf bank_mask:0xf
	v_fmac_f32_dpp v136, -v147, v116 row_newbcast:2 row_mask:0xf bank_mask:0xf
	v_fmac_f32_dpp v137, -v147, v121 row_newbcast:7 row_mask:0xf bank_mask:0xf
	v_fmac_f32_dpp v134, -v147, v122 row_newbcast:8 row_mask:0xf bank_mask:0xf
	v_fmac_f32_dpp v135, -v147, v123 row_newbcast:9 row_mask:0xf bank_mask:0xf
	v_fmac_f32_dpp v136, -v147, v120 row_newbcast:6 row_mask:0xf bank_mask:0xf
	v_fmac_f32_dpp v137, -v147, v125 row_newbcast:11 row_mask:0xf bank_mask:0xf
	v_fmac_f32_dpp v134, -v147, v126 row_newbcast:12 row_mask:0xf bank_mask:0xf
	v_fmac_f32_dpp v135, -v147, v127 row_newbcast:13 row_mask:0xf bank_mask:0xf
	v_fmac_f32_dpp v136, -v147, v124 row_newbcast:10 row_mask:0xf bank_mask:0xf
	v_fmac_f32_dpp v137, -v147, v129 row_newbcast:15 row_mask:0xf bank_mask:0xf
	s_nop 0
	v_fmac_f32_dpp v136, -v147, v128 row_newbcast:14 row_mask:0xf bank_mask:0xf
	v_cndmask_b32_e64 v130, 0, 1.0, vcc
	v_mov_b32_e32 v131, v18
	v_mov_b32_e32 v132, v18
	v_mov_b32_e32 v133, v18
	v_add_f32_e32 v2, v134, v135
	v_add_f32_e32 v3, v136, v137
	v_add_f32_e32 v67, v2, v3
	s_waitcnt lgkmcnt(0)
	v_fmac_f32_dpp v132, -v140, v68 row_newbcast:2 row_mask:0xf bank_mask:0xf
	v_fmac_f32_dpp v133, -v140, v69 row_newbcast:3 row_mask:0xf bank_mask:0xf
	v_fmac_f32_dpp v130, -v140, v70 row_newbcast:4 row_mask:0xf bank_mask:0xf
	v_fmac_f32_dpp v131, -v140, v67 row_newbcast:1 row_mask:0xf bank_mask:0xf
	v_fmac_f32_dpp v132, -v140, v72 row_newbcast:6 row_mask:0xf bank_mask:0xf
	v_fmac_f32_dpp v133, -v140, v73 row_newbcast:7 row_mask:0xf bank_mask:0xf
	v_fmac_f32_dpp v130, -v140, v74 row_newbcast:8 row_mask:0xf bank_mask:0xf
	v_fmac_f32_dpp v131, -v140, v71 row_newbcast:5 row_mask:0xf bank_mask:0xf
	v_fmac_f32_dpp v132, -v140, v76 row_newbcast:10 row_mask:0xf bank_mask:0xf
	v_fmac_f32_dpp v133, -v140, v77 row_newbcast:11 row_mask:0xf bank_mask:0xf
	v_fmac_f32_dpp v130, -v140, v78 row_newbcast:12 row_mask:0xf bank_mask:0xf
	v_fmac_f32_dpp v131, -v140, v75 row_newbcast:9 row_mask:0xf bank_mask:0xf
	v_fmac_f32_dpp v132, -v140, v80 row_newbcast:14 row_mask:0xf bank_mask:0xf
	v_fmac_f32_dpp v133, -v140, v81 row_newbcast:15 row_mask:0xf bank_mask:0xf
	v_fmac_f32_dpp v130, -v141, v82 row_newbcast:0 row_mask:0xf bank_mask:0xf
	v_fmac_f32_dpp v131, -v140, v79 row_newbcast:13 row_mask:0xf bank_mask:0xf
	v_fmac_f32_dpp v132, -v141, v84 row_newbcast:2 row_mask:0xf bank_mask:0xf
	v_fmac_f32_dpp v133, -v141, v85 row_newbcast:3 row_mask:0xf bank_mask:0xf
	v_fmac_f32_dpp v130, -v141, v86 row_newbcast:4 row_mask:0xf bank_mask:0xf
	v_fmac_f32_dpp v131, -v141, v83 row_newbcast:1 row_mask:0xf bank_mask:0xf
	v_fmac_f32_dpp v132, -v141, v88 row_newbcast:6 row_mask:0xf bank_mask:0xf
	v_fmac_f32_dpp v133, -v141, v89 row_newbcast:7 row_mask:0xf bank_mask:0xf
	v_fmac_f32_dpp v130, -v141, v90 row_newbcast:8 row_mask:0xf bank_mask:0xf
	v_fmac_f32_dpp v131, -v141, v87 row_newbcast:5 row_mask:0xf bank_mask:0xf
	v_fmac_f32_dpp v132, -v141, v92 row_newbcast:10 row_mask:0xf bank_mask:0xf
	v_fmac_f32_dpp v133, -v141, v93 row_newbcast:11 row_mask:0xf bank_mask:0xf
	v_fmac_f32_dpp v130, -v141, v94 row_newbcast:12 row_mask:0xf bank_mask:0xf
	v_fmac_f32_dpp v131, -v141, v91 row_newbcast:9 row_mask:0xf bank_mask:0xf
	v_fmac_f32_dpp v132, -v141, v96 row_newbcast:14 row_mask:0xf bank_mask:0xf
	v_fmac_f32_dpp v133, -v141, v97 row_newbcast:15 row_mask:0xf bank_mask:0xf
	v_fmac_f32_dpp v130, -v142, v98 row_newbcast:0 row_mask:0xf bank_mask:0xf
	v_fmac_f32_dpp v131, -v141, v95 row_newbcast:13 row_mask:0xf bank_mask:0xf
	v_fmac_f32_dpp v132, -v142, v100 row_newbcast:2 row_mask:0xf bank_mask:0xf
	v_fmac_f32_dpp v133, -v142, v101 row_newbcast:3 row_mask:0xf bank_mask:0xf
	v_fmac_f32_dpp v130, -v142, v102 row_newbcast:4 row_mask:0xf bank_mask:0xf
	v_fmac_f32_dpp v131, -v142, v99 row_newbcast:1 row_mask:0xf bank_mask:0xf
	v_fmac_f32_dpp v132, -v142, v104 row_newbcast:6 row_mask:0xf bank_mask:0xf
	v_fmac_f32_dpp v133, -v142, v105 row_newbcast:7 row_mask:0xf bank_mask:0xf
	v_fmac_f32_dpp v130, -v142, v106 row_newbcast:8 row_mask:0xf bank_mask:0xf
	v_fmac_f32_dpp v131, -v142, v103 row_newbcast:5 row_mask:0xf bank_mask:0xf
	v_fmac_f32_dpp v132, -v142, v108 row_newbcast:10 row_mask:0xf bank_mask:0xf
	v_fmac_f32_dpp v133, -v142, v109 row_newbcast:11 row_mask:0xf bank_mask:0xf
	v_fmac_f32_dpp v130, -v142, v110 row_newbcast:12 row_mask:0xf bank_mask:0xf
	v_fmac_f32_dpp v131, -v142, v107 row_newbcast:9 row_mask:0xf bank_mask:0xf
	v_fmac_f32_dpp v132, -v142, v112 row_newbcast:14 row_mask:0xf bank_mask:0xf
	v_fmac_f32_dpp v133, -v142, v113 row_newbcast:15 row_mask:0xf bank_mask:0xf
	v_fmac_f32_dpp v130, -v143, v114 row_newbcast:0 row_mask:0xf bank_mask:0xf
	v_fmac_f32_dpp v131, -v142, v111 row_newbcast:13 row_mask:0xf bank_mask:0xf
	v_fmac_f32_dpp v132, -v143, v116 row_newbcast:2 row_mask:0xf bank_mask:0xf
	v_fmac_f32_dpp v133, -v143, v117 row_newbcast:3 row_mask:0xf bank_mask:0xf
	v_fmac_f32_dpp v130, -v143, v118 row_newbcast:4 row_mask:0xf bank_mask:0xf
	v_fmac_f32_dpp v131, -v143, v115 row_newbcast:1 row_mask:0xf bank_mask:0xf
	v_fmac_f32_dpp v132, -v143, v120 row_newbcast:6 row_mask:0xf bank_mask:0xf
	v_fmac_f32_dpp v133, -v143, v121 row_newbcast:7 row_mask:0xf bank_mask:0xf
	v_fmac_f32_dpp v130, -v143, v122 row_newbcast:8 row_mask:0xf bank_mask:0xf
	v_fmac_f32_dpp v131, -v143, v119 row_newbcast:5 row_mask:0xf bank_mask:0xf
	v_fmac_f32_dpp v132, -v143, v124 row_newbcast:10 row_mask:0xf bank_mask:0xf
	v_fmac_f32_dpp v133, -v143, v125 row_newbcast:11 row_mask:0xf bank_mask:0xf
	v_fmac_f32_dpp v130, -v143, v126 row_newbcast:12 row_mask:0xf bank_mask:0xf
	v_fmac_f32_dpp v131, -v143, v123 row_newbcast:9 row_mask:0xf bank_mask:0xf
	v_fmac_f32_dpp v132, -v143, v128 row_newbcast:14 row_mask:0xf bank_mask:0xf
	v_fmac_f32_dpp v133, -v143, v129 row_newbcast:15 row_mask:0xf bank_mask:0xf
	v_fmac_f32_dpp v131, -v143, v127 row_newbcast:13 row_mask:0xf bank_mask:0xf
	v_add_f32_e32 v2, v130, v131
	v_add_f32_e32 v3, v132, v133
	v_add_f32_e32 v66, v2, v3
	v_mov_b32_e32 v19, s5
	v_and_b32_e32 v20, 31, v1
	v_lshlrev_b32_e32 v20, 4, v20
	v_cmp_lt_u32_e32 vcc, 31, v1
	s_nop 1
	v_cndmask_b32_e32 v21, 0, v193, vcc
	v_or_b32_e32 v21, v21, v20
	v_add_u32_e32 v20, 0x1000, v20
	ds_read_b128 v[194:197], v19 offset:0
	ds_read_b128 v[198:201], v19 offset:32
	ds_read_b128 v[202:205], v19 offset:16
	ds_read_b128 v[206:209], v19 offset:48
	ds_read_b128 v[210:213], v19 offset:64
	ds_read_b128 v[214:217], v19 offset:96
	ds_read_b128 v[218:221], v19 offset:80
	ds_read_b128 v[222:225], v19 offset:112
	s_waitcnt lgkmcnt(6)
	v_pk_mul_f32 v[2:3], v[66:67], v[194:195]
	v_pk_mul_f32 v[4:5], v[68:69], v[196:197]
	v_pk_mul_f32 v[6:7], v[74:75], v[198:199]
	v_pk_mul_f32 v[8:9], v[76:77], v[200:201]
	v_cvt_pk_bf16_f32 v10, v2, v3
	v_cvt_pk_bf16_f32 v11, v4, v5
	v_cvt_pk_bf16_f32 v12, v6, v7
	v_cvt_pk_bf16_f32 v13, v8, v9
	global_store_dwordx4 v21, v[10:13], s[6:7] sc0 sc1
	s_waitcnt lgkmcnt(4)
	v_pk_mul_f32 v[2:3], v[70:71], v[202:203]
	v_pk_mul_f32 v[4:5], v[72:73], v[204:205]
	v_pk_mul_f32 v[6:7], v[78:79], v[206:207]
	v_pk_mul_f32 v[8:9], v[80:81], v[208:209]
	v_cvt_pk_bf16_f32 v14, v2, v3
	v_cvt_pk_bf16_f32 v15, v4, v5
	v_cvt_pk_bf16_f32 v16, v6, v7
	v_cvt_pk_bf16_f32 v17, v8, v9
	global_store_dwordx4 v21, v[14:17], s[6:7] offset:512 sc0 sc1
	s_waitcnt lgkmcnt(2)
	v_pk_mul_f32 v[2:3], v[82:83], v[210:211]
	v_pk_mul_f32 v[4:5], v[84:85], v[212:213]
	v_pk_mul_f32 v[6:7], v[90:91], v[214:215]
	v_pk_mul_f32 v[8:9], v[92:93], v[216:217]
	v_cvt_pk_bf16_f32 v10, v2, v3
	v_cvt_pk_bf16_f32 v11, v4, v5
	v_cvt_pk_bf16_f32 v12, v6, v7
	v_cvt_pk_bf16_f32 v13, v8, v9
	global_store_dwordx4 v21, v[10:13], s[6:7] offset:1024 sc0 sc1
	s_waitcnt lgkmcnt(0)
	v_pk_mul_f32 v[2:3], v[86:87], v[218:219]
	v_pk_mul_f32 v[4:5], v[88:89], v[220:221]
	v_pk_mul_f32 v[6:7], v[94:95], v[222:223]
	v_pk_mul_f32 v[8:9], v[96:97], v[224:225]
	v_cvt_pk_bf16_f32 v14, v2, v3
	v_cvt_pk_bf16_f32 v15, v4, v5
	v_cvt_pk_bf16_f32 v16, v6, v7
	v_cvt_pk_bf16_f32 v17, v8, v9
	global_store_dwordx4 v21, v[14:17], s[6:7] offset:1536 sc0 sc1
	s_and_saveexec_b64 s[0:1], vcc
	s_cbranch_execz .LBB0_655
	ds_read_b128 v[194:197], v19 offset:128
	ds_read_b128 v[198:201], v19 offset:160
	ds_read_b128 v[202:205], v19 offset:144
	ds_read_b128 v[206:209], v19 offset:176
	ds_read_b128 v[210:213], v19 offset:192
	ds_read_b128 v[214:217], v19 offset:224
	ds_read_b128 v[218:221], v19 offset:208
	ds_read_b128 v[222:225], v19 offset:240
	s_waitcnt lgkmcnt(6)
	v_pk_mul_f32 v[2:3], v[98:99], v[194:195]
	v_pk_mul_f32 v[4:5], v[100:101], v[196:197]
	v_pk_mul_f32 v[6:7], v[106:107], v[198:199]
	v_pk_mul_f32 v[8:9], v[108:109], v[200:201]
	v_cvt_pk_bf16_f32 v10, v2, v3
	v_cvt_pk_bf16_f32 v11, v4, v5
	v_cvt_pk_bf16_f32 v12, v6, v7
	v_cvt_pk_bf16_f32 v13, v8, v9
	global_store_dwordx4 v20, v[10:13], s[6:7] sc0 sc1
	s_waitcnt lgkmcnt(4)
	v_pk_mul_f32 v[2:3], v[102:103], v[202:203]
	v_pk_mul_f32 v[4:5], v[104:105], v[204:205]
	v_pk_mul_f32 v[6:7], v[110:111], v[206:207]
	v_pk_mul_f32 v[8:9], v[112:113], v[208:209]
	v_cvt_pk_bf16_f32 v14, v2, v3
	v_cvt_pk_bf16_f32 v15, v4, v5
	v_cvt_pk_bf16_f32 v16, v6, v7
	v_cvt_pk_bf16_f32 v17, v8, v9
	global_store_dwordx4 v20, v[14:17], s[6:7] offset:512 sc0 sc1
	s_waitcnt lgkmcnt(2)
	v_pk_mul_f32 v[2:3], v[114:115], v[210:211]
	v_pk_mul_f32 v[4:5], v[116:117], v[212:213]
	v_pk_mul_f32 v[6:7], v[122:123], v[214:215]
	v_pk_mul_f32 v[8:9], v[124:125], v[216:217]
	v_cvt_pk_bf16_f32 v10, v2, v3
	v_cvt_pk_bf16_f32 v11, v4, v5
	v_cvt_pk_bf16_f32 v12, v6, v7
	v_cvt_pk_bf16_f32 v13, v8, v9
	global_store_dwordx4 v20, v[10:13], s[6:7] offset:1024 sc0 sc1
	s_waitcnt lgkmcnt(0)
	v_pk_mul_f32 v[2:3], v[118:119], v[218:219]
	v_pk_mul_f32 v[4:5], v[120:121], v[220:221]
	v_pk_mul_f32 v[6:7], v[126:127], v[222:223]
	v_pk_mul_f32 v[8:9], v[128:129], v[224:225]
	v_cvt_pk_bf16_f32 v14, v2, v3
	v_cvt_pk_bf16_f32 v15, v4, v5
	v_cvt_pk_bf16_f32 v16, v6, v7
	v_cvt_pk_bf16_f32 v17, v8, v9
	global_store_dwordx4 v20, v[14:17], s[6:7] offset:1536 sc0 sc1
	s_nop 1
